# v14 + redundant post-barrier s_waitcnt lgkmcnt(0) at each MFMA block head deleted in the 8 K-loops
# speedup vs baseline: 1.0053x; 1.0053x over previous
; #define PG8_STAGE(bufoff, gbase, voff) do { _Pragma("unroll") for (int _i = 0; _i < 2; ++_i) \
;         __builtin_amdgcn_global_load_lds((const unsigned*)((const char*)(gbase) + (voff)[_i]), (PG8_LAS unsigned*)(lds + (bufoff) + ldsw + _i * 8192), 16, 0, 0); } while (0)
; #define PG8_LDA(dst, b, h) do { _Pragma("unroll") for (int m = 0; m < 4; ++m) _Pragma("unroll") for (int k = 0; k < 2; ++k) dst[m][k] = *(const PG8_LAS bf16x8*)(lds + PG8_SA(b, h) + aoff + m * 2048 + k * 1024); } while (0)
; #define PG8_LDB(dst, b, h) do { _Pragma("unroll") for (int n = 0; n < 2; ++n) _Pragma("unroll") for (int k = 0; k < 2; ++k) dst[n][k] = *(const PG8_LAS bf16x8*)(lds + PG8_SB(b, h) + boff + n * 2048 + k * 1024); } while (0)
; #define PG8_MMA(ai, bj, At, Bt) do { __builtin_amdgcn_s_setprio(1); _Pragma("unroll") for (int m = 0; m < 4; ++m) _Pragma("unroll") for (int n = 0; n < 2; ++n) _Pragma("unroll") for (int k = 0; k < 2; ++k) \
;         acc[ai][bj][m][n] = __builtin_amdgcn_mfma_f32_16x16x32_bf16(Bt[n][k], At[m][k], acc[ai][bj][m][n], 0, 0, 0); __builtin_amdgcn_s_setprio(0); } while (0)
; #define PG8_WAIT_V(n) asm volatile("s_waitcnt vmcnt(" #n ")" ::: "memory")
; #define PG8_WAIT_L(n) asm volatile("s_waitcnt lgkmcnt(" #n ")" ::: "memory")
; #define PG8_BAR __builtin_amdgcn_s_barrier()
; #define PG8_SCHED __builtin_amdgcn_sched_barrier(0)
; template <class Epi, class Sched, bool ALIGN_EPI = false, bool SP2 = false>
; __device__ __forceinline__ void gemm_phase(PG8_LAS unsigned char* lds, const Gemm g, const Sched& S, const Epi& E) {
;     ...
;             PG8_LDB(B0, 0, 0); PG8_LDB(B1, 0, 1); PG8_SCHED; PG8_LDA(At, 0, 0); PG8_STAGE(PG8_SA(1, 1), a1 + hstep, voffA);
;             PG8_WAIT_V(8); PG8_WAIT_L(0); PG8_BAR; PG8_MMA(0, 0, At, B0); PG8_MMA(0, 1, At, B1); PG8_BAR; PG8_SCHED;
;             PG8_LDA(At, 0, 1); PG8_STAGE(PG8_SB(0, 0), b2, voffB); PG8_STAGE(PG8_SB(0, 1), b2 + hstep, voffB); PG8_STAGE(PG8_SA(0, 0), a2, voffA);
;             PG8_WAIT_V(8); PG8_WAIT_L(0); PG8_BAR; PG8_MMA(1, 0, At, B0); PG8_MMA(1, 1, At, B1); PG8_BAR; PG8_SCHED;
.LBB0_115:
	ds_read_b128 v[154:157], v150
	ds_read_b128 v[158:161], v150 offset:1024
	ds_read_b128 v[162:165], v150 offset:2048
	ds_read_b128 v[166:169], v150 offset:3072
	ds_read_b128 v[170:173], v151
	ds_read_b128 v[174:177], v151 offset:1024
	ds_read_b128 v[180:183], v151 offset:2048
	ds_read_b128 v[184:187], v151 offset:3072
	s_add_u32 s50, s48, 0x4000
	s_addc_u32 s51, s49, 0
	s_cmp_eq_u32 s76, 60
	s_cselect_b32 s74, s64, s50
	s_cselect_b32 s75, s25, s51
	s_cselect_b32 s72, s65, s68
	s_cselect_b32 s73, s19, s69
	s_add_u32 s50, s74, 0x8000
	s_addc_u32 s51, s75, 0
	s_sub_u32 s50, s48, 0x4000
	s_subb_u32 s51, s49, 0
	s_mov_b32 m0, s58
	s_nop 0
	global_load_lds_dwordx4 v130, s[50:51]
	s_mov_b32 m0, s59
	s_nop 0
	global_load_lds_dwordx4 v134, s[50:51]
	s_add_i32 m0, s28, 0xc000
	ds_read_b128 v[188:191], v152
	ds_read_b128 v[196:199], v152 offset:1024
	ds_read_b128 v[200:203], v152 offset:2048
	ds_read_b128 v[204:207], v152 offset:3072
	ds_read_b128 v[208:211], v152 offset:4096
	ds_read_b128 v[212:215], v152 offset:5120
	ds_read_b128 v[216:219], v152 offset:6144
	ds_read_b128 v[220:223], v152 offset:7168
	global_load_lds_dwordx4 v140, s[48:49]
	s_add_i32 m0, s28, 0xe000
	s_nop 0
	global_load_lds_dwordx4 v142, s[48:49]
	s_waitcnt vmcnt(8)
	s_waitcnt lgkmcnt(0)
	s_barrier
	v_mfma_f32_16x16x32_bf16 v[126:129], v[154:157], v[188:191], v[126:129]
	v_mfma_f32_16x16x32_bf16 v[126:129], v[158:161], v[196:199], v[126:129]
	v_mfma_f32_16x16x32_bf16 v[110:113], v[154:157], v[200:203], v[110:113]
	v_mfma_f32_16x16x32_bf16 v[110:113], v[158:161], v[204:207], v[110:113]
	v_mfma_f32_16x16x32_bf16 v[94:97], v[154:157], v[208:211], v[94:97]
	v_mfma_f32_16x16x32_bf16 v[94:97], v[158:161], v[212:215], v[94:97]
	v_mfma_f32_16x16x32_bf16 v[78:81], v[154:157], v[216:219], v[78:81]
	v_mfma_f32_16x16x32_bf16 v[78:81], v[158:161], v[220:223], v[78:81]
	v_mfma_f32_16x16x32_bf16 v[70:73], v[162:165], v[216:219], v[70:73]
	v_mfma_f32_16x16x32_bf16 v[70:73], v[166:169], v[220:223], v[70:73]
	v_mfma_f32_16x16x32_bf16 v[86:89], v[162:165], v[208:211], v[86:89]
	v_mfma_f32_16x16x32_bf16 v[86:89], v[166:169], v[212:215], v[86:89]
	v_mfma_f32_16x16x32_bf16 v[102:105], v[162:165], v[200:203], v[102:105]
	v_mfma_f32_16x16x32_bf16 v[102:105], v[166:169], v[204:207], v[102:105]
	v_mfma_f32_16x16x32_bf16 v[118:121], v[162:165], v[188:191], v[118:121]
	v_mfma_f32_16x16x32_bf16 v[118:121], v[166:169], v[196:199], v[118:121]
	v_mfma_f32_16x16x32_bf16 v[122:125], v[170:173], v[188:191], v[122:125]
	v_mfma_f32_16x16x32_bf16 v[122:125], v[174:177], v[196:199], v[122:125]
	v_mfma_f32_16x16x32_bf16 v[106:109], v[170:173], v[200:203], v[106:109]
	v_mfma_f32_16x16x32_bf16 v[106:109], v[174:177], v[204:207], v[106:109]
	v_mfma_f32_16x16x32_bf16 v[90:93], v[170:173], v[208:211], v[90:93]
	v_mfma_f32_16x16x32_bf16 v[90:93], v[174:177], v[212:215], v[90:93]
	v_mfma_f32_16x16x32_bf16 v[74:77], v[170:173], v[216:219], v[74:77]
	v_mfma_f32_16x16x32_bf16 v[74:77], v[174:177], v[220:223], v[74:77]
	v_mfma_f32_16x16x32_bf16 v[66:69], v[180:183], v[216:219], v[66:69]
	v_mfma_f32_16x16x32_bf16 v[66:69], v[184:187], v[220:223], v[66:69]
	v_mfma_f32_16x16x32_bf16 v[82:85], v[180:183], v[208:211], v[82:85]
	v_mfma_f32_16x16x32_bf16 v[82:85], v[184:187], v[212:215], v[82:85]
	v_mfma_f32_16x16x32_bf16 v[98:101], v[180:183], v[200:203], v[98:101]
	v_mfma_f32_16x16x32_bf16 v[98:101], v[184:187], v[204:207], v[98:101]
	v_mfma_f32_16x16x32_bf16 v[114:117], v[180:183], v[188:191], v[114:117]
	v_mfma_f32_16x16x32_bf16 v[114:117], v[184:187], v[196:199], v[114:117]
	s_barrier
	s_add_i32 s77, s61, s3
	s_mov_b32 m0, s77
	ds_read_b128 v[188:191], v152 offset:16384
	ds_read_b128 v[196:199], v152 offset:17408
	ds_read_b128 v[200:203], v152 offset:18432
	ds_read_b128 v[204:207], v152 offset:19456
	ds_read_b128 v[208:211], v152 offset:20480
	ds_read_b128 v[212:215], v152 offset:21504
	ds_read_b128 v[216:219], v152 offset:22528
	ds_read_b128 v[220:223], v152 offset:23552
	global_load_lds_dwordx4 v132, s[72:73]
	s_add_i32 m0, s77, 0x2000
	s_add_u32 s78, s72, 0x4000
	s_addc_u32 s79, s73, 0
	s_add_i32 s77, s62, s3
	global_load_lds_dwordx4 v136, s[72:73]
	s_mov_b32 m0, s77
	s_nop 0
	global_load_lds_dwordx4 v132, s[78:79]
	s_add_i32 m0, s77, 0x2000
	s_nop 0
	global_load_lds_dwordx4 v136, s[78:79]
	s_waitcnt vmcnt(6)
	s_waitcnt lgkmcnt(0)
	s_barrier
	v_mfma_f32_16x16x32_bf16 v[62:65], v[154:157], v[188:191], v[62:65]
	v_mfma_f32_16x16x32_bf16 v[62:65], v[158:161], v[196:199], v[62:65]
	v_mfma_f32_16x16x32_bf16 v[46:49], v[154:157], v[200:203], v[46:49]
	v_mfma_f32_16x16x32_bf16 v[46:49], v[158:161], v[204:207], v[46:49]
	v_mfma_f32_16x16x32_bf16 v[30:33], v[154:157], v[208:211], v[30:33]
	v_mfma_f32_16x16x32_bf16 v[30:33], v[158:161], v[212:215], v[30:33]
	v_mfma_f32_16x16x32_bf16 v[14:17], v[154:157], v[216:219], v[14:17]
	v_mfma_f32_16x16x32_bf16 v[14:17], v[158:161], v[220:223], v[14:17]
	v_mfma_f32_16x16x32_bf16 v[6:9], v[162:165], v[216:219], v[6:9]
	v_mfma_f32_16x16x32_bf16 v[6:9], v[166:169], v[220:223], v[6:9]
	v_mfma_f32_16x16x32_bf16 v[22:25], v[162:165], v[208:211], v[22:25]
	v_mfma_f32_16x16x32_bf16 v[22:25], v[166:169], v[212:215], v[22:25]
	v_mfma_f32_16x16x32_bf16 v[38:41], v[162:165], v[200:203], v[38:41]
	v_mfma_f32_16x16x32_bf16 v[38:41], v[166:169], v[204:207], v[38:41]
	v_mfma_f32_16x16x32_bf16 v[54:57], v[162:165], v[188:191], v[54:57]
	v_mfma_f32_16x16x32_bf16 v[54:57], v[166:169], v[196:199], v[54:57]
	v_mfma_f32_16x16x32_bf16 v[58:61], v[170:173], v[188:191], v[58:61]
	v_mfma_f32_16x16x32_bf16 v[58:61], v[174:177], v[196:199], v[58:61]
	v_mfma_f32_16x16x32_bf16 v[42:45], v[170:173], v[200:203], v[42:45]
	v_mfma_f32_16x16x32_bf16 v[42:45], v[174:177], v[204:207], v[42:45]
	v_mfma_f32_16x16x32_bf16 v[26:29], v[170:173], v[208:211], v[26:29]
	v_mfma_f32_16x16x32_bf16 v[26:29], v[174:177], v[212:215], v[26:29]
	v_mfma_f32_16x16x32_bf16 v[10:13], v[170:173], v[216:219], v[10:13]
	v_mfma_f32_16x16x32_bf16 v[10:13], v[174:177], v[220:223], v[10:13]
	v_mfma_f32_16x16x32_bf16 v[2:5], v[180:183], v[216:219], v[2:5]
	v_mfma_f32_16x16x32_bf16 v[2:5], v[184:187], v[220:223], v[2:5]
	v_mfma_f32_16x16x32_bf16 v[18:21], v[180:183], v[208:211], v[18:21]
	v_mfma_f32_16x16x32_bf16 v[18:21], v[184:187], v[212:215], v[18:21]
	v_mfma_f32_16x16x32_bf16 v[34:37], v[180:183], v[200:203], v[34:37]
	v_mfma_f32_16x16x32_bf16 v[34:37], v[184:187], v[204:207], v[34:37]
	v_mfma_f32_16x16x32_bf16 v[50:53], v[180:183], v[188:191], v[50:53]
	v_mfma_f32_16x16x32_bf16 v[50:53], v[184:187], v[196:199], v[50:53]
	s_barrier
; #define PG8_STAGE(bufoff, gbase, voff) do { _Pragma("unroll") for (int _i = 0; _i < 2; ++_i) \
;         __builtin_amdgcn_global_load_lds((const unsigned*)((const char*)(gbase) + (voff)[_i]), (PG8_LAS unsigned*)(lds + (bufoff) + ldsw + _i * 8192), 16, 0, 0); } while (0)
; #define PG8_LDA(dst, b, h) do { _Pragma("unroll") for (int m = 0; m < 4; ++m) _Pragma("unroll") for (int k = 0; k < 2; ++k) dst[m][k] = *(const PG8_LAS bf16x8*)(lds + PG8_SA(b, h) + aoff + m * 2048 + k * 1024); } while (0)
; #define PG8_LDB(dst, b, h) do { _Pragma("unroll") for (int n = 0; n < 2; ++n) _Pragma("unroll") for (int k = 0; k < 2; ++k) dst[n][k] = *(const PG8_LAS bf16x8*)(lds + PG8_SB(b, h) + boff + n * 2048 + k * 1024); } while (0)
; #define PG8_MMA(ai, bj, At, Bt) do { __builtin_amdgcn_s_setprio(1); _Pragma("unroll") for (int m = 0; m < 4; ++m) _Pragma("unroll") for (int n = 0; n < 2; ++n) _Pragma("unroll") for (int k = 0; k < 2; ++k) \
;         acc[ai][bj][m][n] = __builtin_amdgcn_mfma_f32_16x16x32_bf16(Bt[n][k], At[m][k], acc[ai][bj][m][n], 0, 0, 0); __builtin_amdgcn_s_setprio(0); } while (0)
; #define PG8_WAIT_V(n) asm volatile("s_waitcnt vmcnt(" #n ")" ::: "memory")
; #define PG8_WAIT_L(n) asm volatile("s_waitcnt lgkmcnt(" #n ")" ::: "memory")
; #define PG8_BAR __builtin_amdgcn_s_barrier()
; #define PG8_SCHED __builtin_amdgcn_sched_barrier(0)
; template <class Epi, class Sched, bool ALIGN_EPI = false, bool SP2 = false>
; __device__ __forceinline__ void gemm_phase(PG8_LAS unsigned char* lds, const Gemm g, const Sched& S, const Epi& E) {
;     ...
;             PG8_LDB(B0, 1, 0); PG8_LDB(B1, 1, 1); PG8_SCHED; PG8_LDA(At, 1, 0); PG8_STAGE(PG8_SA(0, 1), a2 + hstep, voffA);
;             PG8_WAIT_V(8); PG8_WAIT_L(0); PG8_BAR; PG8_MMA(0, 0, At, B0); PG8_MMA(0, 1, At, B1); PG8_BAR; PG8_SCHED;
;             PG8_LDA(At, 1, 1); PG8_STAGE(PG8_SB(1, 0), b3, voffB); PG8_STAGE(PG8_SB(1, 1), b3 + hstep, voffB); PG8_STAGE(PG8_SA(1, 0), a3, voffA);
;             PG8_WAIT_V(8); PG8_WAIT_L(0); PG8_BAR; PG8_MMA(1, 0, At, B0); PG8_MMA(1, 1, At, B1); PG8_BAR; PG8_SCHED;
	s_add_i32 s77, 0, 0x18000
	v_add_u32_e32 v138, s77, v148
	s_add_i32 s78, 0, 0x1c000
	ds_read_b128 v[154:157], v138
	ds_read_b128 v[158:161], v138 offset:1024
	ds_read_b128 v[162:165], v138 offset:2048
	ds_read_b128 v[166:169], v138 offset:3072
	v_add_u32_e32 v138, s78, v148
	ds_read_b128 v[170:173], v138
	ds_read_b128 v[174:177], v138 offset:1024
	ds_read_b128 v[180:183], v138 offset:2048
	ds_read_b128 v[184:187], v138 offset:3072
	s_mov_b32 m0, s28
	s_nop 0
	global_load_lds_dwordx4 v130, s[74:75]
	s_mov_b32 m0, s29
	s_nop 0
	global_load_lds_dwordx4 v134, s[74:75]
	s_add_u32 s74, s74, 0x4000
	s_addc_u32 s75, s75, 0
	s_mov_b32 m0, s30
	ds_read_b128 v[188:191], v152 offset:32768
	ds_read_b128 v[196:199], v152 offset:33792
	ds_read_b128 v[200:203], v152 offset:34816
	ds_read_b128 v[204:207], v152 offset:35840
	ds_read_b128 v[208:211], v152 offset:36864
	ds_read_b128 v[212:215], v152 offset:37888
	ds_read_b128 v[216:219], v152 offset:38912
	ds_read_b128 v[220:223], v152 offset:39936
	global_load_lds_dwordx4 v130, s[74:75]
	s_mov_b32 m0, s31
	s_nop 0
	global_load_lds_dwordx4 v134, s[74:75]
	s_waitcnt vmcnt(8)
	s_waitcnt lgkmcnt(0)
	s_barrier
	v_mfma_f32_16x16x32_bf16 v[126:129], v[154:157], v[188:191], v[126:129]
	v_mfma_f32_16x16x32_bf16 v[126:129], v[158:161], v[196:199], v[126:129]
	v_mfma_f32_16x16x32_bf16 v[110:113], v[154:157], v[200:203], v[110:113]
	v_mfma_f32_16x16x32_bf16 v[110:113], v[158:161], v[204:207], v[110:113]
	v_mfma_f32_16x16x32_bf16 v[94:97], v[154:157], v[208:211], v[94:97]
	v_mfma_f32_16x16x32_bf16 v[94:97], v[158:161], v[212:215], v[94:97]
	v_mfma_f32_16x16x32_bf16 v[78:81], v[154:157], v[216:219], v[78:81]
	v_mfma_f32_16x16x32_bf16 v[78:81], v[158:161], v[220:223], v[78:81]
	v_mfma_f32_16x16x32_bf16 v[70:73], v[162:165], v[216:219], v[70:73]
	v_mfma_f32_16x16x32_bf16 v[70:73], v[166:169], v[220:223], v[70:73]
	v_mfma_f32_16x16x32_bf16 v[86:89], v[162:165], v[208:211], v[86:89]
	v_mfma_f32_16x16x32_bf16 v[86:89], v[166:169], v[212:215], v[86:89]
	v_mfma_f32_16x16x32_bf16 v[102:105], v[162:165], v[200:203], v[102:105]
	v_mfma_f32_16x16x32_bf16 v[102:105], v[166:169], v[204:207], v[102:105]
	v_mfma_f32_16x16x32_bf16 v[118:121], v[162:165], v[188:191], v[118:121]
	v_mfma_f32_16x16x32_bf16 v[118:121], v[166:169], v[196:199], v[118:121]
	v_mfma_f32_16x16x32_bf16 v[122:125], v[170:173], v[188:191], v[122:125]
	v_mfma_f32_16x16x32_bf16 v[122:125], v[174:177], v[196:199], v[122:125]
	v_mfma_f32_16x16x32_bf16 v[106:109], v[170:173], v[200:203], v[106:109]
	v_mfma_f32_16x16x32_bf16 v[106:109], v[174:177], v[204:207], v[106:109]
	v_mfma_f32_16x16x32_bf16 v[90:93], v[170:173], v[208:211], v[90:93]
	v_mfma_f32_16x16x32_bf16 v[90:93], v[174:177], v[212:215], v[90:93]
	v_mfma_f32_16x16x32_bf16 v[74:77], v[170:173], v[216:219], v[74:77]
	v_mfma_f32_16x16x32_bf16 v[74:77], v[174:177], v[220:223], v[74:77]
	v_mfma_f32_16x16x32_bf16 v[66:69], v[180:183], v[216:219], v[66:69]
	v_mfma_f32_16x16x32_bf16 v[66:69], v[184:187], v[220:223], v[66:69]
	v_mfma_f32_16x16x32_bf16 v[82:85], v[180:183], v[208:211], v[82:85]
	v_mfma_f32_16x16x32_bf16 v[82:85], v[184:187], v[212:215], v[82:85]
	v_mfma_f32_16x16x32_bf16 v[98:101], v[180:183], v[200:203], v[98:101]
	v_mfma_f32_16x16x32_bf16 v[98:101], v[184:187], v[204:207], v[98:101]
	v_mfma_f32_16x16x32_bf16 v[114:117], v[180:183], v[188:191], v[114:117]
	v_mfma_f32_16x16x32_bf16 v[114:117], v[184:187], v[196:199], v[114:117]
	s_barrier
	s_add_u32 s74, s72, 0x8000
	s_addc_u32 s75, s73, 0
	s_add_i32 s77, s77, s3
	s_mov_b32 m0, s77
	ds_read_b128 v[188:191], v152 offset:49152
	ds_read_b128 v[196:199], v152 offset:50176
	ds_read_b128 v[200:203], v152 offset:51200
	ds_read_b128 v[204:207], v152 offset:52224
	ds_read_b128 v[208:211], v152 offset:53248
	ds_read_b128 v[212:215], v152 offset:54272
	ds_read_b128 v[216:219], v152 offset:55296
	ds_read_b128 v[220:223], v152 offset:56320
	global_load_lds_dwordx4 v132, s[74:75]
	s_add_i32 m0, s77, 0x2000
	s_add_u32 s72, s72, 0xc000
	v_lshl_add_u64 v[224:225], s[74:75], 0, v[136:137]
	s_addc_u32 s73, s73, 0
	s_add_i32 s74, s78, s3
	global_load_lds_dwordx4 v[224:225], off
	s_mov_b32 m0, s74
	s_nop 0
	global_load_lds_dwordx4 v132, s[72:73]
	s_add_i32 m0, s74, 0x2000
	s_nop 0
	global_load_lds_dwordx4 v136, s[72:73]
	s_waitcnt vmcnt(6)
	s_waitcnt lgkmcnt(0)
	s_barrier
	v_mfma_f32_16x16x32_bf16 v[62:65], v[154:157], v[188:191], v[62:65]
	v_mfma_f32_16x16x32_bf16 v[62:65], v[158:161], v[196:199], v[62:65]
	v_mfma_f32_16x16x32_bf16 v[46:49], v[154:157], v[200:203], v[46:49]
	v_mfma_f32_16x16x32_bf16 v[46:49], v[158:161], v[204:207], v[46:49]
	v_mfma_f32_16x16x32_bf16 v[30:33], v[154:157], v[208:211], v[30:33]
	v_mfma_f32_16x16x32_bf16 v[30:33], v[158:161], v[212:215], v[30:33]
	v_mfma_f32_16x16x32_bf16 v[14:17], v[154:157], v[216:219], v[14:17]
	v_mfma_f32_16x16x32_bf16 v[14:17], v[158:161], v[220:223], v[14:17]
	v_mfma_f32_16x16x32_bf16 v[6:9], v[162:165], v[216:219], v[6:9]
	v_mfma_f32_16x16x32_bf16 v[6:9], v[166:169], v[220:223], v[6:9]
	v_mfma_f32_16x16x32_bf16 v[22:25], v[162:165], v[208:211], v[22:25]
	v_mfma_f32_16x16x32_bf16 v[22:25], v[166:169], v[212:215], v[22:25]
	v_mfma_f32_16x16x32_bf16 v[38:41], v[162:165], v[200:203], v[38:41]
	v_mfma_f32_16x16x32_bf16 v[38:41], v[166:169], v[204:207], v[38:41]
	v_mfma_f32_16x16x32_bf16 v[54:57], v[162:165], v[188:191], v[54:57]
	v_mfma_f32_16x16x32_bf16 v[54:57], v[166:169], v[196:199], v[54:57]
	v_mfma_f32_16x16x32_bf16 v[58:61], v[170:173], v[188:191], v[58:61]
	v_mfma_f32_16x16x32_bf16 v[58:61], v[174:177], v[196:199], v[58:61]
	v_mfma_f32_16x16x32_bf16 v[42:45], v[170:173], v[200:203], v[42:45]
	v_mfma_f32_16x16x32_bf16 v[42:45], v[174:177], v[204:207], v[42:45]
	v_mfma_f32_16x16x32_bf16 v[26:29], v[170:173], v[208:211], v[26:29]
	v_mfma_f32_16x16x32_bf16 v[26:29], v[174:177], v[212:215], v[26:29]
	v_mfma_f32_16x16x32_bf16 v[10:13], v[170:173], v[216:219], v[10:13]
	v_mfma_f32_16x16x32_bf16 v[10:13], v[174:177], v[220:223], v[10:13]
	v_mfma_f32_16x16x32_bf16 v[2:5], v[180:183], v[216:219], v[2:5]
	v_mfma_f32_16x16x32_bf16 v[2:5], v[184:187], v[220:223], v[2:5]
	v_mfma_f32_16x16x32_bf16 v[18:21], v[180:183], v[208:211], v[18:21]
	v_mfma_f32_16x16x32_bf16 v[18:21], v[184:187], v[212:215], v[18:21]
	v_mfma_f32_16x16x32_bf16 v[34:37], v[180:183], v[200:203], v[34:37]
	v_mfma_f32_16x16x32_bf16 v[34:37], v[184:187], v[204:207], v[34:37]
	v_mfma_f32_16x16x32_bf16 v[50:53], v[180:183], v[188:191], v[50:53]
	v_mfma_f32_16x16x32_bf16 v[50:53], v[184:187], v[196:199], v[50:53]
	s_barrier
	s_add_i32 s76, s76, 2
	s_add_u32 s48, s48, 0x10000
	s_addc_u32 s49, s49, 0
	s_add_u32 s68, s68, 0x10000
	s_addc_u32 s69, s69, 0
	s_cmp_gt_u32 s76, 61
	s_cbranch_scc0 .LBB0_115
	s_and_b64 vcc, exec, s[14:15]
	s_cbranch_vccz .LBB0_118
	s_barrier

; #define PG8_STAGE(bufoff, gbase, voff) do { _Pragma("unroll") for (int _i = 0; _i < 2; ++_i) \
;         __builtin_amdgcn_global_load_lds((const unsigned*)((const char*)(gbase) + (voff)[_i]), (PG8_LAS unsigned*)(lds + (bufoff) + ldsw + _i * 8192), 16, 0, 0); } while (0)
; #define PG8_LDA(dst, b, h) do { _Pragma("unroll") for (int m = 0; m < 4; ++m) _Pragma("unroll") for (int k = 0; k < 2; ++k) dst[m][k] = *(const PG8_LAS bf16x8*)(lds + PG8_SA(b, h) + aoff + m * 2048 + k * 1024); } while (0)
; #define PG8_LDB(dst, b, h) do { _Pragma("unroll") for (int n = 0; n < 2; ++n) _Pragma("unroll") for (int k = 0; k < 2; ++k) dst[n][k] = *(const PG8_LAS bf16x8*)(lds + PG8_SB(b, h) + boff + n * 2048 + k * 1024); } while (0)
; #define PG8_MMA(ai, bj, At, Bt) do { __builtin_amdgcn_s_setprio(1); _Pragma("unroll") for (int m = 0; m < 4; ++m) _Pragma("unroll") for (int n = 0; n < 2; ++n) _Pragma("unroll") for (int k = 0; k < 2; ++k) \
;         acc[ai][bj][m][n] = __builtin_amdgcn_mfma_f32_16x16x32_bf16(Bt[n][k], At[m][k], acc[ai][bj][m][n], 0, 0, 0); __builtin_amdgcn_s_setprio(0); } while (0)
; #define PG8_WAIT_V(n) asm volatile("s_waitcnt vmcnt(" #n ")" ::: "memory")
; #define PG8_WAIT_L(n) asm volatile("s_waitcnt lgkmcnt(" #n ")" ::: "memory")
; #define PG8_BAR __builtin_amdgcn_s_barrier()
; #define PG8_SCHED __builtin_amdgcn_sched_barrier(0)
; template <class Epi, class Sched, bool ALIGN_EPI = false, bool SP2 = false>
; __device__ __forceinline__ void gemm_phase(PG8_LAS unsigned char* lds, const Gemm g, const Sched& S, const Epi& E) {
;     ...
;             PG8_LDB(B0, 0, 0); PG8_LDB(B1, 0, 1); PG8_SCHED; PG8_LDA(At, 0, 0); PG8_STAGE(PG8_SA(1, 1), a1 + hstep, voffA);
;             PG8_WAIT_V(8); PG8_WAIT_L(0); PG8_BAR; PG8_MMA(0, 0, At, B0); PG8_MMA(0, 1, At, B1); PG8_BAR; PG8_SCHED;
;             PG8_LDA(At, 0, 1); PG8_STAGE(PG8_SB(0, 0), b2, voffB); PG8_STAGE(PG8_SB(0, 1), b2 + hstep, voffB); PG8_STAGE(PG8_SA(0, 0), a2, voffA);
;             PG8_WAIT_V(8); PG8_WAIT_L(0); PG8_BAR; PG8_MMA(1, 0, At, B0); PG8_MMA(1, 1, At, B1); PG8_BAR; PG8_SCHED;
.LBB0_200:
	ds_read_b128 v[148:151], v154
	ds_read_b128 v[158:161], v154 offset:1024
	ds_read_b128 v[162:165], v154 offset:2048
	ds_read_b128 v[166:169], v154 offset:3072
	ds_read_b128 v[170:173], v155
	ds_read_b128 v[174:177], v155 offset:1024
	ds_read_b128 v[180:183], v155 offset:2048
	ds_read_b128 v[184:187], v155 offset:3072
	s_add_u32 s46, s44, 0x4000
	s_addc_u32 s47, s45, 0
	s_cmpk_eq_i32 s76, 0xa8
	s_cselect_b32 s50, s6, s46
	s_cselect_b32 s51, s7, s47
	s_cselect_b32 s48, s24, s74
	s_cselect_b32 s49, s25, s75
	s_add_u32 s46, s50, 0x8000
	s_addc_u32 s47, s51, 0
	s_sub_u32 s46, s44, 0x4000
	s_subb_u32 s47, s45, 0
	s_mov_b32 m0, s57
	s_nop 0
	global_load_lds_dwordx4 v130, s[46:47]
	s_mov_b32 m0, s58
	s_nop 0
	global_load_lds_dwordx4 v134, s[46:47]
	s_add_i32 m0, s26, 0xc000
	ds_read_b128 v[188:191], v156
	ds_read_b128 v[196:199], v156 offset:1024
	ds_read_b128 v[200:203], v156 offset:2048
	ds_read_b128 v[204:207], v156 offset:3072
	ds_read_b128 v[208:211], v156 offset:4096
	ds_read_b128 v[212:215], v156 offset:5120
	ds_read_b128 v[216:219], v156 offset:6144
	ds_read_b128 v[220:223], v156 offset:7168
	global_load_lds_dwordx4 v140, s[44:45]
	s_add_i32 m0, s26, 0xe000
	s_nop 0
	global_load_lds_dwordx4 v142, s[44:45]
	s_waitcnt vmcnt(8)
	s_waitcnt lgkmcnt(0)
	s_barrier
	v_mfma_f32_16x16x32_bf16 v[126:129], v[148:151], v[188:191], v[126:129]
	v_mfma_f32_16x16x32_bf16 v[126:129], v[158:161], v[196:199], v[126:129]
	v_mfma_f32_16x16x32_bf16 v[110:113], v[148:151], v[200:203], v[110:113]
	v_mfma_f32_16x16x32_bf16 v[110:113], v[158:161], v[204:207], v[110:113]
	v_mfma_f32_16x16x32_bf16 v[94:97], v[148:151], v[208:211], v[94:97]
	v_mfma_f32_16x16x32_bf16 v[94:97], v[158:161], v[212:215], v[94:97]
	v_mfma_f32_16x16x32_bf16 v[78:81], v[148:151], v[216:219], v[78:81]
	v_mfma_f32_16x16x32_bf16 v[78:81], v[158:161], v[220:223], v[78:81]
	v_mfma_f32_16x16x32_bf16 v[74:77], v[162:165], v[216:219], v[74:77]
	v_mfma_f32_16x16x32_bf16 v[74:77], v[166:169], v[220:223], v[74:77]
	v_mfma_f32_16x16x32_bf16 v[90:93], v[162:165], v[208:211], v[90:93]
	v_mfma_f32_16x16x32_bf16 v[90:93], v[166:169], v[212:215], v[90:93]
	v_mfma_f32_16x16x32_bf16 v[106:109], v[162:165], v[200:203], v[106:109]
	v_mfma_f32_16x16x32_bf16 v[106:109], v[166:169], v[204:207], v[106:109]
	v_mfma_f32_16x16x32_bf16 v[122:125], v[162:165], v[188:191], v[122:125]
	v_mfma_f32_16x16x32_bf16 v[122:125], v[166:169], v[196:199], v[122:125]
	v_mfma_f32_16x16x32_bf16 v[118:121], v[170:173], v[188:191], v[118:121]
	v_mfma_f32_16x16x32_bf16 v[118:121], v[174:177], v[196:199], v[118:121]
	v_mfma_f32_16x16x32_bf16 v[102:105], v[170:173], v[200:203], v[102:105]
	v_mfma_f32_16x16x32_bf16 v[102:105], v[174:177], v[204:207], v[102:105]
	v_mfma_f32_16x16x32_bf16 v[86:89], v[170:173], v[208:211], v[86:89]
	v_mfma_f32_16x16x32_bf16 v[86:89], v[174:177], v[212:215], v[86:89]
	v_mfma_f32_16x16x32_bf16 v[70:73], v[170:173], v[216:219], v[70:73]
	v_mfma_f32_16x16x32_bf16 v[70:73], v[174:177], v[220:223], v[70:73]
	v_mfma_f32_16x16x32_bf16 v[66:69], v[180:183], v[216:219], v[66:69]
	v_mfma_f32_16x16x32_bf16 v[66:69], v[184:187], v[220:223], v[66:69]
	v_mfma_f32_16x16x32_bf16 v[82:85], v[180:183], v[208:211], v[82:85]
	v_mfma_f32_16x16x32_bf16 v[82:85], v[184:187], v[212:215], v[82:85]
	v_mfma_f32_16x16x32_bf16 v[98:101], v[180:183], v[200:203], v[98:101]
	v_mfma_f32_16x16x32_bf16 v[98:101], v[184:187], v[204:207], v[98:101]
	v_mfma_f32_16x16x32_bf16 v[114:117], v[180:183], v[188:191], v[114:117]
	v_mfma_f32_16x16x32_bf16 v[114:117], v[184:187], v[196:199], v[114:117]
	s_barrier
	s_add_i32 s77, s59, s3
	s_mov_b32 m0, s77
	ds_read_b128 v[188:191], v156 offset:16384
	ds_read_b128 v[196:199], v156 offset:17408
	ds_read_b128 v[200:203], v156 offset:18432
	ds_read_b128 v[204:207], v156 offset:19456
	ds_read_b128 v[208:211], v156 offset:20480
	ds_read_b128 v[212:215], v156 offset:21504
	ds_read_b128 v[216:219], v156 offset:22528
	ds_read_b128 v[220:223], v156 offset:23552
	global_load_lds_dwordx4 v132, s[48:49]
	s_add_i32 m0, s77, 0x2000
	s_add_u32 s78, s48, 0x4000
	s_addc_u32 s79, s49, 0
	s_add_i32 s77, s61, s3
	global_load_lds_dwordx4 v136, s[48:49]
	s_mov_b32 m0, s77
	s_nop 0
	global_load_lds_dwordx4 v132, s[78:79]
	s_add_i32 m0, s77, 0x2000
	s_nop 0
	global_load_lds_dwordx4 v136, s[78:79]
	s_waitcnt vmcnt(6)
	s_waitcnt lgkmcnt(0)
	s_barrier
	v_mfma_f32_16x16x32_bf16 v[62:65], v[148:151], v[188:191], v[62:65]
	v_mfma_f32_16x16x32_bf16 v[62:65], v[158:161], v[196:199], v[62:65]
	v_mfma_f32_16x16x32_bf16 v[46:49], v[148:151], v[200:203], v[46:49]
	v_mfma_f32_16x16x32_bf16 v[46:49], v[158:161], v[204:207], v[46:49]
	v_mfma_f32_16x16x32_bf16 v[30:33], v[148:151], v[208:211], v[30:33]
	v_mfma_f32_16x16x32_bf16 v[30:33], v[158:161], v[212:215], v[30:33]
	v_mfma_f32_16x16x32_bf16 v[14:17], v[148:151], v[216:219], v[14:17]
	v_mfma_f32_16x16x32_bf16 v[14:17], v[158:161], v[220:223], v[14:17]
	v_mfma_f32_16x16x32_bf16 v[10:13], v[162:165], v[216:219], v[10:13]
	v_mfma_f32_16x16x32_bf16 v[10:13], v[166:169], v[220:223], v[10:13]
	v_mfma_f32_16x16x32_bf16 v[26:29], v[162:165], v[208:211], v[26:29]
	v_mfma_f32_16x16x32_bf16 v[26:29], v[166:169], v[212:215], v[26:29]
	v_mfma_f32_16x16x32_bf16 v[42:45], v[162:165], v[200:203], v[42:45]
	v_mfma_f32_16x16x32_bf16 v[42:45], v[166:169], v[204:207], v[42:45]
	v_mfma_f32_16x16x32_bf16 v[58:61], v[162:165], v[188:191], v[58:61]
	v_mfma_f32_16x16x32_bf16 v[58:61], v[166:169], v[196:199], v[58:61]
	v_mfma_f32_16x16x32_bf16 v[54:57], v[170:173], v[188:191], v[54:57]
	v_mfma_f32_16x16x32_bf16 v[54:57], v[174:177], v[196:199], v[54:57]
	v_mfma_f32_16x16x32_bf16 v[38:41], v[170:173], v[200:203], v[38:41]
	v_mfma_f32_16x16x32_bf16 v[38:41], v[174:177], v[204:207], v[38:41]
	v_mfma_f32_16x16x32_bf16 v[22:25], v[170:173], v[208:211], v[22:25]
	v_mfma_f32_16x16x32_bf16 v[22:25], v[174:177], v[212:215], v[22:25]
	v_mfma_f32_16x16x32_bf16 v[6:9], v[170:173], v[216:219], v[6:9]
	v_mfma_f32_16x16x32_bf16 v[6:9], v[174:177], v[220:223], v[6:9]
	v_mfma_f32_16x16x32_bf16 v[2:5], v[180:183], v[216:219], v[2:5]
	v_mfma_f32_16x16x32_bf16 v[2:5], v[184:187], v[220:223], v[2:5]
	v_mfma_f32_16x16x32_bf16 v[18:21], v[180:183], v[208:211], v[18:21]
	v_mfma_f32_16x16x32_bf16 v[18:21], v[184:187], v[212:215], v[18:21]
	v_mfma_f32_16x16x32_bf16 v[34:37], v[180:183], v[200:203], v[34:37]
	v_mfma_f32_16x16x32_bf16 v[34:37], v[184:187], v[204:207], v[34:37]
	v_mfma_f32_16x16x32_bf16 v[50:53], v[180:183], v[188:191], v[50:53]
	v_mfma_f32_16x16x32_bf16 v[50:53], v[184:187], v[196:199], v[50:53]
	s_barrier
; #define PG8_STAGE(bufoff, gbase, voff) do { _Pragma("unroll") for (int _i = 0; _i < 2; ++_i) \
;         __builtin_amdgcn_global_load_lds((const unsigned*)((const char*)(gbase) + (voff)[_i]), (PG8_LAS unsigned*)(lds + (bufoff) + ldsw + _i * 8192), 16, 0, 0); } while (0)
; #define PG8_LDA(dst, b, h) do { _Pragma("unroll") for (int m = 0; m < 4; ++m) _Pragma("unroll") for (int k = 0; k < 2; ++k) dst[m][k] = *(const PG8_LAS bf16x8*)(lds + PG8_SA(b, h) + aoff + m * 2048 + k * 1024); } while (0)
; #define PG8_LDB(dst, b, h) do { _Pragma("unroll") for (int n = 0; n < 2; ++n) _Pragma("unroll") for (int k = 0; k < 2; ++k) dst[n][k] = *(const PG8_LAS bf16x8*)(lds + PG8_SB(b, h) + boff + n * 2048 + k * 1024); } while (0)
; #define PG8_MMA(ai, bj, At, Bt) do { __builtin_amdgcn_s_setprio(1); _Pragma("unroll") for (int m = 0; m < 4; ++m) _Pragma("unroll") for (int n = 0; n < 2; ++n) _Pragma("unroll") for (int k = 0; k < 2; ++k) \
;         acc[ai][bj][m][n] = __builtin_amdgcn_mfma_f32_16x16x32_bf16(Bt[n][k], At[m][k], acc[ai][bj][m][n], 0, 0, 0); __builtin_amdgcn_s_setprio(0); } while (0)
; #define PG8_WAIT_V(n) asm volatile("s_waitcnt vmcnt(" #n ")" ::: "memory")
; #define PG8_WAIT_L(n) asm volatile("s_waitcnt lgkmcnt(" #n ")" ::: "memory")
; #define PG8_BAR __builtin_amdgcn_s_barrier()
; #define PG8_SCHED __builtin_amdgcn_sched_barrier(0)
; template <class Epi, class Sched, bool ALIGN_EPI = false, bool SP2 = false>
; __device__ __forceinline__ void gemm_phase(PG8_LAS unsigned char* lds, const Gemm g, const Sched& S, const Epi& E) {
;     ...
;             PG8_LDB(B0, 1, 0); PG8_LDB(B1, 1, 1); PG8_SCHED; PG8_LDA(At, 1, 0); PG8_STAGE(PG8_SA(0, 1), a2 + hstep, voffA);
;             PG8_WAIT_V(8); PG8_WAIT_L(0); PG8_BAR; PG8_MMA(0, 0, At, B0); PG8_MMA(0, 1, At, B1); PG8_BAR; PG8_SCHED;
;             PG8_LDA(At, 1, 1); PG8_STAGE(PG8_SB(1, 0), b3, voffB); PG8_STAGE(PG8_SB(1, 1), b3 + hstep, voffB); PG8_STAGE(PG8_SA(1, 0), a3, voffA);
;             PG8_WAIT_V(8); PG8_WAIT_L(0); PG8_BAR; PG8_MMA(1, 0, At, B0); PG8_MMA(1, 1, At, B1); PG8_BAR; PG8_SCHED;
	s_add_i32 s77, 0, 0x18000
	v_add_u32_e32 v138, s77, v153
	s_add_i32 s78, 0, 0x1c000
	ds_read_b128 v[148:151], v138
	ds_read_b128 v[158:161], v138 offset:1024
	ds_read_b128 v[162:165], v138 offset:2048
	ds_read_b128 v[166:169], v138 offset:3072
	v_add_u32_e32 v138, s78, v153
	ds_read_b128 v[170:173], v138
	ds_read_b128 v[174:177], v138 offset:1024
	ds_read_b128 v[180:183], v138 offset:2048
	ds_read_b128 v[184:187], v138 offset:3072
	s_mov_b32 m0, s26
	s_nop 0
	global_load_lds_dwordx4 v130, s[50:51]
	s_mov_b32 m0, s27
	s_nop 0
	global_load_lds_dwordx4 v134, s[50:51]
	s_add_u32 s50, s50, 0x4000
	s_addc_u32 s51, s51, 0
	s_mov_b32 m0, s28
	ds_read_b128 v[188:191], v156 offset:32768
	ds_read_b128 v[196:199], v156 offset:33792
	ds_read_b128 v[200:203], v156 offset:34816
	ds_read_b128 v[204:207], v156 offset:35840
	ds_read_b128 v[208:211], v156 offset:36864
	ds_read_b128 v[212:215], v156 offset:37888
	ds_read_b128 v[216:219], v156 offset:38912
	ds_read_b128 v[220:223], v156 offset:39936
	global_load_lds_dwordx4 v130, s[50:51]
	s_mov_b32 m0, s29
	s_nop 0
	global_load_lds_dwordx4 v134, s[50:51]
	s_waitcnt vmcnt(8)
	s_waitcnt lgkmcnt(0)
	s_barrier
	v_mfma_f32_16x16x32_bf16 v[126:129], v[148:151], v[188:191], v[126:129]
	v_mfma_f32_16x16x32_bf16 v[126:129], v[158:161], v[196:199], v[126:129]
	v_mfma_f32_16x16x32_bf16 v[110:113], v[148:151], v[200:203], v[110:113]
	v_mfma_f32_16x16x32_bf16 v[110:113], v[158:161], v[204:207], v[110:113]
	v_mfma_f32_16x16x32_bf16 v[94:97], v[148:151], v[208:211], v[94:97]
	v_mfma_f32_16x16x32_bf16 v[94:97], v[158:161], v[212:215], v[94:97]
	v_mfma_f32_16x16x32_bf16 v[78:81], v[148:151], v[216:219], v[78:81]
	v_mfma_f32_16x16x32_bf16 v[78:81], v[158:161], v[220:223], v[78:81]
	v_mfma_f32_16x16x32_bf16 v[74:77], v[162:165], v[216:219], v[74:77]
	v_mfma_f32_16x16x32_bf16 v[74:77], v[166:169], v[220:223], v[74:77]
	v_mfma_f32_16x16x32_bf16 v[90:93], v[162:165], v[208:211], v[90:93]
	v_mfma_f32_16x16x32_bf16 v[90:93], v[166:169], v[212:215], v[90:93]
	v_mfma_f32_16x16x32_bf16 v[106:109], v[162:165], v[200:203], v[106:109]
	v_mfma_f32_16x16x32_bf16 v[106:109], v[166:169], v[204:207], v[106:109]
	v_mfma_f32_16x16x32_bf16 v[122:125], v[162:165], v[188:191], v[122:125]
	v_mfma_f32_16x16x32_bf16 v[122:125], v[166:169], v[196:199], v[122:125]
	v_mfma_f32_16x16x32_bf16 v[118:121], v[170:173], v[188:191], v[118:121]
	v_mfma_f32_16x16x32_bf16 v[118:121], v[174:177], v[196:199], v[118:121]
	v_mfma_f32_16x16x32_bf16 v[102:105], v[170:173], v[200:203], v[102:105]
	v_mfma_f32_16x16x32_bf16 v[102:105], v[174:177], v[204:207], v[102:105]
	v_mfma_f32_16x16x32_bf16 v[86:89], v[170:173], v[208:211], v[86:89]
	v_mfma_f32_16x16x32_bf16 v[86:89], v[174:177], v[212:215], v[86:89]
	v_mfma_f32_16x16x32_bf16 v[70:73], v[170:173], v[216:219], v[70:73]
	v_mfma_f32_16x16x32_bf16 v[70:73], v[174:177], v[220:223], v[70:73]
	v_mfma_f32_16x16x32_bf16 v[66:69], v[180:183], v[216:219], v[66:69]
	v_mfma_f32_16x16x32_bf16 v[66:69], v[184:187], v[220:223], v[66:69]
	v_mfma_f32_16x16x32_bf16 v[82:85], v[180:183], v[208:211], v[82:85]
	v_mfma_f32_16x16x32_bf16 v[82:85], v[184:187], v[212:215], v[82:85]
	v_mfma_f32_16x16x32_bf16 v[98:101], v[180:183], v[200:203], v[98:101]
	v_mfma_f32_16x16x32_bf16 v[98:101], v[184:187], v[204:207], v[98:101]
	v_mfma_f32_16x16x32_bf16 v[114:117], v[180:183], v[188:191], v[114:117]
	v_mfma_f32_16x16x32_bf16 v[114:117], v[184:187], v[196:199], v[114:117]
	s_barrier
	s_add_u32 s50, s48, 0x8000
	s_addc_u32 s51, s49, 0
	s_add_i32 s77, s77, s3
	s_mov_b32 m0, s77
	ds_read_b128 v[188:191], v156 offset:49152
	ds_read_b128 v[196:199], v156 offset:50176
	ds_read_b128 v[200:203], v156 offset:51200
	ds_read_b128 v[204:207], v156 offset:52224
	ds_read_b128 v[208:211], v156 offset:53248
	ds_read_b128 v[212:215], v156 offset:54272
	ds_read_b128 v[216:219], v156 offset:55296
	ds_read_b128 v[220:223], v156 offset:56320
	global_load_lds_dwordx4 v132, s[50:51]
	s_add_i32 m0, s77, 0x2000
	s_add_u32 s48, s48, 0xc000
	v_lshl_add_u64 v[224:225], s[50:51], 0, v[136:137]
	s_addc_u32 s49, s49, 0
	s_add_i32 s50, s78, s3
	global_load_lds_dwordx4 v[224:225], off
	s_mov_b32 m0, s50
	s_nop 0
	global_load_lds_dwordx4 v132, s[48:49]
	s_add_i32 m0, s50, 0x2000
	s_nop 0
	global_load_lds_dwordx4 v136, s[48:49]
	s_waitcnt vmcnt(6)
	s_waitcnt lgkmcnt(0)
	s_barrier
	v_mfma_f32_16x16x32_bf16 v[62:65], v[148:151], v[188:191], v[62:65]
	v_mfma_f32_16x16x32_bf16 v[62:65], v[158:161], v[196:199], v[62:65]
	v_mfma_f32_16x16x32_bf16 v[46:49], v[148:151], v[200:203], v[46:49]
	v_mfma_f32_16x16x32_bf16 v[46:49], v[158:161], v[204:207], v[46:49]
	v_mfma_f32_16x16x32_bf16 v[30:33], v[148:151], v[208:211], v[30:33]
	v_mfma_f32_16x16x32_bf16 v[30:33], v[158:161], v[212:215], v[30:33]
	v_mfma_f32_16x16x32_bf16 v[14:17], v[148:151], v[216:219], v[14:17]
	v_mfma_f32_16x16x32_bf16 v[14:17], v[158:161], v[220:223], v[14:17]
	v_mfma_f32_16x16x32_bf16 v[10:13], v[162:165], v[216:219], v[10:13]
	v_mfma_f32_16x16x32_bf16 v[10:13], v[166:169], v[220:223], v[10:13]
	v_mfma_f32_16x16x32_bf16 v[26:29], v[162:165], v[208:211], v[26:29]
	v_mfma_f32_16x16x32_bf16 v[26:29], v[166:169], v[212:215], v[26:29]
	v_mfma_f32_16x16x32_bf16 v[42:45], v[162:165], v[200:203], v[42:45]
	v_mfma_f32_16x16x32_bf16 v[42:45], v[166:169], v[204:207], v[42:45]
	v_mfma_f32_16x16x32_bf16 v[58:61], v[162:165], v[188:191], v[58:61]
	v_mfma_f32_16x16x32_bf16 v[58:61], v[166:169], v[196:199], v[58:61]
	v_mfma_f32_16x16x32_bf16 v[54:57], v[170:173], v[188:191], v[54:57]
	v_mfma_f32_16x16x32_bf16 v[54:57], v[174:177], v[196:199], v[54:57]
	v_mfma_f32_16x16x32_bf16 v[38:41], v[170:173], v[200:203], v[38:41]
	v_mfma_f32_16x16x32_bf16 v[38:41], v[174:177], v[204:207], v[38:41]
	v_mfma_f32_16x16x32_bf16 v[22:25], v[170:173], v[208:211], v[22:25]
	v_mfma_f32_16x16x32_bf16 v[22:25], v[174:177], v[212:215], v[22:25]
	v_mfma_f32_16x16x32_bf16 v[6:9], v[170:173], v[216:219], v[6:9]
	v_mfma_f32_16x16x32_bf16 v[6:9], v[174:177], v[220:223], v[6:9]
	v_mfma_f32_16x16x32_bf16 v[2:5], v[180:183], v[216:219], v[2:5]
	v_mfma_f32_16x16x32_bf16 v[2:5], v[184:187], v[220:223], v[2:5]
	v_mfma_f32_16x16x32_bf16 v[18:21], v[180:183], v[208:211], v[18:21]
	v_mfma_f32_16x16x32_bf16 v[18:21], v[184:187], v[212:215], v[18:21]
	v_mfma_f32_16x16x32_bf16 v[34:37], v[180:183], v[200:203], v[34:37]
	v_mfma_f32_16x16x32_bf16 v[34:37], v[184:187], v[204:207], v[34:37]
	v_mfma_f32_16x16x32_bf16 v[50:53], v[180:183], v[188:191], v[50:53]
	v_mfma_f32_16x16x32_bf16 v[50:53], v[184:187], v[196:199], v[50:53]
	s_barrier
	s_add_i32 s76, s76, 2
	s_add_u32 s44, s44, 0x10000
	s_addc_u32 s45, s45, 0
	s_add_u32 s74, s74, 0x10000
	s_addc_u32 s75, s75, 0
	s_cmpk_gt_u32 s76, 0xa9
	s_cbranch_scc0 .LBB0_200
	s_and_b64 vcc, exec, s[18:19]
	s_cbranch_vccz .LBB0_203
	s_barrier

; #define PG8_STAGE(bufoff, gbase, voff) do { _Pragma("unroll") for (int _i = 0; _i < 2; ++_i) \
;         __builtin_amdgcn_global_load_lds((const unsigned*)((const char*)(gbase) + (voff)[_i]), (PG8_LAS unsigned*)(lds + (bufoff) + ldsw + _i * 8192), 16, 0, 0); } while (0)
; #define PG8_LDA(dst, b, h) do { _Pragma("unroll") for (int m = 0; m < 4; ++m) _Pragma("unroll") for (int k = 0; k < 2; ++k) dst[m][k] = *(const PG8_LAS bf16x8*)(lds + PG8_SA(b, h) + aoff + m * 2048 + k * 1024); } while (0)
; #define PG8_LDB(dst, b, h) do { _Pragma("unroll") for (int n = 0; n < 2; ++n) _Pragma("unroll") for (int k = 0; k < 2; ++k) dst[n][k] = *(const PG8_LAS bf16x8*)(lds + PG8_SB(b, h) + boff + n * 2048 + k * 1024); } while (0)
; #define PG8_MMA(ai, bj, At, Bt) do { __builtin_amdgcn_s_setprio(1); _Pragma("unroll") for (int m = 0; m < 4; ++m) _Pragma("unroll") for (int n = 0; n < 2; ++n) _Pragma("unroll") for (int k = 0; k < 2; ++k) \
;         acc[ai][bj][m][n] = __builtin_amdgcn_mfma_f32_16x16x32_bf16(Bt[n][k], At[m][k], acc[ai][bj][m][n], 0, 0, 0); __builtin_amdgcn_s_setprio(0); } while (0)
; #define PG8_WAIT_V(n) asm volatile("s_waitcnt vmcnt(" #n ")" ::: "memory")
; #define PG8_WAIT_L(n) asm volatile("s_waitcnt lgkmcnt(" #n ")" ::: "memory")
; #define PG8_BAR __builtin_amdgcn_s_barrier()
; #define PG8_SCHED __builtin_amdgcn_sched_barrier(0)
; template <class Epi, class Sched, bool ALIGN_EPI = false, bool SP2 = false>
; __device__ __forceinline__ void gemm_phase(PG8_LAS unsigned char* lds, const Gemm g, const Sched& S, const Epi& E) {
;     ...
;             PG8_LDB(B0, 0, 0); PG8_LDB(B1, 0, 1); PG8_SCHED; PG8_LDA(At, 0, 0); PG8_STAGE(PG8_SA(1, 1), a1 + hstep, voffA);
;             PG8_WAIT_V(8); PG8_WAIT_L(0); PG8_BAR; PG8_MMA(0, 0, At, B0); PG8_MMA(0, 1, At, B1); PG8_BAR; PG8_SCHED;
;             PG8_LDA(At, 0, 1); PG8_STAGE(PG8_SB(0, 0), b2, voffB); PG8_STAGE(PG8_SB(0, 1), b2 + hstep, voffB); PG8_STAGE(PG8_SA(0, 0), a2, voffA);
;             PG8_WAIT_V(8); PG8_WAIT_L(0); PG8_BAR; PG8_MMA(1, 0, At, B0); PG8_MMA(1, 1, At, B1); PG8_BAR; PG8_SCHED;
.LBB0_290:
	ds_read_b128 v[146:149], v162
	ds_read_b128 v[150:153], v162 offset:1024
	ds_read_b128 v[154:157], v162 offset:2048
	ds_read_b128 v[168:171], v162 offset:3072
	ds_read_b128 v[172:175], v163
	ds_read_b128 v[180:183], v163 offset:1024
	ds_read_b128 v[184:187], v163 offset:2048
	ds_read_b128 v[188:191], v163 offset:3072
	s_add_u32 s59, s72, 0x4000
	s_addc_u32 s62, s73, 0
	s_cmp_eq_u32 s58, 60
	s_cselect_b32 s78, s19, s59
	s_cselect_b32 s79, s5, s62
	s_cselect_b32 s76, s26, s33
	s_cselect_b32 s77, s17, s56
	s_add_u32 s74, s78, 0x8000
	s_addc_u32 s75, s79, 0
	s_sub_u32 s74, s72, 0x4000
	s_subb_u32 s75, s73, 0
	s_mov_b32 m0, s51
	s_nop 0
	global_load_lds_dwordx4 v130, s[74:75]
	s_mov_b32 m0, s57
	s_nop 0
	global_load_lds_dwordx4 v134, s[74:75]
	s_add_i32 m0, s15, 0xc000
	ds_read_b128 v[198:201], v164
	ds_read_b128 v[202:205], v164 offset:1024
	ds_read_b128 v[206:209], v164 offset:2048
	ds_read_b128 v[210:213], v164 offset:3072
	ds_read_b128 v[214:217], v164 offset:4096
	ds_read_b128 v[218:221], v164 offset:5120
	ds_read_b128 v[222:225], v164 offset:6144
	ds_read_b128 v[226:229], v164 offset:7168
	global_load_lds_dwordx4 v138, s[72:73]
	s_add_i32 m0, s15, 0xe000
	s_nop 0
	global_load_lds_dwordx4 v140, s[72:73]
	s_waitcnt vmcnt(8)
	s_waitcnt lgkmcnt(0)
	s_barrier
	v_mfma_f32_16x16x32_bf16 v[126:129], v[146:149], v[198:201], v[126:129]
	v_mfma_f32_16x16x32_bf16 v[126:129], v[150:153], v[202:205], v[126:129]
	v_mfma_f32_16x16x32_bf16 v[110:113], v[146:149], v[206:209], v[110:113]
	v_mfma_f32_16x16x32_bf16 v[110:113], v[150:153], v[210:213], v[110:113]
	v_mfma_f32_16x16x32_bf16 v[94:97], v[146:149], v[214:217], v[94:97]
	v_mfma_f32_16x16x32_bf16 v[94:97], v[150:153], v[218:221], v[94:97]
	v_mfma_f32_16x16x32_bf16 v[78:81], v[146:149], v[222:225], v[78:81]
	v_mfma_f32_16x16x32_bf16 v[78:81], v[150:153], v[226:229], v[78:81]
	v_mfma_f32_16x16x32_bf16 v[74:77], v[154:157], v[222:225], v[74:77]
	v_mfma_f32_16x16x32_bf16 v[74:77], v[168:171], v[226:229], v[74:77]
	v_mfma_f32_16x16x32_bf16 v[90:93], v[154:157], v[214:217], v[90:93]
	v_mfma_f32_16x16x32_bf16 v[90:93], v[168:171], v[218:221], v[90:93]
	v_mfma_f32_16x16x32_bf16 v[106:109], v[154:157], v[206:209], v[106:109]
	v_mfma_f32_16x16x32_bf16 v[106:109], v[168:171], v[210:213], v[106:109]
	v_mfma_f32_16x16x32_bf16 v[122:125], v[154:157], v[198:201], v[122:125]
	v_mfma_f32_16x16x32_bf16 v[122:125], v[168:171], v[202:205], v[122:125]
	v_mfma_f32_16x16x32_bf16 v[118:121], v[172:175], v[198:201], v[118:121]
	v_mfma_f32_16x16x32_bf16 v[118:121], v[180:183], v[202:205], v[118:121]
	v_mfma_f32_16x16x32_bf16 v[102:105], v[172:175], v[206:209], v[102:105]
	v_mfma_f32_16x16x32_bf16 v[102:105], v[180:183], v[210:213], v[102:105]
	v_mfma_f32_16x16x32_bf16 v[86:89], v[172:175], v[214:217], v[86:89]
	v_mfma_f32_16x16x32_bf16 v[86:89], v[180:183], v[218:221], v[86:89]
	v_mfma_f32_16x16x32_bf16 v[70:73], v[172:175], v[222:225], v[70:73]
	v_mfma_f32_16x16x32_bf16 v[70:73], v[180:183], v[226:229], v[70:73]
	v_mfma_f32_16x16x32_bf16 v[66:69], v[184:187], v[222:225], v[66:69]
	v_mfma_f32_16x16x32_bf16 v[66:69], v[188:191], v[226:229], v[66:69]
	v_mfma_f32_16x16x32_bf16 v[82:85], v[184:187], v[214:217], v[82:85]
	v_mfma_f32_16x16x32_bf16 v[82:85], v[188:191], v[218:221], v[82:85]
	v_mfma_f32_16x16x32_bf16 v[98:101], v[184:187], v[206:209], v[98:101]
	v_mfma_f32_16x16x32_bf16 v[98:101], v[188:191], v[210:213], v[98:101]
	v_mfma_f32_16x16x32_bf16 v[114:117], v[184:187], v[198:201], v[114:117]
	v_mfma_f32_16x16x32_bf16 v[114:117], v[188:191], v[202:205], v[114:117]
	s_barrier
	s_add_i32 s59, s81, s3
	s_mov_b32 m0, s59
	ds_read_b128 v[198:201], v164 offset:16384
	ds_read_b128 v[202:205], v164 offset:17408
	ds_read_b128 v[206:209], v164 offset:18432
	ds_read_b128 v[210:213], v164 offset:19456
	ds_read_b128 v[214:217], v164 offset:20480
	ds_read_b128 v[218:221], v164 offset:21504
	ds_read_b128 v[222:225], v164 offset:22528
	ds_read_b128 v[226:229], v164 offset:23552
	global_load_lds_dwordx4 v132, s[76:77]
	s_add_i32 m0, s59, 0x2000
	s_add_u32 s62, s76, 0x4000
	s_addc_u32 s63, s77, 0
	s_add_i32 s59, s82, s3
	global_load_lds_dwordx4 v136, s[76:77]
	s_mov_b32 m0, s59
	s_nop 0
	global_load_lds_dwordx4 v132, s[62:63]
	s_add_i32 m0, s59, 0x2000
	s_nop 0
	global_load_lds_dwordx4 v136, s[62:63]
	s_waitcnt vmcnt(6)
	s_waitcnt lgkmcnt(0)
	s_barrier
	v_mfma_f32_16x16x32_bf16 v[62:65], v[146:149], v[198:201], v[62:65]
	v_mfma_f32_16x16x32_bf16 v[62:65], v[150:153], v[202:205], v[62:65]
	v_mfma_f32_16x16x32_bf16 v[46:49], v[146:149], v[206:209], v[46:49]
	v_mfma_f32_16x16x32_bf16 v[46:49], v[150:153], v[210:213], v[46:49]
	v_mfma_f32_16x16x32_bf16 v[30:33], v[146:149], v[214:217], v[30:33]
	v_mfma_f32_16x16x32_bf16 v[30:33], v[150:153], v[218:221], v[30:33]
	v_mfma_f32_16x16x32_bf16 v[14:17], v[146:149], v[222:225], v[14:17]
	v_mfma_f32_16x16x32_bf16 v[14:17], v[150:153], v[226:229], v[14:17]
	v_mfma_f32_16x16x32_bf16 v[10:13], v[154:157], v[222:225], v[10:13]
	v_mfma_f32_16x16x32_bf16 v[10:13], v[168:171], v[226:229], v[10:13]
	v_mfma_f32_16x16x32_bf16 v[26:29], v[154:157], v[214:217], v[26:29]
	v_mfma_f32_16x16x32_bf16 v[26:29], v[168:171], v[218:221], v[26:29]
	v_mfma_f32_16x16x32_bf16 v[42:45], v[154:157], v[206:209], v[42:45]
	v_mfma_f32_16x16x32_bf16 v[42:45], v[168:171], v[210:213], v[42:45]
	v_mfma_f32_16x16x32_bf16 v[58:61], v[154:157], v[198:201], v[58:61]
	v_mfma_f32_16x16x32_bf16 v[58:61], v[168:171], v[202:205], v[58:61]
	v_mfma_f32_16x16x32_bf16 v[54:57], v[172:175], v[198:201], v[54:57]
	v_mfma_f32_16x16x32_bf16 v[54:57], v[180:183], v[202:205], v[54:57]
	v_mfma_f32_16x16x32_bf16 v[38:41], v[172:175], v[206:209], v[38:41]
	v_mfma_f32_16x16x32_bf16 v[38:41], v[180:183], v[210:213], v[38:41]
	v_mfma_f32_16x16x32_bf16 v[22:25], v[172:175], v[214:217], v[22:25]
	v_mfma_f32_16x16x32_bf16 v[22:25], v[180:183], v[218:221], v[22:25]
	v_mfma_f32_16x16x32_bf16 v[6:9], v[172:175], v[222:225], v[6:9]
	v_mfma_f32_16x16x32_bf16 v[6:9], v[180:183], v[226:229], v[6:9]
	v_mfma_f32_16x16x32_bf16 v[2:5], v[184:187], v[222:225], v[2:5]
	v_mfma_f32_16x16x32_bf16 v[2:5], v[188:191], v[226:229], v[2:5]
	v_mfma_f32_16x16x32_bf16 v[18:21], v[184:187], v[214:217], v[18:21]
	v_mfma_f32_16x16x32_bf16 v[18:21], v[188:191], v[218:221], v[18:21]
	v_mfma_f32_16x16x32_bf16 v[34:37], v[184:187], v[206:209], v[34:37]
	v_mfma_f32_16x16x32_bf16 v[34:37], v[188:191], v[210:213], v[34:37]
	v_mfma_f32_16x16x32_bf16 v[50:53], v[184:187], v[198:201], v[50:53]
	v_mfma_f32_16x16x32_bf16 v[50:53], v[188:191], v[202:205], v[50:53]
	s_barrier
; #define PG8_STAGE(bufoff, gbase, voff) do { _Pragma("unroll") for (int _i = 0; _i < 2; ++_i) \
;         __builtin_amdgcn_global_load_lds((const unsigned*)((const char*)(gbase) + (voff)[_i]), (PG8_LAS unsigned*)(lds + (bufoff) + ldsw + _i * 8192), 16, 0, 0); } while (0)
; #define PG8_LDA(dst, b, h) do { _Pragma("unroll") for (int m = 0; m < 4; ++m) _Pragma("unroll") for (int k = 0; k < 2; ++k) dst[m][k] = *(const PG8_LAS bf16x8*)(lds + PG8_SA(b, h) + aoff + m * 2048 + k * 1024); } while (0)
; #define PG8_LDB(dst, b, h) do { _Pragma("unroll") for (int n = 0; n < 2; ++n) _Pragma("unroll") for (int k = 0; k < 2; ++k) dst[n][k] = *(const PG8_LAS bf16x8*)(lds + PG8_SB(b, h) + boff + n * 2048 + k * 1024); } while (0)
; #define PG8_MMA(ai, bj, At, Bt) do { __builtin_amdgcn_s_setprio(1); _Pragma("unroll") for (int m = 0; m < 4; ++m) _Pragma("unroll") for (int n = 0; n < 2; ++n) _Pragma("unroll") for (int k = 0; k < 2; ++k) \
;         acc[ai][bj][m][n] = __builtin_amdgcn_mfma_f32_16x16x32_bf16(Bt[n][k], At[m][k], acc[ai][bj][m][n], 0, 0, 0); __builtin_amdgcn_s_setprio(0); } while (0)
; #define PG8_WAIT_V(n) asm volatile("s_waitcnt vmcnt(" #n ")" ::: "memory")
; #define PG8_WAIT_L(n) asm volatile("s_waitcnt lgkmcnt(" #n ")" ::: "memory")
; #define PG8_BAR __builtin_amdgcn_s_barrier()
; #define PG8_SCHED __builtin_amdgcn_sched_barrier(0)
; template <class Epi, class Sched, bool ALIGN_EPI = false, bool SP2 = false>
; __device__ __forceinline__ void gemm_phase(PG8_LAS unsigned char* lds, const Gemm g, const Sched& S, const Epi& E) {
;     ...
;             PG8_LDB(B0, 1, 0); PG8_LDB(B1, 1, 1); PG8_SCHED; PG8_LDA(At, 1, 0); PG8_STAGE(PG8_SA(0, 1), a2 + hstep, voffA);
;             PG8_WAIT_V(8); PG8_WAIT_L(0); PG8_BAR; PG8_MMA(0, 0, At, B0); PG8_MMA(0, 1, At, B1); PG8_BAR; PG8_SCHED;
;             PG8_LDA(At, 1, 1); PG8_STAGE(PG8_SB(1, 0), b3, voffB); PG8_STAGE(PG8_SB(1, 1), b3 + hstep, voffB); PG8_STAGE(PG8_SA(1, 0), a3, voffA);
;             PG8_WAIT_V(8); PG8_WAIT_L(0); PG8_BAR; PG8_MMA(1, 0, At, B0); PG8_MMA(1, 1, At, B1); PG8_BAR; PG8_SCHED;
	s_add_i32 s59, 0, 0x18000
	v_add_u32_e32 v158, s59, v160
	s_add_i32 s64, 0, 0x1c000
	ds_read_b128 v[146:149], v158
	ds_read_b128 v[150:153], v158 offset:1024
	ds_read_b128 v[154:157], v158 offset:2048
	ds_read_b128 v[168:171], v158 offset:3072
	v_add_u32_e32 v158, s64, v160
	ds_read_b128 v[172:175], v158
	ds_read_b128 v[180:183], v158 offset:1024
	ds_read_b128 v[184:187], v158 offset:2048
	ds_read_b128 v[188:191], v158 offset:3072
	s_mov_b32 m0, s15
	s_nop 0
	global_load_lds_dwordx4 v130, s[78:79]
	s_mov_b32 m0, s27
	s_nop 0
	global_load_lds_dwordx4 v134, s[78:79]
	s_add_u32 s62, s78, 0x4000
	s_addc_u32 s63, s79, 0
	s_mov_b32 m0, s28
	ds_read_b128 v[198:201], v164 offset:32768
	ds_read_b128 v[202:205], v164 offset:33792
	ds_read_b128 v[206:209], v164 offset:34816
	ds_read_b128 v[210:213], v164 offset:35840
	ds_read_b128 v[214:217], v164 offset:36864
	ds_read_b128 v[218:221], v164 offset:37888
	ds_read_b128 v[222:225], v164 offset:38912
	ds_read_b128 v[226:229], v164 offset:39936
	global_load_lds_dwordx4 v130, s[62:63]
	s_mov_b32 m0, s29
	s_nop 0
	global_load_lds_dwordx4 v134, s[62:63]
	s_waitcnt vmcnt(8)
	s_waitcnt lgkmcnt(0)
	s_barrier
	v_mfma_f32_16x16x32_bf16 v[126:129], v[146:149], v[198:201], v[126:129]
	v_mfma_f32_16x16x32_bf16 v[126:129], v[150:153], v[202:205], v[126:129]
	v_mfma_f32_16x16x32_bf16 v[110:113], v[146:149], v[206:209], v[110:113]
	v_mfma_f32_16x16x32_bf16 v[110:113], v[150:153], v[210:213], v[110:113]
	v_mfma_f32_16x16x32_bf16 v[94:97], v[146:149], v[214:217], v[94:97]
	v_mfma_f32_16x16x32_bf16 v[94:97], v[150:153], v[218:221], v[94:97]
	v_mfma_f32_16x16x32_bf16 v[78:81], v[146:149], v[222:225], v[78:81]
	v_mfma_f32_16x16x32_bf16 v[78:81], v[150:153], v[226:229], v[78:81]
	v_mfma_f32_16x16x32_bf16 v[74:77], v[154:157], v[222:225], v[74:77]
	v_mfma_f32_16x16x32_bf16 v[74:77], v[168:171], v[226:229], v[74:77]
	v_mfma_f32_16x16x32_bf16 v[90:93], v[154:157], v[214:217], v[90:93]
	v_mfma_f32_16x16x32_bf16 v[90:93], v[168:171], v[218:221], v[90:93]
	v_mfma_f32_16x16x32_bf16 v[106:109], v[154:157], v[206:209], v[106:109]
	v_mfma_f32_16x16x32_bf16 v[106:109], v[168:171], v[210:213], v[106:109]
	v_mfma_f32_16x16x32_bf16 v[122:125], v[154:157], v[198:201], v[122:125]
	v_mfma_f32_16x16x32_bf16 v[122:125], v[168:171], v[202:205], v[122:125]
	v_mfma_f32_16x16x32_bf16 v[118:121], v[172:175], v[198:201], v[118:121]
	v_mfma_f32_16x16x32_bf16 v[118:121], v[180:183], v[202:205], v[118:121]
	v_mfma_f32_16x16x32_bf16 v[102:105], v[172:175], v[206:209], v[102:105]
	v_mfma_f32_16x16x32_bf16 v[102:105], v[180:183], v[210:213], v[102:105]
	v_mfma_f32_16x16x32_bf16 v[86:89], v[172:175], v[214:217], v[86:89]
	v_mfma_f32_16x16x32_bf16 v[86:89], v[180:183], v[218:221], v[86:89]
	v_mfma_f32_16x16x32_bf16 v[70:73], v[172:175], v[222:225], v[70:73]
	v_mfma_f32_16x16x32_bf16 v[70:73], v[180:183], v[226:229], v[70:73]
	v_mfma_f32_16x16x32_bf16 v[66:69], v[184:187], v[222:225], v[66:69]
	v_mfma_f32_16x16x32_bf16 v[66:69], v[188:191], v[226:229], v[66:69]
	v_mfma_f32_16x16x32_bf16 v[82:85], v[184:187], v[214:217], v[82:85]
	v_mfma_f32_16x16x32_bf16 v[82:85], v[188:191], v[218:221], v[82:85]
	v_mfma_f32_16x16x32_bf16 v[98:101], v[184:187], v[206:209], v[98:101]
	v_mfma_f32_16x16x32_bf16 v[98:101], v[188:191], v[210:213], v[98:101]
	v_mfma_f32_16x16x32_bf16 v[114:117], v[184:187], v[198:201], v[114:117]
	v_mfma_f32_16x16x32_bf16 v[114:117], v[188:191], v[202:205], v[114:117]
	s_barrier
	s_add_u32 s62, s76, 0x8000
	s_addc_u32 s63, s77, 0
	s_add_i32 s59, s59, s3
	s_mov_b32 m0, s59
	ds_read_b128 v[198:201], v164 offset:49152
	ds_read_b128 v[202:205], v164 offset:50176
	ds_read_b128 v[206:209], v164 offset:51200
	ds_read_b128 v[210:213], v164 offset:52224
	ds_read_b128 v[214:217], v164 offset:53248
	ds_read_b128 v[218:221], v164 offset:54272
	ds_read_b128 v[222:225], v164 offset:55296
	ds_read_b128 v[226:229], v164 offset:56320
	global_load_lds_dwordx4 v132, s[62:63]
	s_add_i32 m0, s59, 0x2000
	v_lshl_add_u64 v[158:159], s[62:63], 0, v[136:137]
	s_add_u32 s62, s76, 0xc000
	s_addc_u32 s63, s77, 0
	s_add_i32 s59, s64, s3
	global_load_lds_dwordx4 v[158:159], off
	s_mov_b32 m0, s59
	s_nop 0
	global_load_lds_dwordx4 v132, s[62:63]
	s_add_i32 m0, s59, 0x2000
	s_nop 0
	global_load_lds_dwordx4 v136, s[62:63]
	s_waitcnt vmcnt(6)
	s_waitcnt lgkmcnt(0)
	s_barrier
	v_mfma_f32_16x16x32_bf16 v[62:65], v[146:149], v[198:201], v[62:65]
	v_mfma_f32_16x16x32_bf16 v[62:65], v[150:153], v[202:205], v[62:65]
	v_mfma_f32_16x16x32_bf16 v[46:49], v[146:149], v[206:209], v[46:49]
	v_mfma_f32_16x16x32_bf16 v[46:49], v[150:153], v[210:213], v[46:49]
	v_mfma_f32_16x16x32_bf16 v[30:33], v[146:149], v[214:217], v[30:33]
	v_mfma_f32_16x16x32_bf16 v[30:33], v[150:153], v[218:221], v[30:33]
	v_mfma_f32_16x16x32_bf16 v[14:17], v[146:149], v[222:225], v[14:17]
	v_mfma_f32_16x16x32_bf16 v[14:17], v[150:153], v[226:229], v[14:17]
	v_mfma_f32_16x16x32_bf16 v[10:13], v[154:157], v[222:225], v[10:13]
	v_mfma_f32_16x16x32_bf16 v[10:13], v[168:171], v[226:229], v[10:13]
	v_mfma_f32_16x16x32_bf16 v[26:29], v[154:157], v[214:217], v[26:29]
	v_mfma_f32_16x16x32_bf16 v[26:29], v[168:171], v[218:221], v[26:29]
	v_mfma_f32_16x16x32_bf16 v[42:45], v[154:157], v[206:209], v[42:45]
	v_mfma_f32_16x16x32_bf16 v[42:45], v[168:171], v[210:213], v[42:45]
	v_mfma_f32_16x16x32_bf16 v[58:61], v[154:157], v[198:201], v[58:61]
	v_mfma_f32_16x16x32_bf16 v[58:61], v[168:171], v[202:205], v[58:61]
	v_mfma_f32_16x16x32_bf16 v[54:57], v[172:175], v[198:201], v[54:57]
	v_mfma_f32_16x16x32_bf16 v[54:57], v[180:183], v[202:205], v[54:57]
	v_mfma_f32_16x16x32_bf16 v[38:41], v[172:175], v[206:209], v[38:41]
	v_mfma_f32_16x16x32_bf16 v[38:41], v[180:183], v[210:213], v[38:41]
	v_mfma_f32_16x16x32_bf16 v[22:25], v[172:175], v[214:217], v[22:25]
	v_mfma_f32_16x16x32_bf16 v[22:25], v[180:183], v[218:221], v[22:25]
	v_mfma_f32_16x16x32_bf16 v[6:9], v[172:175], v[222:225], v[6:9]
	v_mfma_f32_16x16x32_bf16 v[6:9], v[180:183], v[226:229], v[6:9]
	v_mfma_f32_16x16x32_bf16 v[2:5], v[184:187], v[222:225], v[2:5]
	v_mfma_f32_16x16x32_bf16 v[2:5], v[188:191], v[226:229], v[2:5]
	v_mfma_f32_16x16x32_bf16 v[18:21], v[184:187], v[214:217], v[18:21]
	v_mfma_f32_16x16x32_bf16 v[18:21], v[188:191], v[218:221], v[18:21]
	v_mfma_f32_16x16x32_bf16 v[34:37], v[184:187], v[206:209], v[34:37]
	v_mfma_f32_16x16x32_bf16 v[34:37], v[188:191], v[210:213], v[34:37]
	v_mfma_f32_16x16x32_bf16 v[50:53], v[184:187], v[198:201], v[50:53]
	v_mfma_f32_16x16x32_bf16 v[50:53], v[188:191], v[202:205], v[50:53]
	s_barrier
	s_add_i32 s58, s58, 2
	s_add_u32 s72, s72, 0x10000
	s_addc_u32 s73, s73, 0
	s_add_u32 s33, s33, 0x10000
	s_addc_u32 s56, s56, 0
	s_cmp_gt_u32 s58, 61
	s_cbranch_scc0 .LBB0_290
	s_and_b64 vcc, exec, s[12:13]
	s_cbranch_vccz .LBB0_293
	s_barrier

; #define PG8_STAGE(bufoff, gbase, voff) do { _Pragma("unroll") for (int _i = 0; _i < 2; ++_i) \
;         __builtin_amdgcn_global_load_lds((const unsigned*)((const char*)(gbase) + (voff)[_i]), (PG8_LAS unsigned*)(lds + (bufoff) + ldsw + _i * 8192), 16, 0, 0); } while (0)
; #define PG8_LDA(dst, b, h) do { _Pragma("unroll") for (int m = 0; m < 4; ++m) _Pragma("unroll") for (int k = 0; k < 2; ++k) dst[m][k] = *(const PG8_LAS bf16x8*)(lds + PG8_SA(b, h) + aoff + m * 2048 + k * 1024); } while (0)
; #define PG8_LDB(dst, b, h) do { _Pragma("unroll") for (int n = 0; n < 2; ++n) _Pragma("unroll") for (int k = 0; k < 2; ++k) dst[n][k] = *(const PG8_LAS bf16x8*)(lds + PG8_SB(b, h) + boff + n * 2048 + k * 1024); } while (0)
; #define PG8_MMA(ai, bj, At, Bt) do { __builtin_amdgcn_s_setprio(1); _Pragma("unroll") for (int m = 0; m < 4; ++m) _Pragma("unroll") for (int n = 0; n < 2; ++n) _Pragma("unroll") for (int k = 0; k < 2; ++k) \
;         acc[ai][bj][m][n] = __builtin_amdgcn_mfma_f32_16x16x32_bf16(Bt[n][k], At[m][k], acc[ai][bj][m][n], 0, 0, 0); __builtin_amdgcn_s_setprio(0); } while (0)
; #define PG8_WAIT_V(n) asm volatile("s_waitcnt vmcnt(" #n ")" ::: "memory")
; #define PG8_WAIT_L(n) asm volatile("s_waitcnt lgkmcnt(" #n ")" ::: "memory")
; #define PG8_BAR __builtin_amdgcn_s_barrier()
; #define PG8_SCHED __builtin_amdgcn_sched_barrier(0)
; template <class Epi, class Sched, bool ALIGN_EPI = false, bool SP2 = false>
; __device__ __forceinline__ void gemm_phase(PG8_LAS unsigned char* lds, const Gemm g, const Sched& S, const Epi& E) {
;     ...
;             PG8_LDB(B0, 0, 0); PG8_LDB(B1, 0, 1); PG8_SCHED; PG8_LDA(At, 0, 0); PG8_STAGE(PG8_SA(1, 1), a1 + hstep, voffA);
;             PG8_WAIT_V(8); PG8_WAIT_L(0); PG8_BAR; PG8_MMA(0, 0, At, B0); PG8_MMA(0, 1, At, B1); PG8_BAR; PG8_SCHED;
;             PG8_LDA(At, 0, 1); PG8_STAGE(PG8_SB(0, 0), b2, voffB); PG8_STAGE(PG8_SB(0, 1), b2 + hstep, voffB); PG8_STAGE(PG8_SA(0, 0), a2, voffA);
.LBB0_682:
	ds_read_b128 v[166:169], v163
	ds_read_b128 v[170:173], v163 offset:1024
	ds_read_b128 v[174:177], v163 offset:2048
	ds_read_b128 v[180:183], v163 offset:3072
	ds_read_b128 v[184:187], v164
	ds_read_b128 v[188:191], v164 offset:1024
	ds_read_b128 v[198:201], v164 offset:2048
	ds_read_b128 v[202:205], v164 offset:3072
	v_lshl_add_u64 v[242:243], v[130:131], 0, s[44:45]
	s_add_i32 s83, s29, 0xc000
	v_lshl_add_u64 v[238:239], v[242:243], 0, s[10:11]
	s_mov_b32 m0, s83
	v_lshl_add_u64 v[244:245], v[132:133], 0, s[44:45]
	s_add_i32 s84, s29, 0xe000
	ds_read_b128 v[206:209], v165
	ds_read_b128 v[210:213], v165 offset:1024
	ds_read_b128 v[214:217], v165 offset:2048
	ds_read_b128 v[218:221], v165 offset:3072
	ds_read_b128 v[222:225], v165 offset:4096
	ds_read_b128 v[226:229], v165 offset:5120
	ds_read_b128 v[230:233], v165 offset:6144
	ds_read_b128 v[234:237], v165 offset:7168
	global_load_lds_dwordx4 v[238:239], off
	v_lshl_add_u64 v[238:239], v[244:245], 0, s[10:11]
	s_mov_b32 m0, s84
	s_nop 0
	global_load_lds_dwordx4 v[238:239], off
	s_waitcnt vmcnt(8)
	s_waitcnt lgkmcnt(0)
	s_barrier
	v_mfma_f32_16x16x32_bf16 v[14:17], v[166:169], v[206:209], v[14:17]
	v_mfma_f32_16x16x32_bf16 v[14:17], v[170:173], v[210:213], v[14:17]
	v_mfma_f32_16x16x32_bf16 v[38:41], v[166:169], v[214:217], v[38:41]
	v_mfma_f32_16x16x32_bf16 v[38:41], v[170:173], v[218:221], v[38:41]
	v_mfma_f32_16x16x32_bf16 v[70:73], v[166:169], v[222:225], v[70:73]
	v_mfma_f32_16x16x32_bf16 v[70:73], v[170:173], v[226:229], v[70:73]
	v_mfma_f32_16x16x32_bf16 v[94:97], v[166:169], v[230:233], v[94:97]
	v_mfma_f32_16x16x32_bf16 v[94:97], v[170:173], v[234:237], v[94:97]
	v_mfma_f32_16x16x32_bf16 v[90:93], v[174:177], v[230:233], v[90:93]
	v_mfma_f32_16x16x32_bf16 v[90:93], v[180:183], v[234:237], v[90:93]
	v_mfma_f32_16x16x32_bf16 v[66:69], v[174:177], v[222:225], v[66:69]
	v_mfma_f32_16x16x32_bf16 v[66:69], v[180:183], v[226:229], v[66:69]
	v_mfma_f32_16x16x32_bf16 v[34:37], v[174:177], v[214:217], v[34:37]
	v_mfma_f32_16x16x32_bf16 v[34:37], v[180:183], v[218:221], v[34:37]
	v_mfma_f32_16x16x32_bf16 v[10:13], v[174:177], v[206:209], v[10:13]
	v_mfma_f32_16x16x32_bf16 v[10:13], v[180:183], v[210:213], v[10:13]
	v_mfma_f32_16x16x32_bf16 v[30:33], v[184:187], v[206:209], v[30:33]
	v_mfma_f32_16x16x32_bf16 v[30:33], v[188:191], v[210:213], v[30:33]
	v_mfma_f32_16x16x32_bf16 v[54:57], v[184:187], v[214:217], v[54:57]
	v_mfma_f32_16x16x32_bf16 v[54:57], v[188:191], v[218:221], v[54:57]
	v_mfma_f32_16x16x32_bf16 v[86:89], v[184:187], v[222:225], v[86:89]
	v_mfma_f32_16x16x32_bf16 v[86:89], v[188:191], v[226:229], v[86:89]
	v_mfma_f32_16x16x32_bf16 v[110:113], v[184:187], v[230:233], v[110:113]
	v_mfma_f32_16x16x32_bf16 v[110:113], v[188:191], v[234:237], v[110:113]
	v_mfma_f32_16x16x32_bf16 v[106:109], v[198:201], v[230:233], v[106:109]
	v_mfma_f32_16x16x32_bf16 v[106:109], v[202:205], v[234:237], v[106:109]
	v_mfma_f32_16x16x32_bf16 v[82:85], v[198:201], v[222:225], v[82:85]
	v_mfma_f32_16x16x32_bf16 v[82:85], v[202:205], v[226:229], v[82:85]
	v_mfma_f32_16x16x32_bf16 v[50:53], v[198:201], v[214:217], v[50:53]
	v_mfma_f32_16x16x32_bf16 v[50:53], v[202:205], v[218:221], v[50:53]
	v_mfma_f32_16x16x32_bf16 v[26:29], v[198:201], v[206:209], v[26:29]
	v_mfma_f32_16x16x32_bf16 v[26:29], v[202:205], v[210:213], v[26:29]
	s_barrier
	v_lshl_add_u64 v[246:247], v[156:157], 0, s[44:45]
	s_add_i32 s85, s80, s28
	v_lshl_add_u64 v[238:239], v[246:247], 0, s[14:15]
	s_mov_b32 m0, s85
	v_lshl_add_u64 v[248:249], v[158:159], 0, s[44:45]
	s_add_i32 s86, s85, 0x2000
	ds_read_b128 v[206:209], v165 offset:16384
	ds_read_b128 v[210:213], v165 offset:17408
	ds_read_b128 v[214:217], v165 offset:18432
	ds_read_b128 v[218:221], v165 offset:19456
	ds_read_b128 v[222:225], v165 offset:20480
	ds_read_b128 v[226:229], v165 offset:21504
	ds_read_b128 v[230:233], v165 offset:22528
	ds_read_b128 v[234:237], v165 offset:23552
	global_load_lds_dwordx4 v[238:239], off
	v_lshl_add_u64 v[238:239], v[248:249], 0, s[14:15]
	s_mov_b32 m0, s86
	s_add_i32 s87, s81, s28
	global_load_lds_dwordx4 v[238:239], off
	v_lshl_add_u64 v[238:239], v[246:247], 0, s[16:17]
	s_mov_b32 m0, s87
	s_add_i32 s88, s87, 0x2000
	global_load_lds_dwordx4 v[238:239], off
	v_lshl_add_u64 v[238:239], v[248:249], 0, s[16:17]
	s_mov_b32 m0, s88
	s_nop 0
	global_load_lds_dwordx4 v[238:239], off
	v_lshl_add_u64 v[238:239], v[242:243], 0, s[14:15]
	s_mov_b32 m0, s29
	s_nop 0
	global_load_lds_dwordx4 v[238:239], off
	v_lshl_add_u64 v[238:239], v[244:245], 0, s[14:15]
	s_mov_b32 m0, s30
	s_nop 0
	global_load_lds_dwordx4 v[238:239], off
	s_waitcnt vmcnt(8)
	s_waitcnt lgkmcnt(0)
	s_barrier
; #define PG8_STAGE(bufoff, gbase, voff) do { _Pragma("unroll") for (int _i = 0; _i < 2; ++_i) \
;         __builtin_amdgcn_global_load_lds((const unsigned*)((const char*)(gbase) + (voff)[_i]), (PG8_LAS unsigned*)(lds + (bufoff) + ldsw + _i * 8192), 16, 0, 0); } while (0)
; #define PG8_LDA(dst, b, h) do { _Pragma("unroll") for (int m = 0; m < 4; ++m) _Pragma("unroll") for (int k = 0; k < 2; ++k) dst[m][k] = *(const PG8_LAS bf16x8*)(lds + PG8_SA(b, h) + aoff + m * 2048 + k * 1024); } while (0)
; #define PG8_LDB(dst, b, h) do { _Pragma("unroll") for (int n = 0; n < 2; ++n) _Pragma("unroll") for (int k = 0; k < 2; ++k) dst[n][k] = *(const PG8_LAS bf16x8*)(lds + PG8_SB(b, h) + boff + n * 2048 + k * 1024); } while (0)
; #define PG8_MMA(ai, bj, At, Bt) do { __builtin_amdgcn_s_setprio(1); _Pragma("unroll") for (int m = 0; m < 4; ++m) _Pragma("unroll") for (int n = 0; n < 2; ++n) _Pragma("unroll") for (int k = 0; k < 2; ++k) \
;         acc[ai][bj][m][n] = __builtin_amdgcn_mfma_f32_16x16x32_bf16(Bt[n][k], At[m][k], acc[ai][bj][m][n], 0, 0, 0); __builtin_amdgcn_s_setprio(0); } while (0)
; #define PG8_WAIT_V(n) asm volatile("s_waitcnt vmcnt(" #n ")" ::: "memory")
; #define PG8_WAIT_L(n) asm volatile("s_waitcnt lgkmcnt(" #n ")" ::: "memory")
; #define PG8_BAR __builtin_amdgcn_s_barrier()
; #define PG8_SCHED __builtin_amdgcn_sched_barrier(0)
; template <class Epi, class Sched, bool ALIGN_EPI = false, bool SP2 = false>
; __device__ __forceinline__ void gemm_phase(PG8_LAS unsigned char* lds, const Gemm g, const Sched& S, const Epi& E) {
;     ...
;             PG8_WAIT_V(8); PG8_WAIT_L(0); PG8_BAR; PG8_MMA(1, 0, At, B0); PG8_MMA(1, 1, At, B1); PG8_BAR; PG8_SCHED;
;             PG8_LDB(B0, 1, 0); PG8_LDB(B1, 1, 1); PG8_SCHED; PG8_LDA(At, 1, 0); PG8_STAGE(PG8_SA(0, 1), a2 + hstep, voffA);
;             PG8_WAIT_V(8); PG8_WAIT_L(0); PG8_BAR; PG8_MMA(0, 0, At, B0); PG8_MMA(0, 1, At, B1); PG8_BAR; PG8_SCHED;
	v_mfma_f32_16x16x32_bf16 v[126:129], v[166:169], v[206:209], v[126:129]
	v_mfma_f32_16x16x32_bf16 v[126:129], v[170:173], v[210:213], v[126:129]
	v_mfma_f32_16x16x32_bf16 v[102:105], v[166:169], v[214:217], v[102:105]
	v_mfma_f32_16x16x32_bf16 v[102:105], v[170:173], v[218:221], v[102:105]
	v_mfma_f32_16x16x32_bf16 v[62:65], v[166:169], v[222:225], v[62:65]
	v_mfma_f32_16x16x32_bf16 v[62:65], v[170:173], v[226:229], v[62:65]
	v_mfma_f32_16x16x32_bf16 v[22:25], v[166:169], v[230:233], v[22:25]
	v_mfma_f32_16x16x32_bf16 v[22:25], v[170:173], v[234:237], v[22:25]
	v_mfma_f32_16x16x32_bf16 v[18:21], v[174:177], v[230:233], v[18:21]
	v_mfma_f32_16x16x32_bf16 v[18:21], v[180:183], v[234:237], v[18:21]
	v_mfma_f32_16x16x32_bf16 v[58:61], v[174:177], v[222:225], v[58:61]
	v_mfma_f32_16x16x32_bf16 v[58:61], v[180:183], v[226:229], v[58:61]
	v_mfma_f32_16x16x32_bf16 v[98:101], v[174:177], v[214:217], v[98:101]
	v_mfma_f32_16x16x32_bf16 v[98:101], v[180:183], v[218:221], v[98:101]
	v_mfma_f32_16x16x32_bf16 v[122:125], v[174:177], v[206:209], v[122:125]
	v_mfma_f32_16x16x32_bf16 v[122:125], v[180:183], v[210:213], v[122:125]
	v_mfma_f32_16x16x32_bf16 v[118:121], v[184:187], v[206:209], v[118:121]
	v_mfma_f32_16x16x32_bf16 v[118:121], v[188:191], v[210:213], v[118:121]
	v_mfma_f32_16x16x32_bf16 v[78:81], v[184:187], v[214:217], v[78:81]
	v_mfma_f32_16x16x32_bf16 v[78:81], v[188:191], v[218:221], v[78:81]
	v_mfma_f32_16x16x32_bf16 v[46:49], v[184:187], v[222:225], v[46:49]
	v_mfma_f32_16x16x32_bf16 v[46:49], v[188:191], v[226:229], v[46:49]
	v_mfma_f32_16x16x32_bf16 v[6:9], v[184:187], v[230:233], v[6:9]
	v_mfma_f32_16x16x32_bf16 v[6:9], v[188:191], v[234:237], v[6:9]
	v_mfma_f32_16x16x32_bf16 v[2:5], v[198:201], v[230:233], v[2:5]
	v_mfma_f32_16x16x32_bf16 v[2:5], v[202:205], v[234:237], v[2:5]
	v_mfma_f32_16x16x32_bf16 v[42:45], v[198:201], v[222:225], v[42:45]
	v_mfma_f32_16x16x32_bf16 v[42:45], v[202:205], v[226:229], v[42:45]
	v_mfma_f32_16x16x32_bf16 v[74:77], v[198:201], v[214:217], v[74:77]
	v_mfma_f32_16x16x32_bf16 v[74:77], v[202:205], v[218:221], v[74:77]
	v_mfma_f32_16x16x32_bf16 v[114:117], v[198:201], v[206:209], v[114:117]
	v_mfma_f32_16x16x32_bf16 v[114:117], v[202:205], v[210:213], v[114:117]
	s_barrier
	s_add_i32 s89, 0, 0x18000
	s_add_i32 s91, 0, 0x1c000
	v_add_u32_e32 v142, s89, v161
	v_add_u32_e32 v167, s91, v161
	ds_read_b128 v[168:171], v142
	ds_read_b128 v[172:175], v142 offset:1024
	ds_read_b128 v[180:183], v142 offset:2048
	ds_read_b128 v[184:187], v142 offset:3072
	ds_read_b128 v[188:191], v167
	ds_read_b128 v[198:201], v167 offset:1024
	ds_read_b128 v[202:205], v167 offset:2048
	ds_read_b128 v[206:209], v167 offset:3072
	s_mov_b32 m0, s31
	v_lshl_add_u64 v[176:177], v[242:243], 0, s[16:17]
	ds_read_b128 v[210:213], v165 offset:32768
	ds_read_b128 v[214:217], v165 offset:33792
	ds_read_b128 v[218:221], v165 offset:34816
	ds_read_b128 v[222:225], v165 offset:35840
	ds_read_b128 v[226:229], v165 offset:36864
	ds_read_b128 v[230:233], v165 offset:37888
	ds_read_b128 v[234:237], v165 offset:38912
	ds_read_b128 v[238:241], v165 offset:39936
	global_load_lds_dwordx4 v[176:177], off
	v_lshl_add_u64 v[176:177], v[244:245], 0, s[16:17]
	s_mov_b32 m0, s35
	s_nop 0
	global_load_lds_dwordx4 v[176:177], off
	s_waitcnt vmcnt(8)
	s_waitcnt lgkmcnt(0)
	s_barrier
	v_mfma_f32_16x16x32_bf16 v[14:17], v[168:171], v[210:213], v[14:17]
	v_mfma_f32_16x16x32_bf16 v[14:17], v[172:175], v[214:217], v[14:17]
	v_mfma_f32_16x16x32_bf16 v[38:41], v[168:171], v[218:221], v[38:41]
	v_mfma_f32_16x16x32_bf16 v[38:41], v[172:175], v[222:225], v[38:41]
	v_mfma_f32_16x16x32_bf16 v[70:73], v[168:171], v[226:229], v[70:73]
	v_mfma_f32_16x16x32_bf16 v[70:73], v[172:175], v[230:233], v[70:73]
	v_mfma_f32_16x16x32_bf16 v[94:97], v[168:171], v[234:237], v[94:97]
	v_mfma_f32_16x16x32_bf16 v[94:97], v[172:175], v[238:241], v[94:97]
	v_mfma_f32_16x16x32_bf16 v[90:93], v[180:183], v[234:237], v[90:93]
	v_mfma_f32_16x16x32_bf16 v[90:93], v[184:187], v[238:241], v[90:93]
	v_mfma_f32_16x16x32_bf16 v[66:69], v[180:183], v[226:229], v[66:69]
	v_mfma_f32_16x16x32_bf16 v[66:69], v[184:187], v[230:233], v[66:69]
	v_mfma_f32_16x16x32_bf16 v[34:37], v[180:183], v[218:221], v[34:37]
	v_mfma_f32_16x16x32_bf16 v[34:37], v[184:187], v[222:225], v[34:37]
	v_mfma_f32_16x16x32_bf16 v[10:13], v[180:183], v[210:213], v[10:13]
	v_mfma_f32_16x16x32_bf16 v[10:13], v[184:187], v[214:217], v[10:13]
	v_mfma_f32_16x16x32_bf16 v[30:33], v[188:191], v[210:213], v[30:33]
	v_mfma_f32_16x16x32_bf16 v[30:33], v[198:201], v[214:217], v[30:33]
	v_mfma_f32_16x16x32_bf16 v[54:57], v[188:191], v[218:221], v[54:57]
	v_mfma_f32_16x16x32_bf16 v[54:57], v[198:201], v[222:225], v[54:57]
	v_mfma_f32_16x16x32_bf16 v[86:89], v[188:191], v[226:229], v[86:89]
	v_mfma_f32_16x16x32_bf16 v[86:89], v[198:201], v[230:233], v[86:89]
	v_mfma_f32_16x16x32_bf16 v[110:113], v[188:191], v[234:237], v[110:113]
	v_mfma_f32_16x16x32_bf16 v[110:113], v[198:201], v[238:241], v[110:113]
	v_mfma_f32_16x16x32_bf16 v[106:109], v[202:205], v[234:237], v[106:109]
	v_mfma_f32_16x16x32_bf16 v[106:109], v[206:209], v[238:241], v[106:109]
	v_mfma_f32_16x16x32_bf16 v[82:85], v[202:205], v[226:229], v[82:85]
	v_mfma_f32_16x16x32_bf16 v[82:85], v[206:209], v[230:233], v[82:85]
	v_mfma_f32_16x16x32_bf16 v[50:53], v[202:205], v[218:221], v[50:53]
	v_mfma_f32_16x16x32_bf16 v[50:53], v[206:209], v[222:225], v[50:53]
	v_mfma_f32_16x16x32_bf16 v[26:29], v[202:205], v[210:213], v[26:29]
	v_mfma_f32_16x16x32_bf16 v[26:29], v[206:209], v[214:217], v[26:29]
	s_barrier
; __device__ __forceinline__ float bflo(unsigned w) { return __uint_as_float(w << 16); }
; __device__ __forceinline__ float bfhi(unsigned w) { return __uint_as_float(w & 0xffff0000u); }
; #define PG8_STAGE(bufoff, gbase, voff) do { _Pragma("unroll") for (int _i = 0; _i < 2; ++_i) \
;         __builtin_amdgcn_global_load_lds((const unsigned*)((const char*)(gbase) + (voff)[_i]), (PG8_LAS unsigned*)(lds + (bufoff) + ldsw + _i * 8192), 16, 0, 0); } while (0)
; #define PG8_LDA(dst, b, h) do { _Pragma("unroll") for (int m = 0; m < 4; ++m) _Pragma("unroll") for (int k = 0; k < 2; ++k) dst[m][k] = *(const PG8_LAS bf16x8*)(lds + PG8_SA(b, h) + aoff + m * 2048 + k * 1024); } while (0)
; #define PG8_WAIT_V(n) asm volatile("s_waitcnt vmcnt(" #n ")" ::: "memory")
; #define PG8_WAIT_L(n) asm volatile("s_waitcnt lgkmcnt(" #n ")" ::: "memory")
; #define PG8_BAR __builtin_amdgcn_s_barrier()
; #define PG8_SCHED __builtin_amdgcn_sched_barrier(0)
;     __device__ __forceinline__ void mid(f32x4 (&acc)[2][2][4][2], const Unit& u, int wr, int wc, int fr, int fq) const {
;     ...
;             for (int m = 0; m < 4; ++m) { const bf16_t* pr = P + (size_t)(row0 + ai * HALF + m * 16) * NP + col0;
; #pragma unroll
;                 for (int bj = 0; bj < 2; ++bj) { const u32x4 a = *(const u32x4*)(pr + PC_GA + bj * HALF), b = *(const u32x4*)(pr + PC_GB + bj * HALF);
;                     const f32x4 b0 = {bflo(b.x), bfhi(b.x), bflo(b.y), bfhi(b.y)}, b1 = {bflo(b.z), bfhi(b.z), bflo(b.w), bfhi(b.w)};
;                     const f32x4 a0 = {bflo(a.x), bfhi(a.x), bflo(a.y), bfhi(a.y)}, a1 = {bflo(a.z), bfhi(a.z), bflo(a.w), bfhi(a.w)};
;                     f32x4 r0, r1;
; #pragma unroll
;                     for (int j = 0; j < 4; ++j) { r0[j] = a0[j] * __builtin_amdgcn_rcpf(fmaxf(b0[j], 1e-30f)); r1[j] = a1[j] * __builtin_amdgcn_rcpf(fmaxf(b1[j], 1e-30f)); }
;                     acc[ai][bj][m][0] *= r0; acc[ai][bj][m][1] *= r1; }
; template <class Epi, class Sched, bool ALIGN_EPI = false, bool SP2 = false>
; __device__ __forceinline__ void gemm_phase(PG8_LAS unsigned char* lds, const Gemm g, const Sched& S, const Epi& E) {
;     ...
;             PG8_LDA(At, 1, 1); PG8_STAGE(PG8_SB(1, 0), b3, voffB); PG8_STAGE(PG8_SB(1, 1), b3 + hstep, voffB); PG8_STAGE(PG8_SA(1, 0), a3, voffA);
;             PG8_WAIT_V(8); PG8_WAIT_L(0); PG8_BAR; PG8_MMA(1, 0, At, B0); PG8_MMA(1, 1, At, B1); PG8_BAR; PG8_SCHED;
	s_add_i32 s89, s89, s28
	v_lshl_add_u64 v[176:177], v[246:247], 0, s[22:23]
	s_mov_b32 m0, s89
	s_add_i32 s90, s89, 0x2000
	ds_read_b128 v[210:213], v165 offset:49152
	ds_read_b128 v[214:217], v165 offset:50176
	ds_read_b128 v[218:221], v165 offset:51200
	ds_read_b128 v[222:225], v165 offset:52224
	ds_read_b128 v[226:229], v165 offset:53248
	ds_read_b128 v[230:233], v165 offset:54272
	ds_read_b128 v[234:237], v165 offset:55296
	ds_read_b128 v[238:241], v165 offset:56320
	global_load_lds_dwordx4 v[176:177], off
	v_lshl_add_u64 v[176:177], v[248:249], 0, s[22:23]
	s_mov_b32 m0, s90
	s_add_i32 s91, s91, s28
	global_load_lds_dwordx4 v[176:177], off
	v_lshl_add_u64 v[176:177], v[246:247], 0, s[36:37]
	s_mov_b32 m0, s91
	s_add_i32 s92, s91, 0x2000
	global_load_lds_dwordx4 v[176:177], off
	v_lshl_add_u64 v[176:177], v[248:249], 0, s[36:37]
	s_mov_b32 m0, s92
	s_nop 0
	global_load_lds_dwordx4 v[176:177], off
	v_lshl_add_u64 v[176:177], v[242:243], 0, s[22:23]
	s_mov_b32 m0, s75
	s_nop 0
	global_load_lds_dwordx4 v[176:177], off
	v_lshl_add_u64 v[176:177], v[244:245], 0, s[22:23]
	s_mov_b32 m0, s76
	s_nop 0
	global_load_lds_dwordx4 v[176:177], off
	s_waitcnt vmcnt(8)
	s_waitcnt lgkmcnt(0)
	s_barrier
	v_mfma_f32_16x16x32_bf16 v[126:129], v[168:171], v[210:213], v[126:129]
	v_mfma_f32_16x16x32_bf16 v[126:129], v[172:175], v[214:217], v[126:129]
	v_mfma_f32_16x16x32_bf16 v[102:105], v[168:171], v[218:221], v[102:105]
	v_mfma_f32_16x16x32_bf16 v[102:105], v[172:175], v[222:225], v[102:105]
	v_mfma_f32_16x16x32_bf16 v[62:65], v[168:171], v[226:229], v[62:65]
	v_mfma_f32_16x16x32_bf16 v[62:65], v[172:175], v[230:233], v[62:65]
	v_mfma_f32_16x16x32_bf16 v[22:25], v[168:171], v[234:237], v[22:25]
	v_mfma_f32_16x16x32_bf16 v[22:25], v[172:175], v[238:241], v[22:25]
	v_mfma_f32_16x16x32_bf16 v[18:21], v[180:183], v[234:237], v[18:21]
	v_mfma_f32_16x16x32_bf16 v[18:21], v[184:187], v[238:241], v[18:21]
	v_mfma_f32_16x16x32_bf16 v[58:61], v[180:183], v[226:229], v[58:61]
	v_mfma_f32_16x16x32_bf16 v[58:61], v[184:187], v[230:233], v[58:61]
	v_mfma_f32_16x16x32_bf16 v[98:101], v[180:183], v[218:221], v[98:101]
	v_mfma_f32_16x16x32_bf16 v[98:101], v[184:187], v[222:225], v[98:101]
	v_mfma_f32_16x16x32_bf16 v[122:125], v[180:183], v[210:213], v[122:125]
	v_mfma_f32_16x16x32_bf16 v[122:125], v[184:187], v[214:217], v[122:125]
	v_mfma_f32_16x16x32_bf16 v[118:121], v[188:191], v[210:213], v[118:121]
	v_mfma_f32_16x16x32_bf16 v[118:121], v[198:201], v[214:217], v[118:121]
	v_mfma_f32_16x16x32_bf16 v[78:81], v[188:191], v[218:221], v[78:81]
	v_mfma_f32_16x16x32_bf16 v[78:81], v[198:201], v[222:225], v[78:81]
	v_mfma_f32_16x16x32_bf16 v[46:49], v[188:191], v[226:229], v[46:49]
	v_mfma_f32_16x16x32_bf16 v[46:49], v[198:201], v[230:233], v[46:49]
	v_mfma_f32_16x16x32_bf16 v[6:9], v[188:191], v[234:237], v[6:9]
	v_mfma_f32_16x16x32_bf16 v[6:9], v[198:201], v[238:241], v[6:9]
	v_mfma_f32_16x16x32_bf16 v[2:5], v[202:205], v[234:237], v[2:5]
	v_mfma_f32_16x16x32_bf16 v[2:5], v[206:209], v[238:241], v[2:5]
	v_mfma_f32_16x16x32_bf16 v[42:45], v[202:205], v[226:229], v[42:45]
	v_mfma_f32_16x16x32_bf16 v[42:45], v[206:209], v[230:233], v[42:45]
	v_mfma_f32_16x16x32_bf16 v[74:77], v[202:205], v[218:221], v[74:77]
	v_mfma_f32_16x16x32_bf16 v[74:77], v[206:209], v[222:225], v[74:77]
	v_mfma_f32_16x16x32_bf16 v[114:117], v[202:205], v[210:213], v[114:117]
	v_mfma_f32_16x16x32_bf16 v[114:117], v[206:209], v[214:217], v[114:117]
	s_barrier
	s_add_i32 s27, s27, 2
	s_add_u32 s44, s44, 0x10000
	s_addc_u32 s45, s45, 0
	s_cmp_lt_u32 s27, 30
	s_cbranch_scc1 .LBB0_682
	s_ashr_i32 s41, s40, 31
	s_lshl_b64 s[44:45], s[40:41], 21
	s_add_u32 s44, s18, s44
	s_addc_u32 s45, s19, s45
	s_ashr_i32 s39, s38, 31
	s_lshl_b64 s[46:47], s[38:39], 21
	v_readlane_b32 s58, v255, 15
	v_readlane_b32 s59, v255, 16
	s_add_u32 s46, s58, s46
	s_addc_u32 s47, s59, s47
	s_lshl_b32 s39, s26, 8
	v_or_b32_e32 v130, s39, v162
	v_ashrrev_i32_e32 v131, 31, v130
	v_lshl_add_u32 v166, s70, 8, v160
	v_lshl_add_u64 v[156:157], v[130:131], 1, s[24:25]
	v_mov_b32_e32 v168, v166
	s_and_b64 s[26:27], s[0:1], exec
	v_mad_i64_i32 v[158:159], s[58:59], v168, s78, v[156:157]
	v_add_co_u32_e32 v174, vcc, s61, v158
	s_cselect_b32 s41, s45, s51
	s_nop 0
	v_addc_co_u32_e32 v175, vcc, 0, v159, vcc
	v_add_co_u32_e32 v158, vcc, s77, v158
	global_load_dwordx4 v[130:133], v[174:175], off
	s_nop 0
	v_addc_co_u32_e32 v159, vcc, 0, v159, vcc
	global_load_dwordx4 v[170:173], v[158:159], off
	s_cselect_b32 s93, s44, s50
	s_cselect_b32 s27, s47, s49
	s_cselect_b32 s97, s46, s48
	s_add_u32 s50, s50, 0x10c000
	s_addc_u32 s51, s51, 0
	s_add_u32 s26, s48, 0x110000
	s_addc_u32 s33, s49, 0
	s_mov_b32 s56, 30
	s_waitcnt vmcnt(0)
	v_and_b32_e32 v177, 0xffff0000, v130
	v_lshlrev_b32_e32 v169, 16, v170
	v_max_f32_e32 v169, v169, v169
	v_lshlrev_b32_e32 v178, 16, v171
	v_and_b32_e32 v179, 0xffff0000, v171
	v_lshlrev_b32_e32 v171, 16, v172
	v_max_f32_e32 v169, 0xda24260, v169
	v_and_b32_e32 v176, 0xffff0000, v170
	v_rcp_f32_e32 v170, v169
	v_max_f32_e32 v169, v171, v171
	v_max_f32_e32 v169, 0xda24260, v169
	v_and_b32_e32 v180, 0xffff0000, v172
	v_rcp_f32_e32 v172, v169
	v_max_f32_e32 v169, v176, v176
	v_max_f32_e32 v169, 0xda24260, v169
	v_lshlrev_b32_e32 v176, 16, v130
	v_max_f32_e32 v130, v180, v180
	v_rcp_f32_e32 v171, v169
	v_max_f32_e32 v130, 0xda24260, v130
	v_lshlrev_b32_e32 v181, 16, v173
	v_and_b32_e32 v182, 0xffff0000, v173
	v_rcp_f32_e32 v173, v130
	v_max_f32_e32 v130, v178, v178
	v_pk_mul_f32 v[170:171], v[170:171], v[176:177]
	v_lshlrev_b32_e32 v176, 16, v132
	v_and_b32_e32 v177, 0xffff0000, v132
	v_max_f32_e32 v130, 0xda24260, v130
	v_pk_mul_f32 v[172:173], v[172:173], v[176:177]
	v_rcp_f32_e32 v176, v130
	v_max_f32_e32 v130, v181, v181
	v_lshlrev_b32_e32 v180, 16, v131
	v_and_b32_e32 v181, 0xffff0000, v131
	v_max_f32_e32 v131, v182, v182
	v_max_f32_e32 v130, 0xda24260, v130
	v_max_f32_e32 v131, 0xda24260, v131
	v_rcp_f32_e32 v130, v130
	v_rcp_f32_e32 v131, v131
	v_max_f32_e32 v132, v179, v179
	v_max_f32_e32 v132, 0xda24260, v132
	v_rcp_f32_e32 v177, v132
	v_lshlrev_b32_e32 v132, 16, v133
	v_and_b32_e32 v133, 0xffff0000, v133
	v_pk_mul_f32 v[130:131], v[130:131], v[132:133]
	v_pk_mul_f32 v[14:15], v[14:15], v[170:171]
	v_pk_mul_f32 v[12:13], v[12:13], v[130:131]
	v_pk_mul_f32 v[10:11], v[10:11], v[172:173]
	global_load_dwordx4 v[130:133], v[174:175], off offset:256
	global_load_dwordx4 v[170:173], v[158:159], off offset:256
	v_pk_mul_f32 v[176:177], v[176:177], v[180:181]
	s_waitcnt vmcnt(0)
; __device__ __forceinline__ float bflo(unsigned w) { return __uint_as_float(w << 16); }
; __device__ __forceinline__ float bfhi(unsigned w) { return __uint_as_float(w & 0xffff0000u); }
;     __device__ __forceinline__ void mid(f32x4 (&acc)[2][2][4][2], const Unit& u, int wr, int wc, int fr, int fq) const {
;     ...
;             for (int m = 0; m < 4; ++m) { const bf16_t* pr = P + (size_t)(row0 + ai * HALF + m * 16) * NP + col0;
; #pragma unroll
;                 for (int bj = 0; bj < 2; ++bj) { const u32x4 a = *(const u32x4*)(pr + PC_GA + bj * HALF), b = *(const u32x4*)(pr + PC_GB + bj * HALF);
;                     const f32x4 b0 = {bflo(b.x), bfhi(b.x), bflo(b.y), bfhi(b.y)}, b1 = {bflo(b.z), bfhi(b.z), bflo(b.w), bfhi(b.w)};
;                     const f32x4 a0 = {bflo(a.x), bfhi(a.x), bflo(a.y), bfhi(a.y)}, a1 = {bflo(a.z), bfhi(a.z), bflo(a.w), bfhi(a.w)};
;                     f32x4 r0, r1;
; #pragma unroll
;                     for (int j = 0; j < 4; ++j) { r0[j] = a0[j] * __builtin_amdgcn_rcpf(fmaxf(b0[j], 1e-30f)); r1[j] = a1[j] * __builtin_amdgcn_rcpf(fmaxf(b1[j], 1e-30f)); }
;                     acc[ai][bj][m][0] *= r0; acc[ai][bj][m][1] *= r1; }
	v_lshlrev_b32_e32 v158, 16, v170
	v_and_b32_e32 v159, 0xffff0000, v170
	v_lshlrev_b32_e32 v169, 16, v171
	v_and_b32_e32 v174, 0xffff0000, v171
	v_lshlrev_b32_e32 v170, 16, v172
	v_and_b32_e32 v171, 0xffff0000, v172
	v_max_f32_e32 v158, v158, v158
	v_max_f32_e32 v159, v159, v159
	v_pk_mul_f32 v[16:17], v[16:17], v[176:177]
	v_lshlrev_b32_e32 v175, 16, v173
	v_and_b32_e32 v176, 0xffff0000, v173
	v_max_f32_e32 v158, 0xda24260, v158
	v_max_f32_e32 v170, v170, v170
	v_max_f32_e32 v159, 0xda24260, v159
	v_lshlrev_b32_e32 v172, 16, v130
	v_and_b32_e32 v173, 0xffff0000, v130
	v_max_f32_e32 v130, v171, v171
	v_rcp_f32_e32 v158, v158
	v_max_f32_e32 v170, 0xda24260, v170
	v_rcp_f32_e32 v159, v159
	v_max_f32_e32 v130, 0xda24260, v130
	v_rcp_f32_e32 v170, v170
	v_rcp_f32_e32 v171, v130
	v_max_f32_e32 v130, v169, v169
	v_pk_mul_f32 v[158:159], v[158:159], v[172:173]
	v_lshlrev_b32_e32 v172, 16, v132
	v_and_b32_e32 v173, 0xffff0000, v132
	v_max_f32_e32 v130, 0xda24260, v130
	v_pk_mul_f32 v[170:171], v[170:171], v[172:173]
	v_rcp_f32_e32 v172, v130
	v_max_f32_e32 v130, v175, v175
	v_max_f32_e32 v132, v174, v174
	v_lshlrev_b32_e32 v174, 16, v131
	v_and_b32_e32 v175, 0xffff0000, v131
	v_max_f32_e32 v131, v176, v176
	v_max_f32_e32 v130, 0xda24260, v130
	v_max_f32_e32 v131, 0xda24260, v131
	v_rcp_f32_e32 v130, v130
	v_rcp_f32_e32 v131, v131
	v_max_f32_e32 v132, 0xda24260, v132
	v_rcp_f32_e32 v173, v132
	v_lshlrev_b32_e32 v132, 16, v133
	v_and_b32_e32 v133, 0xffff0000, v133
	v_pk_mul_f32 v[130:131], v[130:131], v[132:133]
	v_pk_mul_f32 v[30:31], v[30:31], v[158:159]
	v_pk_mul_f32 v[28:29], v[28:29], v[130:131]
	v_add_u32_e32 v130, 16, v168
	v_mad_i64_i32 v[158:159], s[58:59], v130, s78, v[156:157]
	v_pk_mul_f32 v[172:173], v[172:173], v[174:175]
	v_add_co_u32_e32 v174, vcc, s61, v158
	v_pk_mul_f32 v[32:33], v[32:33], v[172:173]
	s_nop 0
	v_addc_co_u32_e32 v175, vcc, 0, v159, vcc
	v_add_co_u32_e32 v158, vcc, s77, v158
	v_pk_mul_f32 v[26:27], v[26:27], v[170:171]
	s_nop 0
	v_addc_co_u32_e32 v159, vcc, 0, v159, vcc
	global_load_dwordx4 v[130:133], v[174:175], off
	global_load_dwordx4 v[170:173], v[158:159], off
	s_waitcnt vmcnt(1)
	v_and_b32_e32 v177, 0xffff0000, v130
	s_waitcnt vmcnt(0)
	v_lshlrev_b32_e32 v169, 16, v170
	v_max_f32_e32 v169, v169, v169
	v_lshlrev_b32_e32 v178, 16, v171
	v_and_b32_e32 v179, 0xffff0000, v171
	v_lshlrev_b32_e32 v171, 16, v172
	v_max_f32_e32 v169, 0xda24260, v169
	v_and_b32_e32 v176, 0xffff0000, v170
	v_rcp_f32_e32 v170, v169
	v_max_f32_e32 v169, v171, v171
	v_max_f32_e32 v169, 0xda24260, v169
	v_and_b32_e32 v180, 0xffff0000, v172
	v_rcp_f32_e32 v172, v169
	v_max_f32_e32 v169, v176, v176
	v_max_f32_e32 v169, 0xda24260, v169
	v_lshlrev_b32_e32 v176, 16, v130
	v_max_f32_e32 v130, v180, v180
	v_rcp_f32_e32 v171, v169
	v_max_f32_e32 v130, 0xda24260, v130
	v_lshlrev_b32_e32 v181, 16, v173
	v_and_b32_e32 v182, 0xffff0000, v173
	v_rcp_f32_e32 v173, v130
	v_max_f32_e32 v130, v178, v178
	v_pk_mul_f32 v[170:171], v[170:171], v[176:177]
	v_lshlrev_b32_e32 v176, 16, v132
	v_and_b32_e32 v177, 0xffff0000, v132
	v_max_f32_e32 v130, 0xda24260, v130
	v_pk_mul_f32 v[172:173], v[172:173], v[176:177]
	v_rcp_f32_e32 v176, v130
	v_max_f32_e32 v130, v181, v181
	v_lshlrev_b32_e32 v180, 16, v131
	v_and_b32_e32 v181, 0xffff0000, v131
	v_max_f32_e32 v131, v182, v182
	v_max_f32_e32 v130, 0xda24260, v130
	v_max_f32_e32 v131, 0xda24260, v131
	v_rcp_f32_e32 v130, v130
	v_rcp_f32_e32 v131, v131
	v_max_f32_e32 v132, v179, v179
	v_max_f32_e32 v132, 0xda24260, v132
	v_rcp_f32_e32 v177, v132
	v_lshlrev_b32_e32 v132, 16, v133
	v_and_b32_e32 v133, 0xffff0000, v133
	v_pk_mul_f32 v[130:131], v[130:131], v[132:133]
	v_pk_mul_f32 v[38:39], v[38:39], v[170:171]
	v_pk_mul_f32 v[36:37], v[36:37], v[130:131]
	v_pk_mul_f32 v[34:35], v[34:35], v[172:173]
	global_load_dwordx4 v[130:133], v[174:175], off offset:256
	global_load_dwordx4 v[170:173], v[158:159], off offset:256
	v_pk_mul_f32 v[176:177], v[176:177], v[180:181]
	s_waitcnt vmcnt(0)
	v_lshlrev_b32_e32 v158, 16, v170
	v_and_b32_e32 v159, 0xffff0000, v170
	v_lshlrev_b32_e32 v169, 16, v171
	v_and_b32_e32 v174, 0xffff0000, v171
	v_lshlrev_b32_e32 v170, 16, v172
	v_and_b32_e32 v171, 0xffff0000, v172
	v_max_f32_e32 v158, v158, v158
	v_max_f32_e32 v159, v159, v159
	v_pk_mul_f32 v[40:41], v[40:41], v[176:177]
	v_lshlrev_b32_e32 v175, 16, v173
	v_and_b32_e32 v176, 0xffff0000, v173
	v_max_f32_e32 v158, 0xda24260, v158
	v_max_f32_e32 v170, v170, v170
	v_max_f32_e32 v159, 0xda24260, v159
	v_lshlrev_b32_e32 v172, 16, v130
	v_and_b32_e32 v173, 0xffff0000, v130
	v_max_f32_e32 v130, v171, v171
	v_rcp_f32_e32 v158, v158
	v_max_f32_e32 v170, 0xda24260, v170
	v_rcp_f32_e32 v159, v159
	v_max_f32_e32 v130, 0xda24260, v130
	v_rcp_f32_e32 v170, v170
	v_rcp_f32_e32 v171, v130
	v_max_f32_e32 v130, v169, v169
	v_pk_mul_f32 v[158:159], v[158:159], v[172:173]
	v_lshlrev_b32_e32 v172, 16, v132
	v_and_b32_e32 v173, 0xffff0000, v132
	v_max_f32_e32 v130, 0xda24260, v130
	v_pk_mul_f32 v[170:171], v[170:171], v[172:173]
	v_rcp_f32_e32 v172, v130
	v_max_f32_e32 v130, v175, v175
	v_max_f32_e32 v132, v174, v174
	v_lshlrev_b32_e32 v174, 16, v131
	v_and_b32_e32 v175, 0xffff0000, v131
	v_max_f32_e32 v131, v176, v176
	v_max_f32_e32 v130, 0xda24260, v130
	v_max_f32_e32 v131, 0xda24260, v131
	v_rcp_f32_e32 v130, v130
	v_rcp_f32_e32 v131, v131
	v_max_f32_e32 v132, 0xda24260, v132
	v_rcp_f32_e32 v173, v132
	v_lshlrev_b32_e32 v132, 16, v133
	v_and_b32_e32 v133, 0xffff0000, v133
	v_pk_mul_f32 v[130:131], v[130:131], v[132:133]
	v_pk_mul_f32 v[54:55], v[54:55], v[158:159]
	v_pk_mul_f32 v[52:53], v[52:53], v[130:131]
	v_add_u32_e32 v130, 32, v168
	v_mad_i64_i32 v[158:159], s[58:59], v130, s78, v[156:157]
	v_pk_mul_f32 v[172:173], v[172:173], v[174:175]
	v_add_co_u32_e32 v174, vcc, s61, v158
	v_pk_mul_f32 v[56:57], v[56:57], v[172:173]
	s_nop 0
	v_addc_co_u32_e32 v175, vcc, 0, v159, vcc
	v_add_co_u32_e32 v158, vcc, s77, v158
	v_pk_mul_f32 v[50:51], v[50:51], v[170:171]
	s_nop 0
	v_addc_co_u32_e32 v159, vcc, 0, v159, vcc
	global_load_dwordx4 v[130:133], v[174:175], off
	global_load_dwordx4 v[170:173], v[158:159], off
	s_waitcnt vmcnt(1)
; __device__ __forceinline__ float bflo(unsigned w) { return __uint_as_float(w << 16); }
; __device__ __forceinline__ float bfhi(unsigned w) { return __uint_as_float(w & 0xffff0000u); }
;     __device__ __forceinline__ void mid(f32x4 (&acc)[2][2][4][2], const Unit& u, int wr, int wc, int fr, int fq) const {
;     ...
;             for (int m = 0; m < 4; ++m) { const bf16_t* pr = P + (size_t)(row0 + ai * HALF + m * 16) * NP + col0;
; #pragma unroll
;                 for (int bj = 0; bj < 2; ++bj) { const u32x4 a = *(const u32x4*)(pr + PC_GA + bj * HALF), b = *(const u32x4*)(pr + PC_GB + bj * HALF);
;                     const f32x4 b0 = {bflo(b.x), bfhi(b.x), bflo(b.y), bfhi(b.y)}, b1 = {bflo(b.z), bfhi(b.z), bflo(b.w), bfhi(b.w)};
;                     const f32x4 a0 = {bflo(a.x), bfhi(a.x), bflo(a.y), bfhi(a.y)}, a1 = {bflo(a.z), bfhi(a.z), bflo(a.w), bfhi(a.w)};
;                     f32x4 r0, r1;
; #pragma unroll
;                     for (int j = 0; j < 4; ++j) { r0[j] = a0[j] * __builtin_amdgcn_rcpf(fmaxf(b0[j], 1e-30f)); r1[j] = a1[j] * __builtin_amdgcn_rcpf(fmaxf(b1[j], 1e-30f)); }
;                     acc[ai][bj][m][0] *= r0; acc[ai][bj][m][1] *= r1; }
	v_and_b32_e32 v177, 0xffff0000, v130
	s_waitcnt vmcnt(0)
	v_lshlrev_b32_e32 v169, 16, v170
	v_max_f32_e32 v169, v169, v169
	v_lshlrev_b32_e32 v178, 16, v171
	v_and_b32_e32 v179, 0xffff0000, v171
	v_lshlrev_b32_e32 v171, 16, v172
	v_max_f32_e32 v169, 0xda24260, v169
	v_and_b32_e32 v176, 0xffff0000, v170
	v_rcp_f32_e32 v170, v169
	v_max_f32_e32 v169, v171, v171
	v_max_f32_e32 v169, 0xda24260, v169
	v_and_b32_e32 v180, 0xffff0000, v172
	v_rcp_f32_e32 v172, v169
	v_max_f32_e32 v169, v176, v176
	v_max_f32_e32 v169, 0xda24260, v169
	v_lshlrev_b32_e32 v176, 16, v130
	v_max_f32_e32 v130, v180, v180
	v_rcp_f32_e32 v171, v169
	v_max_f32_e32 v130, 0xda24260, v130
	v_lshlrev_b32_e32 v181, 16, v173
	v_and_b32_e32 v182, 0xffff0000, v173
	v_rcp_f32_e32 v173, v130
	v_max_f32_e32 v130, v178, v178
	v_pk_mul_f32 v[170:171], v[170:171], v[176:177]
	v_lshlrev_b32_e32 v176, 16, v132
	v_and_b32_e32 v177, 0xffff0000, v132
	v_max_f32_e32 v130, 0xda24260, v130
	v_pk_mul_f32 v[172:173], v[172:173], v[176:177]
	v_rcp_f32_e32 v176, v130
	v_max_f32_e32 v130, v181, v181
	v_lshlrev_b32_e32 v180, 16, v131
	v_and_b32_e32 v181, 0xffff0000, v131
	v_max_f32_e32 v131, v182, v182
	v_max_f32_e32 v130, 0xda24260, v130
	v_max_f32_e32 v131, 0xda24260, v131
	v_rcp_f32_e32 v130, v130
	v_rcp_f32_e32 v131, v131
	v_max_f32_e32 v132, v179, v179
	v_max_f32_e32 v132, 0xda24260, v132
	v_rcp_f32_e32 v177, v132
	v_lshlrev_b32_e32 v132, 16, v133
	v_and_b32_e32 v133, 0xffff0000, v133
	v_pk_mul_f32 v[130:131], v[130:131], v[132:133]
	v_pk_mul_f32 v[70:71], v[70:71], v[170:171]
	v_pk_mul_f32 v[68:69], v[68:69], v[130:131]
	v_pk_mul_f32 v[66:67], v[66:67], v[172:173]
	global_load_dwordx4 v[130:133], v[174:175], off offset:256
	global_load_dwordx4 v[170:173], v[158:159], off offset:256
	v_pk_mul_f32 v[176:177], v[176:177], v[180:181]
	s_waitcnt vmcnt(0)
	v_lshlrev_b32_e32 v158, 16, v170
	v_and_b32_e32 v159, 0xffff0000, v170
	v_lshlrev_b32_e32 v169, 16, v171
	v_and_b32_e32 v174, 0xffff0000, v171
	v_lshlrev_b32_e32 v170, 16, v172
	v_and_b32_e32 v171, 0xffff0000, v172
	v_max_f32_e32 v158, v158, v158
	v_max_f32_e32 v159, v159, v159
	v_pk_mul_f32 v[72:73], v[72:73], v[176:177]
	v_lshlrev_b32_e32 v175, 16, v173
	v_and_b32_e32 v176, 0xffff0000, v173
	v_max_f32_e32 v158, 0xda24260, v158
	v_max_f32_e32 v170, v170, v170
	v_max_f32_e32 v159, 0xda24260, v159
	v_lshlrev_b32_e32 v172, 16, v130
	v_and_b32_e32 v173, 0xffff0000, v130
	v_max_f32_e32 v130, v171, v171
	v_rcp_f32_e32 v158, v158
	v_max_f32_e32 v170, 0xda24260, v170
	v_rcp_f32_e32 v159, v159
	v_max_f32_e32 v130, 0xda24260, v130
	v_rcp_f32_e32 v170, v170
	v_rcp_f32_e32 v171, v130
	v_max_f32_e32 v130, v169, v169
	v_pk_mul_f32 v[158:159], v[158:159], v[172:173]
	v_lshlrev_b32_e32 v172, 16, v132
	v_and_b32_e32 v173, 0xffff0000, v132
	v_max_f32_e32 v130, 0xda24260, v130
	v_pk_mul_f32 v[170:171], v[170:171], v[172:173]
	v_rcp_f32_e32 v172, v130
	v_max_f32_e32 v130, v175, v175
	v_max_f32_e32 v132, v174, v174
	v_lshlrev_b32_e32 v174, 16, v131
	v_and_b32_e32 v175, 0xffff0000, v131
	v_max_f32_e32 v131, v176, v176
	v_max_f32_e32 v130, 0xda24260, v130
	v_max_f32_e32 v131, 0xda24260, v131
	v_rcp_f32_e32 v130, v130
	v_rcp_f32_e32 v131, v131
	v_max_f32_e32 v132, 0xda24260, v132
	v_rcp_f32_e32 v173, v132
	v_lshlrev_b32_e32 v132, 16, v133
	v_and_b32_e32 v133, 0xffff0000, v133
	v_pk_mul_f32 v[130:131], v[130:131], v[132:133]
	v_pk_mul_f32 v[86:87], v[86:87], v[158:159]
	v_pk_mul_f32 v[84:85], v[84:85], v[130:131]
	v_add_u32_e32 v130, 48, v168
	v_mad_i64_i32 v[158:159], s[58:59], v130, s78, v[156:157]
	v_pk_mul_f32 v[172:173], v[172:173], v[174:175]
	v_add_co_u32_e32 v174, vcc, s61, v158
	v_pk_mul_f32 v[88:89], v[88:89], v[172:173]
	s_nop 0
	v_addc_co_u32_e32 v175, vcc, 0, v159, vcc
	v_add_co_u32_e32 v158, vcc, s77, v158
	v_pk_mul_f32 v[82:83], v[82:83], v[170:171]
	s_nop 0
	v_addc_co_u32_e32 v159, vcc, 0, v159, vcc
	global_load_dwordx4 v[130:133], v[174:175], off
	global_load_dwordx4 v[170:173], v[158:159], off
	s_waitcnt vmcnt(1)
	v_and_b32_e32 v177, 0xffff0000, v130
	s_waitcnt vmcnt(0)
	v_lshlrev_b32_e32 v169, 16, v170
	v_max_f32_e32 v169, v169, v169
	v_lshlrev_b32_e32 v178, 16, v171
	v_and_b32_e32 v179, 0xffff0000, v171
	v_lshlrev_b32_e32 v171, 16, v172
	v_max_f32_e32 v169, 0xda24260, v169
	v_and_b32_e32 v176, 0xffff0000, v170
	v_rcp_f32_e32 v170, v169
	v_max_f32_e32 v169, v171, v171
	v_max_f32_e32 v169, 0xda24260, v169
	v_and_b32_e32 v180, 0xffff0000, v172
	v_rcp_f32_e32 v172, v169
	v_max_f32_e32 v169, v176, v176
	v_max_f32_e32 v169, 0xda24260, v169
	v_lshlrev_b32_e32 v176, 16, v130
	v_max_f32_e32 v130, v180, v180
	v_rcp_f32_e32 v171, v169
	v_max_f32_e32 v130, 0xda24260, v130
	v_lshlrev_b32_e32 v181, 16, v173
	v_and_b32_e32 v182, 0xffff0000, v173
	v_rcp_f32_e32 v173, v130
	v_max_f32_e32 v130, v178, v178
	v_pk_mul_f32 v[170:171], v[170:171], v[176:177]
	v_lshlrev_b32_e32 v176, 16, v132
	v_and_b32_e32 v177, 0xffff0000, v132
	v_max_f32_e32 v130, 0xda24260, v130
	v_pk_mul_f32 v[172:173], v[172:173], v[176:177]
	v_rcp_f32_e32 v176, v130
	v_max_f32_e32 v130, v181, v181
	v_lshlrev_b32_e32 v180, 16, v131
	v_and_b32_e32 v181, 0xffff0000, v131
	v_max_f32_e32 v131, v182, v182
	v_max_f32_e32 v130, 0xda24260, v130
	v_max_f32_e32 v131, 0xda24260, v131
	v_rcp_f32_e32 v130, v130
	v_rcp_f32_e32 v131, v131
	v_max_f32_e32 v132, v179, v179
	v_max_f32_e32 v132, 0xda24260, v132
	v_rcp_f32_e32 v177, v132
	v_lshlrev_b32_e32 v132, 16, v133
	v_and_b32_e32 v133, 0xffff0000, v133
	v_pk_mul_f32 v[130:131], v[130:131], v[132:133]
	v_pk_mul_f32 v[94:95], v[94:95], v[170:171]
	v_pk_mul_f32 v[92:93], v[92:93], v[130:131]
	v_pk_mul_f32 v[90:91], v[90:91], v[172:173]
	global_load_dwordx4 v[130:133], v[174:175], off offset:256
	global_load_dwordx4 v[170:173], v[158:159], off offset:256
	v_pk_mul_f32 v[176:177], v[176:177], v[180:181]
	s_waitcnt vmcnt(0)
; __device__ __forceinline__ float bflo(unsigned w) { return __uint_as_float(w << 16); }
; __device__ __forceinline__ float bfhi(unsigned w) { return __uint_as_float(w & 0xffff0000u); }
;     __device__ __forceinline__ void mid(f32x4 (&acc)[2][2][4][2], const Unit& u, int wr, int wc, int fr, int fq) const {
;     ...
;             for (int m = 0; m < 4; ++m) { const bf16_t* pr = P + (size_t)(row0 + ai * HALF + m * 16) * NP + col0;
; #pragma unroll
;                 for (int bj = 0; bj < 2; ++bj) { const u32x4 a = *(const u32x4*)(pr + PC_GA + bj * HALF), b = *(const u32x4*)(pr + PC_GB + bj * HALF);
;                     const f32x4 b0 = {bflo(b.x), bfhi(b.x), bflo(b.y), bfhi(b.y)}, b1 = {bflo(b.z), bfhi(b.z), bflo(b.w), bfhi(b.w)};
;                     const f32x4 a0 = {bflo(a.x), bfhi(a.x), bflo(a.y), bfhi(a.y)}, a1 = {bflo(a.z), bfhi(a.z), bflo(a.w), bfhi(a.w)};
;                     f32x4 r0, r1;
; #pragma unroll
;                     for (int j = 0; j < 4; ++j) { r0[j] = a0[j] * __builtin_amdgcn_rcpf(fmaxf(b0[j], 1e-30f)); r1[j] = a1[j] * __builtin_amdgcn_rcpf(fmaxf(b1[j], 1e-30f)); }
;                     acc[ai][bj][m][0] *= r0; acc[ai][bj][m][1] *= r1; }
	v_lshlrev_b32_e32 v158, 16, v170
	v_and_b32_e32 v159, 0xffff0000, v170
	v_lshlrev_b32_e32 v169, 16, v171
	v_and_b32_e32 v174, 0xffff0000, v171
	v_lshlrev_b32_e32 v170, 16, v172
	v_and_b32_e32 v171, 0xffff0000, v172
	v_max_f32_e32 v158, v158, v158
	v_max_f32_e32 v159, v159, v159
	v_pk_mul_f32 v[96:97], v[96:97], v[176:177]
	v_lshlrev_b32_e32 v175, 16, v173
	v_and_b32_e32 v176, 0xffff0000, v173
	v_max_f32_e32 v158, 0xda24260, v158
	v_max_f32_e32 v170, v170, v170
	v_max_f32_e32 v159, 0xda24260, v159
	v_lshlrev_b32_e32 v172, 16, v130
	v_and_b32_e32 v173, 0xffff0000, v130
	v_max_f32_e32 v130, v171, v171
	v_rcp_f32_e32 v158, v158
	v_max_f32_e32 v170, 0xda24260, v170
	v_rcp_f32_e32 v159, v159
	v_max_f32_e32 v130, 0xda24260, v130
	v_rcp_f32_e32 v170, v170
	v_rcp_f32_e32 v171, v130
	v_max_f32_e32 v130, v169, v169
	v_pk_mul_f32 v[158:159], v[158:159], v[172:173]
	v_lshlrev_b32_e32 v172, 16, v132
	v_and_b32_e32 v173, 0xffff0000, v132
	v_max_f32_e32 v130, 0xda24260, v130
	v_pk_mul_f32 v[170:171], v[170:171], v[172:173]
	v_rcp_f32_e32 v172, v130
	v_max_f32_e32 v130, v175, v175
	v_max_f32_e32 v132, v174, v174
	v_lshlrev_b32_e32 v174, 16, v131
	v_and_b32_e32 v175, 0xffff0000, v131
	v_max_f32_e32 v131, v176, v176
	v_max_f32_e32 v130, 0xda24260, v130
	v_max_f32_e32 v131, 0xda24260, v131
	v_rcp_f32_e32 v130, v130
	v_rcp_f32_e32 v131, v131
	v_max_f32_e32 v132, 0xda24260, v132
	v_rcp_f32_e32 v173, v132
	v_lshlrev_b32_e32 v132, 16, v133
	v_and_b32_e32 v133, 0xffff0000, v133
	v_pk_mul_f32 v[130:131], v[130:131], v[132:133]
	v_pk_mul_f32 v[110:111], v[110:111], v[158:159]
	v_pk_mul_f32 v[108:109], v[108:109], v[130:131]
	v_add_u32_e32 v130, 0x80, v168
	v_mad_i64_i32 v[158:159], s[58:59], v130, s78, v[156:157]
	v_pk_mul_f32 v[172:173], v[172:173], v[174:175]
	v_add_co_u32_e32 v174, vcc, s61, v158
	v_pk_mul_f32 v[112:113], v[112:113], v[172:173]
	s_nop 0
	v_addc_co_u32_e32 v175, vcc, 0, v159, vcc
	v_add_co_u32_e32 v158, vcc, s77, v158
	v_pk_mul_f32 v[106:107], v[106:107], v[170:171]
	s_nop 0
	v_addc_co_u32_e32 v159, vcc, 0, v159, vcc
	global_load_dwordx4 v[130:133], v[174:175], off
	global_load_dwordx4 v[170:173], v[158:159], off
	s_waitcnt vmcnt(1)
	v_and_b32_e32 v177, 0xffff0000, v130
	s_waitcnt vmcnt(0)
	v_lshlrev_b32_e32 v169, 16, v170
	v_max_f32_e32 v169, v169, v169
	v_lshlrev_b32_e32 v178, 16, v171
	v_and_b32_e32 v179, 0xffff0000, v171
	v_lshlrev_b32_e32 v171, 16, v172
	v_max_f32_e32 v169, 0xda24260, v169
	v_and_b32_e32 v176, 0xffff0000, v170
	v_rcp_f32_e32 v170, v169
	v_max_f32_e32 v169, v171, v171
	v_max_f32_e32 v169, 0xda24260, v169
	v_and_b32_e32 v180, 0xffff0000, v172
	v_rcp_f32_e32 v172, v169
	v_max_f32_e32 v169, v176, v176
	v_max_f32_e32 v169, 0xda24260, v169
	v_lshlrev_b32_e32 v176, 16, v130
	v_max_f32_e32 v130, v180, v180
	v_rcp_f32_e32 v171, v169
	v_max_f32_e32 v130, 0xda24260, v130
	v_lshlrev_b32_e32 v181, 16, v173
	v_and_b32_e32 v182, 0xffff0000, v173
	v_rcp_f32_e32 v173, v130
	v_max_f32_e32 v130, v178, v178
	v_pk_mul_f32 v[170:171], v[170:171], v[176:177]
	v_lshlrev_b32_e32 v176, 16, v132
	v_and_b32_e32 v177, 0xffff0000, v132
	v_max_f32_e32 v130, 0xda24260, v130
	v_pk_mul_f32 v[172:173], v[172:173], v[176:177]
	v_rcp_f32_e32 v176, v130
	v_max_f32_e32 v130, v181, v181
	v_lshlrev_b32_e32 v180, 16, v131
	v_and_b32_e32 v181, 0xffff0000, v131
	v_max_f32_e32 v131, v182, v182
	v_max_f32_e32 v130, 0xda24260, v130
	v_max_f32_e32 v131, 0xda24260, v131
	v_rcp_f32_e32 v130, v130
	v_rcp_f32_e32 v131, v131
	v_max_f32_e32 v132, v179, v179
	v_max_f32_e32 v132, 0xda24260, v132
	v_rcp_f32_e32 v177, v132
	v_lshlrev_b32_e32 v132, 16, v133
	v_and_b32_e32 v133, 0xffff0000, v133
	v_pk_mul_f32 v[130:131], v[130:131], v[132:133]
	v_pk_mul_f32 v[126:127], v[126:127], v[170:171]
	v_pk_mul_f32 v[124:125], v[124:125], v[130:131]
	v_pk_mul_f32 v[122:123], v[122:123], v[172:173]
	global_load_dwordx4 v[130:133], v[174:175], off offset:256
	global_load_dwordx4 v[170:173], v[158:159], off offset:256
	v_pk_mul_f32 v[176:177], v[176:177], v[180:181]
	s_waitcnt vmcnt(0)
	v_lshlrev_b32_e32 v158, 16, v170
	v_and_b32_e32 v159, 0xffff0000, v170
	v_lshlrev_b32_e32 v169, 16, v171
	v_and_b32_e32 v174, 0xffff0000, v171
	v_lshlrev_b32_e32 v170, 16, v172
	v_and_b32_e32 v171, 0xffff0000, v172
	v_max_f32_e32 v158, v158, v158
	v_max_f32_e32 v159, v159, v159
	v_pk_mul_f32 v[128:129], v[128:129], v[176:177]
	v_lshlrev_b32_e32 v175, 16, v173
	v_and_b32_e32 v176, 0xffff0000, v173
	v_max_f32_e32 v158, 0xda24260, v158
	v_max_f32_e32 v170, v170, v170
	v_max_f32_e32 v159, 0xda24260, v159
	v_lshlrev_b32_e32 v172, 16, v130
	v_and_b32_e32 v173, 0xffff0000, v130
	v_max_f32_e32 v130, v171, v171
	v_rcp_f32_e32 v158, v158
	v_max_f32_e32 v170, 0xda24260, v170
	v_rcp_f32_e32 v159, v159
	v_max_f32_e32 v130, 0xda24260, v130
	v_rcp_f32_e32 v170, v170
	v_rcp_f32_e32 v171, v130
	v_max_f32_e32 v130, v169, v169
	v_pk_mul_f32 v[158:159], v[158:159], v[172:173]
	v_lshlrev_b32_e32 v172, 16, v132
	v_and_b32_e32 v173, 0xffff0000, v132
	v_max_f32_e32 v130, 0xda24260, v130
	v_pk_mul_f32 v[170:171], v[170:171], v[172:173]
	v_rcp_f32_e32 v172, v130
	v_max_f32_e32 v130, v175, v175
	v_max_f32_e32 v132, v174, v174
	v_lshlrev_b32_e32 v174, 16, v131
	v_and_b32_e32 v175, 0xffff0000, v131
	v_max_f32_e32 v131, v176, v176
	v_max_f32_e32 v130, 0xda24260, v130
	v_max_f32_e32 v131, 0xda24260, v131
	v_rcp_f32_e32 v130, v130
	v_rcp_f32_e32 v131, v131
	v_max_f32_e32 v132, 0xda24260, v132
	v_rcp_f32_e32 v173, v132
	v_lshlrev_b32_e32 v132, 16, v133
	v_and_b32_e32 v133, 0xffff0000, v133
	v_pk_mul_f32 v[130:131], v[130:131], v[132:133]
	v_pk_mul_f32 v[118:119], v[118:119], v[158:159]
	v_pk_mul_f32 v[116:117], v[116:117], v[130:131]
	v_add_u32_e32 v130, 0x90, v168
	v_mad_i64_i32 v[158:159], s[58:59], v130, s78, v[156:157]
	v_pk_mul_f32 v[172:173], v[172:173], v[174:175]
	v_add_co_u32_e32 v174, vcc, s61, v158
	v_pk_mul_f32 v[120:121], v[120:121], v[172:173]
	s_nop 0
	v_addc_co_u32_e32 v175, vcc, 0, v159, vcc
	v_add_co_u32_e32 v158, vcc, s77, v158
	v_pk_mul_f32 v[114:115], v[114:115], v[170:171]
	s_nop 0
	v_addc_co_u32_e32 v159, vcc, 0, v159, vcc
	global_load_dwordx4 v[130:133], v[174:175], off
	global_load_dwordx4 v[170:173], v[158:159], off
	s_waitcnt vmcnt(1)
; __device__ __forceinline__ float bflo(unsigned w) { return __uint_as_float(w << 16); }
; __device__ __forceinline__ float bfhi(unsigned w) { return __uint_as_float(w & 0xffff0000u); }
;     __device__ __forceinline__ void mid(f32x4 (&acc)[2][2][4][2], const Unit& u, int wr, int wc, int fr, int fq) const {
;     ...
;             for (int m = 0; m < 4; ++m) { const bf16_t* pr = P + (size_t)(row0 + ai * HALF + m * 16) * NP + col0;
; #pragma unroll
;                 for (int bj = 0; bj < 2; ++bj) { const u32x4 a = *(const u32x4*)(pr + PC_GA + bj * HALF), b = *(const u32x4*)(pr + PC_GB + bj * HALF);
;                     const f32x4 b0 = {bflo(b.x), bfhi(b.x), bflo(b.y), bfhi(b.y)}, b1 = {bflo(b.z), bfhi(b.z), bflo(b.w), bfhi(b.w)};
;                     const f32x4 a0 = {bflo(a.x), bfhi(a.x), bflo(a.y), bfhi(a.y)}, a1 = {bflo(a.z), bfhi(a.z), bflo(a.w), bfhi(a.w)};
;                     f32x4 r0, r1;
; #pragma unroll
;                     for (int j = 0; j < 4; ++j) { r0[j] = a0[j] * __builtin_amdgcn_rcpf(fmaxf(b0[j], 1e-30f)); r1[j] = a1[j] * __builtin_amdgcn_rcpf(fmaxf(b1[j], 1e-30f)); }
;                     acc[ai][bj][m][0] *= r0; acc[ai][bj][m][1] *= r1; }
	v_and_b32_e32 v177, 0xffff0000, v130
	s_waitcnt vmcnt(0)
	v_lshlrev_b32_e32 v169, 16, v170
	v_max_f32_e32 v169, v169, v169
	v_lshlrev_b32_e32 v178, 16, v171
	v_and_b32_e32 v179, 0xffff0000, v171
	v_lshlrev_b32_e32 v171, 16, v172
	v_max_f32_e32 v169, 0xda24260, v169
	v_and_b32_e32 v176, 0xffff0000, v170
	v_rcp_f32_e32 v170, v169
	v_max_f32_e32 v169, v171, v171
	v_max_f32_e32 v169, 0xda24260, v169
	v_and_b32_e32 v180, 0xffff0000, v172
	v_rcp_f32_e32 v172, v169
	v_max_f32_e32 v169, v176, v176
	v_max_f32_e32 v169, 0xda24260, v169
	v_lshlrev_b32_e32 v176, 16, v130
	v_max_f32_e32 v130, v180, v180
	v_rcp_f32_e32 v171, v169
	v_max_f32_e32 v130, 0xda24260, v130
	v_lshlrev_b32_e32 v181, 16, v173
	v_and_b32_e32 v182, 0xffff0000, v173
	v_rcp_f32_e32 v173, v130
	v_max_f32_e32 v130, v178, v178
	v_pk_mul_f32 v[170:171], v[170:171], v[176:177]
	v_lshlrev_b32_e32 v176, 16, v132
	v_and_b32_e32 v177, 0xffff0000, v132
	v_max_f32_e32 v130, 0xda24260, v130
	v_pk_mul_f32 v[172:173], v[172:173], v[176:177]
	v_rcp_f32_e32 v176, v130
	v_max_f32_e32 v130, v181, v181
	v_lshlrev_b32_e32 v180, 16, v131
	v_and_b32_e32 v181, 0xffff0000, v131
	v_max_f32_e32 v131, v182, v182
	v_max_f32_e32 v130, 0xda24260, v130
	v_max_f32_e32 v131, 0xda24260, v131
	v_rcp_f32_e32 v130, v130
	v_rcp_f32_e32 v131, v131
	v_max_f32_e32 v132, v179, v179
	v_max_f32_e32 v132, 0xda24260, v132
	v_rcp_f32_e32 v177, v132
	v_lshlrev_b32_e32 v132, 16, v133
	v_and_b32_e32 v133, 0xffff0000, v133
	v_pk_mul_f32 v[130:131], v[130:131], v[132:133]
	v_pk_mul_f32 v[102:103], v[102:103], v[170:171]
	v_pk_mul_f32 v[100:101], v[100:101], v[130:131]
	v_pk_mul_f32 v[98:99], v[98:99], v[172:173]
	global_load_dwordx4 v[130:133], v[174:175], off offset:256
	global_load_dwordx4 v[170:173], v[158:159], off offset:256
	v_pk_mul_f32 v[176:177], v[176:177], v[180:181]
	s_waitcnt vmcnt(0)
	v_lshlrev_b32_e32 v158, 16, v170
	v_and_b32_e32 v159, 0xffff0000, v170
	v_lshlrev_b32_e32 v169, 16, v171
	v_and_b32_e32 v174, 0xffff0000, v171
	v_lshlrev_b32_e32 v170, 16, v172
	v_and_b32_e32 v171, 0xffff0000, v172
	v_max_f32_e32 v158, v158, v158
	v_max_f32_e32 v159, v159, v159
	v_pk_mul_f32 v[104:105], v[104:105], v[176:177]
	v_lshlrev_b32_e32 v175, 16, v173
	v_and_b32_e32 v176, 0xffff0000, v173
	v_max_f32_e32 v158, 0xda24260, v158
	v_max_f32_e32 v170, v170, v170
	v_max_f32_e32 v159, 0xda24260, v159
	v_lshlrev_b32_e32 v172, 16, v130
	v_and_b32_e32 v173, 0xffff0000, v130
	v_max_f32_e32 v130, v171, v171
	v_rcp_f32_e32 v158, v158
	v_max_f32_e32 v170, 0xda24260, v170
	v_rcp_f32_e32 v159, v159
	v_max_f32_e32 v130, 0xda24260, v130
	v_rcp_f32_e32 v170, v170
	v_rcp_f32_e32 v171, v130
	v_max_f32_e32 v130, v169, v169
	v_pk_mul_f32 v[158:159], v[158:159], v[172:173]
	v_lshlrev_b32_e32 v172, 16, v132
	v_and_b32_e32 v173, 0xffff0000, v132
	v_max_f32_e32 v130, 0xda24260, v130
	v_pk_mul_f32 v[170:171], v[170:171], v[172:173]
	v_rcp_f32_e32 v172, v130
	v_max_f32_e32 v130, v175, v175
	v_max_f32_e32 v132, v174, v174
	v_lshlrev_b32_e32 v174, 16, v131
	v_and_b32_e32 v175, 0xffff0000, v131
	v_max_f32_e32 v131, v176, v176
	v_max_f32_e32 v130, 0xda24260, v130
	v_max_f32_e32 v131, 0xda24260, v131
	v_rcp_f32_e32 v130, v130
	v_rcp_f32_e32 v131, v131
	v_max_f32_e32 v132, 0xda24260, v132
	v_rcp_f32_e32 v173, v132
	v_lshlrev_b32_e32 v132, 16, v133
	v_and_b32_e32 v133, 0xffff0000, v133
	v_pk_mul_f32 v[130:131], v[130:131], v[132:133]
	v_pk_mul_f32 v[78:79], v[78:79], v[158:159]
	v_pk_mul_f32 v[76:77], v[76:77], v[130:131]
	v_add_u32_e32 v130, 0xa0, v168
	v_mad_i64_i32 v[158:159], s[58:59], v130, s78, v[156:157]
	v_pk_mul_f32 v[172:173], v[172:173], v[174:175]
	v_add_co_u32_e32 v174, vcc, s61, v158
	v_pk_mul_f32 v[80:81], v[80:81], v[172:173]
	s_nop 0
	v_addc_co_u32_e32 v175, vcc, 0, v159, vcc
	v_add_co_u32_e32 v158, vcc, s77, v158
	v_pk_mul_f32 v[74:75], v[74:75], v[170:171]
	s_nop 0
	v_addc_co_u32_e32 v159, vcc, 0, v159, vcc
	global_load_dwordx4 v[130:133], v[174:175], off
	global_load_dwordx4 v[170:173], v[158:159], off
	s_waitcnt vmcnt(1)
	v_and_b32_e32 v177, 0xffff0000, v130
	s_waitcnt vmcnt(0)
	v_lshlrev_b32_e32 v169, 16, v170
	v_max_f32_e32 v169, v169, v169
	v_lshlrev_b32_e32 v178, 16, v171
	v_and_b32_e32 v179, 0xffff0000, v171
	v_lshlrev_b32_e32 v171, 16, v172
	v_max_f32_e32 v169, 0xda24260, v169
	v_and_b32_e32 v176, 0xffff0000, v170
	v_rcp_f32_e32 v170, v169
	v_max_f32_e32 v169, v171, v171
	v_max_f32_e32 v169, 0xda24260, v169
	v_and_b32_e32 v180, 0xffff0000, v172
	v_rcp_f32_e32 v172, v169
	v_max_f32_e32 v169, v176, v176
	v_max_f32_e32 v169, 0xda24260, v169
	v_lshlrev_b32_e32 v176, 16, v130
	v_max_f32_e32 v130, v180, v180
	v_rcp_f32_e32 v171, v169
	v_max_f32_e32 v130, 0xda24260, v130
	v_lshlrev_b32_e32 v181, 16, v173
	v_and_b32_e32 v182, 0xffff0000, v173
	v_rcp_f32_e32 v173, v130
	v_max_f32_e32 v130, v178, v178
	v_pk_mul_f32 v[170:171], v[170:171], v[176:177]
	v_lshlrev_b32_e32 v176, 16, v132
	v_and_b32_e32 v177, 0xffff0000, v132
	v_max_f32_e32 v130, 0xda24260, v130
	v_pk_mul_f32 v[172:173], v[172:173], v[176:177]
	v_rcp_f32_e32 v176, v130
	v_max_f32_e32 v130, v181, v181
	v_lshlrev_b32_e32 v180, 16, v131
	v_and_b32_e32 v181, 0xffff0000, v131
	v_max_f32_e32 v131, v182, v182
	v_max_f32_e32 v130, 0xda24260, v130
	v_max_f32_e32 v131, 0xda24260, v131
	v_rcp_f32_e32 v130, v130
	v_rcp_f32_e32 v131, v131
	v_max_f32_e32 v132, v179, v179
	v_max_f32_e32 v132, 0xda24260, v132
	v_rcp_f32_e32 v177, v132
	v_lshlrev_b32_e32 v132, 16, v133
	v_and_b32_e32 v133, 0xffff0000, v133
	v_pk_mul_f32 v[130:131], v[130:131], v[132:133]
	v_pk_mul_f32 v[62:63], v[62:63], v[170:171]
	v_pk_mul_f32 v[60:61], v[60:61], v[130:131]
	v_pk_mul_f32 v[58:59], v[58:59], v[172:173]
	global_load_dwordx4 v[130:133], v[174:175], off offset:256
	global_load_dwordx4 v[170:173], v[158:159], off offset:256
	v_pk_mul_f32 v[176:177], v[176:177], v[180:181]
	s_waitcnt vmcnt(0)
; __device__ __forceinline__ float bflo(unsigned w) { return __uint_as_float(w << 16); }
; __device__ __forceinline__ float bfhi(unsigned w) { return __uint_as_float(w & 0xffff0000u); }
;     __device__ __forceinline__ void mid(f32x4 (&acc)[2][2][4][2], const Unit& u, int wr, int wc, int fr, int fq) const {
;     ...
;             for (int m = 0; m < 4; ++m) { const bf16_t* pr = P + (size_t)(row0 + ai * HALF + m * 16) * NP + col0;
; #pragma unroll
;                 for (int bj = 0; bj < 2; ++bj) { const u32x4 a = *(const u32x4*)(pr + PC_GA + bj * HALF), b = *(const u32x4*)(pr + PC_GB + bj * HALF);
;                     const f32x4 b0 = {bflo(b.x), bfhi(b.x), bflo(b.y), bfhi(b.y)}, b1 = {bflo(b.z), bfhi(b.z), bflo(b.w), bfhi(b.w)};
;                     const f32x4 a0 = {bflo(a.x), bfhi(a.x), bflo(a.y), bfhi(a.y)}, a1 = {bflo(a.z), bfhi(a.z), bflo(a.w), bfhi(a.w)};
;                     f32x4 r0, r1;
; #pragma unroll
;                     for (int j = 0; j < 4; ++j) { r0[j] = a0[j] * __builtin_amdgcn_rcpf(fmaxf(b0[j], 1e-30f)); r1[j] = a1[j] * __builtin_amdgcn_rcpf(fmaxf(b1[j], 1e-30f)); }
;                     acc[ai][bj][m][0] *= r0; acc[ai][bj][m][1] *= r1; }
	v_lshlrev_b32_e32 v158, 16, v170
	v_and_b32_e32 v159, 0xffff0000, v170
	v_lshlrev_b32_e32 v169, 16, v171
	v_and_b32_e32 v174, 0xffff0000, v171
	v_lshlrev_b32_e32 v170, 16, v172
	v_and_b32_e32 v171, 0xffff0000, v172
	v_max_f32_e32 v158, v158, v158
	v_max_f32_e32 v159, v159, v159
	v_pk_mul_f32 v[64:65], v[64:65], v[176:177]
	v_lshlrev_b32_e32 v175, 16, v173
	v_and_b32_e32 v176, 0xffff0000, v173
	v_max_f32_e32 v158, 0xda24260, v158
	v_max_f32_e32 v170, v170, v170
	v_max_f32_e32 v159, 0xda24260, v159
	v_lshlrev_b32_e32 v172, 16, v130
	v_and_b32_e32 v173, 0xffff0000, v130
	v_max_f32_e32 v130, v171, v171
	v_rcp_f32_e32 v158, v158
	v_max_f32_e32 v170, 0xda24260, v170
	v_rcp_f32_e32 v159, v159
	v_max_f32_e32 v130, 0xda24260, v130
	v_rcp_f32_e32 v170, v170
	v_rcp_f32_e32 v171, v130
	v_max_f32_e32 v130, v169, v169
	v_pk_mul_f32 v[158:159], v[158:159], v[172:173]
	v_lshlrev_b32_e32 v172, 16, v132
	v_and_b32_e32 v173, 0xffff0000, v132
	v_max_f32_e32 v130, 0xda24260, v130
	v_pk_mul_f32 v[170:171], v[170:171], v[172:173]
	v_rcp_f32_e32 v172, v130
	v_max_f32_e32 v130, v175, v175
	v_max_f32_e32 v132, v174, v174
	v_lshlrev_b32_e32 v174, 16, v131
	v_and_b32_e32 v175, 0xffff0000, v131
	v_max_f32_e32 v131, v176, v176
	v_max_f32_e32 v130, 0xda24260, v130
	v_max_f32_e32 v131, 0xda24260, v131
	v_rcp_f32_e32 v130, v130
	v_rcp_f32_e32 v131, v131
	v_max_f32_e32 v132, 0xda24260, v132
	v_rcp_f32_e32 v173, v132
	v_lshlrev_b32_e32 v132, 16, v133
	v_and_b32_e32 v133, 0xffff0000, v133
	v_pk_mul_f32 v[130:131], v[130:131], v[132:133]
	v_pk_mul_f32 v[46:47], v[46:47], v[158:159]
	v_pk_mul_f32 v[44:45], v[44:45], v[130:131]
	v_add_u32_e32 v130, 0xb0, v168
	v_mad_i64_i32 v[156:157], s[58:59], v130, s78, v[156:157]
	v_add_co_u32_e32 v158, vcc, s61, v156
	v_pk_mul_f32 v[42:43], v[42:43], v[170:171]
	s_nop 0
	v_addc_co_u32_e32 v159, vcc, 0, v157, vcc
	v_add_co_u32_e32 v156, vcc, s77, v156
	global_load_dwordx4 v[130:133], v[158:159], off
	s_nop 0
	v_addc_co_u32_e32 v157, vcc, 0, v157, vcc
	global_load_dwordx4 v[168:171], v[156:157], off
	v_pk_mul_f32 v[172:173], v[172:173], v[174:175]
	s_waitcnt vmcnt(0)
	v_lshlrev_b32_e32 v174, 16, v169
	v_and_b32_e32 v175, 0xffff0000, v169
	v_lshlrev_b32_e32 v169, 16, v170
	v_max_f32_e32 v169, v169, v169
	v_pk_mul_f32 v[48:49], v[48:49], v[172:173]
	v_lshlrev_b32_e32 v172, 16, v168
	v_and_b32_e32 v173, 0xffff0000, v168
	v_max_f32_e32 v169, 0xda24260, v169
	v_and_b32_e32 v176, 0xffff0000, v170
	v_max_f32_e32 v168, v172, v172
	v_rcp_f32_e32 v170, v169
	v_max_f32_e32 v169, v173, v173
	v_max_f32_e32 v168, 0xda24260, v168
	v_max_f32_e32 v169, 0xda24260, v169
	v_lshlrev_b32_e32 v172, 16, v130
	v_and_b32_e32 v173, 0xffff0000, v130
	v_max_f32_e32 v130, v176, v176
	v_rcp_f32_e32 v168, v168
	v_rcp_f32_e32 v169, v169
	v_max_f32_e32 v130, 0xda24260, v130
	v_lshlrev_b32_e32 v177, 16, v171
	v_and_b32_e32 v178, 0xffff0000, v171
	v_rcp_f32_e32 v171, v130
	v_max_f32_e32 v130, v174, v174
	v_pk_mul_f32 v[168:169], v[168:169], v[172:173]
	v_lshlrev_b32_e32 v172, 16, v132
	v_and_b32_e32 v173, 0xffff0000, v132
	v_max_f32_e32 v130, 0xda24260, v130
	v_pk_mul_f32 v[170:171], v[170:171], v[172:173]
	v_rcp_f32_e32 v172, v130
	v_max_f32_e32 v130, v177, v177
	v_max_f32_e32 v132, v175, v175
	v_lshlrev_b32_e32 v174, 16, v131
	v_and_b32_e32 v175, 0xffff0000, v131
	v_max_f32_e32 v131, v178, v178
	v_max_f32_e32 v130, 0xda24260, v130
	v_max_f32_e32 v131, 0xda24260, v131
	v_rcp_f32_e32 v130, v130
	v_rcp_f32_e32 v131, v131
	v_max_f32_e32 v132, 0xda24260, v132
	v_rcp_f32_e32 v173, v132
	v_lshlrev_b32_e32 v132, 16, v133
	v_and_b32_e32 v133, 0xffff0000, v133
	v_pk_mul_f32 v[130:131], v[130:131], v[132:133]
	v_pk_mul_f32 v[18:19], v[18:19], v[170:171]
	v_pk_mul_f32 v[20:21], v[20:21], v[130:131]
	global_load_dwordx4 v[130:133], v[158:159], off offset:256
	s_nop 0
	global_load_dwordx4 v[156:159], v[156:157], off offset:256
	v_pk_mul_f32 v[172:173], v[172:173], v[174:175]
	v_pk_mul_f32 v[22:23], v[22:23], v[168:169]
	v_pk_mul_f32 v[24:25], v[24:25], v[172:173]
	s_waitcnt vmcnt(0)
	v_lshlrev_b32_e32 v170, 16, v157
	v_and_b32_e32 v171, 0xffff0000, v157
	v_lshlrev_b32_e32 v157, 16, v158
	v_max_f32_e32 v157, v157, v157
	v_lshlrev_b32_e32 v168, 16, v156
	v_and_b32_e32 v169, 0xffff0000, v156
	v_max_f32_e32 v157, 0xda24260, v157
	v_and_b32_e32 v172, 0xffff0000, v158
	v_max_f32_e32 v156, v168, v168
	v_rcp_f32_e32 v158, v157
	v_max_f32_e32 v157, v169, v169
	v_max_f32_e32 v156, 0xda24260, v156
	v_max_f32_e32 v157, 0xda24260, v157
	v_lshlrev_b32_e32 v168, 16, v130
	v_and_b32_e32 v169, 0xffff0000, v130
	v_max_f32_e32 v130, v172, v172
	v_rcp_f32_e32 v156, v156
	v_rcp_f32_e32 v157, v157
	v_max_f32_e32 v130, 0xda24260, v130
	v_lshlrev_b32_e32 v173, 16, v159
	v_and_b32_e32 v174, 0xffff0000, v159
	v_rcp_f32_e32 v159, v130
	v_max_f32_e32 v130, v170, v170
	v_pk_mul_f32 v[156:157], v[156:157], v[168:169]
	v_lshlrev_b32_e32 v168, 16, v132
	v_and_b32_e32 v169, 0xffff0000, v132
	v_max_f32_e32 v130, 0xda24260, v130
	v_pk_mul_f32 v[158:159], v[158:159], v[168:169]
	v_rcp_f32_e32 v168, v130
	v_max_f32_e32 v130, v173, v173
	v_max_f32_e32 v132, v171, v171
	v_lshlrev_b32_e32 v170, 16, v131
	v_and_b32_e32 v171, 0xffff0000, v131
	v_max_f32_e32 v131, v174, v174
	v_max_f32_e32 v130, 0xda24260, v130
	v_max_f32_e32 v132, 0xda24260, v132
	v_max_f32_e32 v131, 0xda24260, v131
	v_rcp_f32_e32 v130, v130
	v_rcp_f32_e32 v169, v132
	v_rcp_f32_e32 v131, v131
	v_lshlrev_b32_e32 v132, 16, v133
	v_and_b32_e32 v133, 0xffff0000, v133
	v_pk_mul_f32 v[168:169], v[168:169], v[170:171]
	v_pk_mul_f32 v[130:131], v[130:131], v[132:133]
	v_pk_mul_f32 v[8:9], v[8:9], v[168:169]
	v_pk_mul_f32 v[6:7], v[6:7], v[156:157]
	v_pk_mul_f32 v[4:5], v[4:5], v[130:131]
	v_pk_mul_f32 v[2:3], v[2:3], v[158:159]
; #define PG8_STAGE(bufoff, gbase, voff) do { _Pragma("unroll") for (int _i = 0; _i < 2; ++_i) \
;         __builtin_amdgcn_global_load_lds((const unsigned*)((const char*)(gbase) + (voff)[_i]), (PG8_LAS unsigned*)(lds + (bufoff) + ldsw + _i * 8192), 16, 0, 0); } while (0)
; #define PG8_LDA(dst, b, h) do { _Pragma("unroll") for (int m = 0; m < 4; ++m) _Pragma("unroll") for (int k = 0; k < 2; ++k) dst[m][k] = *(const PG8_LAS bf16x8*)(lds + PG8_SA(b, h) + aoff + m * 2048 + k * 1024); } while (0)
; #define PG8_LDB(dst, b, h) do { _Pragma("unroll") for (int n = 0; n < 2; ++n) _Pragma("unroll") for (int k = 0; k < 2; ++k) dst[n][k] = *(const PG8_LAS bf16x8*)(lds + PG8_SB(b, h) + boff + n * 2048 + k * 1024); } while (0)
; #define PG8_MMA(ai, bj, At, Bt) do { __builtin_amdgcn_s_setprio(1); _Pragma("unroll") for (int m = 0; m < 4; ++m) _Pragma("unroll") for (int n = 0; n < 2; ++n) _Pragma("unroll") for (int k = 0; k < 2; ++k) \
;         acc[ai][bj][m][n] = __builtin_amdgcn_mfma_f32_16x16x32_bf16(Bt[n][k], At[m][k], acc[ai][bj][m][n], 0, 0, 0); __builtin_amdgcn_s_setprio(0); } while (0)
; #define PG8_WAIT_V(n) asm volatile("s_waitcnt vmcnt(" #n ")" ::: "memory")
; #define PG8_WAIT_L(n) asm volatile("s_waitcnt lgkmcnt(" #n ")" ::: "memory")
; #define PG8_BAR __builtin_amdgcn_s_barrier()
; #define PG8_SCHED __builtin_amdgcn_sched_barrier(0)
; template <class Epi, class Sched, bool ALIGN_EPI = false, bool SP2 = false>
; __device__ __forceinline__ void gemm_phase(PG8_LAS unsigned char* lds, const Gemm g, const Sched& S, const Epi& E) {
;     ...
;             PG8_LDB(B0, 0, 0); PG8_LDB(B1, 0, 1); PG8_SCHED; PG8_LDA(At, 0, 0); PG8_STAGE(PG8_SA(1, 1), a1 + hstep, voffA);
;             PG8_WAIT_V(8); PG8_WAIT_L(0); PG8_BAR; PG8_MMA(0, 0, At, B0); PG8_MMA(0, 1, At, B1); PG8_BAR; PG8_SCHED;
;             PG8_LDA(At, 0, 1); PG8_STAGE(PG8_SB(0, 0), b2, voffB); PG8_STAGE(PG8_SB(0, 1), b2 + hstep, voffB); PG8_STAGE(PG8_SA(0, 0), a2, voffA);
;             PG8_WAIT_V(8); PG8_WAIT_L(0); PG8_BAR; PG8_MMA(1, 0, At, B0); PG8_MMA(1, 1, At, B1); PG8_BAR; PG8_SCHED;
.LBB0_684:
	ds_read_b128 v[130:133], v163
	ds_read_b128 v[156:159], v163 offset:1024
	ds_read_b128 v[168:171], v163 offset:2048
	ds_read_b128 v[172:175], v163 offset:3072
	ds_read_b128 v[180:183], v164
	ds_read_b128 v[184:187], v164 offset:1024
	ds_read_b128 v[188:191], v164 offset:2048
	ds_read_b128 v[198:201], v164 offset:3072
	s_add_u32 s48, s50, 0x4000
	s_addc_u32 s49, s51, 0
	s_cmp_eq_u32 s56, 60
	s_cselect_b32 s72, s93, s48
	s_cselect_b32 s73, s41, s49
	s_cselect_b32 s70, s97, s26
	s_cselect_b32 s71, s27, s33
	s_add_u32 s48, s72, 0x8000
	s_addc_u32 s49, s73, 0
	s_mov_b32 m0, s83
	ds_read_b128 v[202:205], v165
	ds_read_b128 v[206:209], v165 offset:1024
	ds_read_b128 v[210:213], v165 offset:2048
	ds_read_b128 v[214:217], v165 offset:3072
	ds_read_b128 v[218:221], v165 offset:4096
	ds_read_b128 v[222:225], v165 offset:5120
	ds_read_b128 v[226:229], v165 offset:6144
	ds_read_b128 v[230:233], v165 offset:7168
	global_load_lds_dwordx4 v144, s[50:51]
	s_mov_b32 m0, s84
	s_nop 0
	global_load_lds_dwordx4 v146, s[50:51]
	s_waitcnt vmcnt(8)
	s_waitcnt lgkmcnt(0)
	s_barrier
	v_mfma_f32_16x16x32_bf16 v[14:17], v[130:133], v[202:205], v[14:17]
	v_mfma_f32_16x16x32_bf16 v[14:17], v[156:159], v[206:209], v[14:17]
	v_mfma_f32_16x16x32_bf16 v[38:41], v[130:133], v[210:213], v[38:41]
	v_mfma_f32_16x16x32_bf16 v[38:41], v[156:159], v[214:217], v[38:41]
	v_mfma_f32_16x16x32_bf16 v[70:73], v[130:133], v[218:221], v[70:73]
	v_mfma_f32_16x16x32_bf16 v[70:73], v[156:159], v[222:225], v[70:73]
	v_mfma_f32_16x16x32_bf16 v[94:97], v[130:133], v[226:229], v[94:97]
	v_mfma_f32_16x16x32_bf16 v[94:97], v[156:159], v[230:233], v[94:97]
	v_mfma_f32_16x16x32_bf16 v[90:93], v[168:171], v[226:229], v[90:93]
	v_mfma_f32_16x16x32_bf16 v[90:93], v[172:175], v[230:233], v[90:93]
	v_mfma_f32_16x16x32_bf16 v[66:69], v[168:171], v[218:221], v[66:69]
	v_mfma_f32_16x16x32_bf16 v[66:69], v[172:175], v[222:225], v[66:69]
	v_mfma_f32_16x16x32_bf16 v[34:37], v[168:171], v[210:213], v[34:37]
	v_mfma_f32_16x16x32_bf16 v[34:37], v[172:175], v[214:217], v[34:37]
	v_mfma_f32_16x16x32_bf16 v[10:13], v[168:171], v[202:205], v[10:13]
	v_mfma_f32_16x16x32_bf16 v[10:13], v[172:175], v[206:209], v[10:13]
	v_mfma_f32_16x16x32_bf16 v[30:33], v[180:183], v[202:205], v[30:33]
	v_mfma_f32_16x16x32_bf16 v[30:33], v[184:187], v[206:209], v[30:33]
	v_mfma_f32_16x16x32_bf16 v[54:57], v[180:183], v[210:213], v[54:57]
	v_mfma_f32_16x16x32_bf16 v[54:57], v[184:187], v[214:217], v[54:57]
	v_mfma_f32_16x16x32_bf16 v[86:89], v[180:183], v[218:221], v[86:89]
	v_mfma_f32_16x16x32_bf16 v[86:89], v[184:187], v[222:225], v[86:89]
	v_mfma_f32_16x16x32_bf16 v[110:113], v[180:183], v[226:229], v[110:113]
	v_mfma_f32_16x16x32_bf16 v[110:113], v[184:187], v[230:233], v[110:113]
	v_mfma_f32_16x16x32_bf16 v[106:109], v[188:191], v[226:229], v[106:109]
	v_mfma_f32_16x16x32_bf16 v[106:109], v[198:201], v[230:233], v[106:109]
	v_mfma_f32_16x16x32_bf16 v[82:85], v[188:191], v[218:221], v[82:85]
	v_mfma_f32_16x16x32_bf16 v[82:85], v[198:201], v[222:225], v[82:85]
	v_mfma_f32_16x16x32_bf16 v[50:53], v[188:191], v[210:213], v[50:53]
	v_mfma_f32_16x16x32_bf16 v[50:53], v[198:201], v[214:217], v[50:53]
	v_mfma_f32_16x16x32_bf16 v[26:29], v[188:191], v[202:205], v[26:29]
	v_mfma_f32_16x16x32_bf16 v[26:29], v[198:201], v[206:209], v[26:29]
	s_barrier
	s_mov_b32 m0, s85
	s_add_u32 s58, s70, 0x4000
	ds_read_b128 v[202:205], v165 offset:16384
	ds_read_b128 v[206:209], v165 offset:17408
	ds_read_b128 v[210:213], v165 offset:18432
	ds_read_b128 v[214:217], v165 offset:19456
	ds_read_b128 v[218:221], v165 offset:20480
	ds_read_b128 v[222:225], v165 offset:21504
	ds_read_b128 v[226:229], v165 offset:22528
	ds_read_b128 v[230:233], v165 offset:23552
	global_load_lds_dwordx4 v136, s[70:71]
	s_mov_b32 m0, s86
	s_addc_u32 s59, s71, 0
	global_load_lds_dwordx4 v140, s[70:71]
	s_mov_b32 m0, s87
	s_nop 0
	global_load_lds_dwordx4 v136, s[58:59]
	s_mov_b32 m0, s88
	s_nop 0
	global_load_lds_dwordx4 v140, s[58:59]
	s_mov_b32 m0, s29
	s_nop 0
	global_load_lds_dwordx4 v134, s[72:73]
	s_mov_b32 m0, s30
	s_nop 0
	global_load_lds_dwordx4 v138, s[72:73]
	s_waitcnt vmcnt(8)
	s_waitcnt lgkmcnt(0)
	s_barrier
	v_mfma_f32_16x16x32_bf16 v[126:129], v[130:133], v[202:205], v[126:129]
	v_mfma_f32_16x16x32_bf16 v[126:129], v[156:159], v[206:209], v[126:129]
	v_mfma_f32_16x16x32_bf16 v[102:105], v[130:133], v[210:213], v[102:105]
	v_mfma_f32_16x16x32_bf16 v[102:105], v[156:159], v[214:217], v[102:105]
	v_mfma_f32_16x16x32_bf16 v[62:65], v[130:133], v[218:221], v[62:65]
	v_mfma_f32_16x16x32_bf16 v[62:65], v[156:159], v[222:225], v[62:65]
	v_mfma_f32_16x16x32_bf16 v[22:25], v[130:133], v[226:229], v[22:25]
	v_mfma_f32_16x16x32_bf16 v[22:25], v[156:159], v[230:233], v[22:25]
	v_mfma_f32_16x16x32_bf16 v[18:21], v[168:171], v[226:229], v[18:21]
	v_mfma_f32_16x16x32_bf16 v[18:21], v[172:175], v[230:233], v[18:21]
	v_mfma_f32_16x16x32_bf16 v[58:61], v[168:171], v[218:221], v[58:61]
	v_mfma_f32_16x16x32_bf16 v[58:61], v[172:175], v[222:225], v[58:61]
	v_mfma_f32_16x16x32_bf16 v[98:101], v[168:171], v[210:213], v[98:101]
	v_mfma_f32_16x16x32_bf16 v[98:101], v[172:175], v[214:217], v[98:101]
	v_mfma_f32_16x16x32_bf16 v[122:125], v[168:171], v[202:205], v[122:125]
	v_mfma_f32_16x16x32_bf16 v[122:125], v[172:175], v[206:209], v[122:125]
	v_mfma_f32_16x16x32_bf16 v[118:121], v[180:183], v[202:205], v[118:121]
	v_mfma_f32_16x16x32_bf16 v[118:121], v[184:187], v[206:209], v[118:121]
	v_mfma_f32_16x16x32_bf16 v[78:81], v[180:183], v[210:213], v[78:81]
	v_mfma_f32_16x16x32_bf16 v[78:81], v[184:187], v[214:217], v[78:81]
	v_mfma_f32_16x16x32_bf16 v[46:49], v[180:183], v[218:221], v[46:49]
	v_mfma_f32_16x16x32_bf16 v[46:49], v[184:187], v[222:225], v[46:49]
	v_mfma_f32_16x16x32_bf16 v[6:9], v[180:183], v[226:229], v[6:9]
	v_mfma_f32_16x16x32_bf16 v[6:9], v[184:187], v[230:233], v[6:9]
	v_mfma_f32_16x16x32_bf16 v[2:5], v[188:191], v[226:229], v[2:5]
	v_mfma_f32_16x16x32_bf16 v[2:5], v[198:201], v[230:233], v[2:5]
	v_mfma_f32_16x16x32_bf16 v[42:45], v[188:191], v[218:221], v[42:45]
	v_mfma_f32_16x16x32_bf16 v[42:45], v[198:201], v[222:225], v[42:45]
	v_mfma_f32_16x16x32_bf16 v[74:77], v[188:191], v[210:213], v[74:77]
	v_mfma_f32_16x16x32_bf16 v[74:77], v[198:201], v[214:217], v[74:77]
	v_mfma_f32_16x16x32_bf16 v[114:117], v[188:191], v[202:205], v[114:117]
	v_mfma_f32_16x16x32_bf16 v[114:117], v[198:201], v[206:209], v[114:117]
	s_barrier
; #define PG8_STAGE(bufoff, gbase, voff) do { _Pragma("unroll") for (int _i = 0; _i < 2; ++_i) \
;         __builtin_amdgcn_global_load_lds((const unsigned*)((const char*)(gbase) + (voff)[_i]), (PG8_LAS unsigned*)(lds + (bufoff) + ldsw + _i * 8192), 16, 0, 0); } while (0)
; #define PG8_LDA(dst, b, h) do { _Pragma("unroll") for (int m = 0; m < 4; ++m) _Pragma("unroll") for (int k = 0; k < 2; ++k) dst[m][k] = *(const PG8_LAS bf16x8*)(lds + PG8_SA(b, h) + aoff + m * 2048 + k * 1024); } while (0)
; #define PG8_LDB(dst, b, h) do { _Pragma("unroll") for (int n = 0; n < 2; ++n) _Pragma("unroll") for (int k = 0; k < 2; ++k) dst[n][k] = *(const PG8_LAS bf16x8*)(lds + PG8_SB(b, h) + boff + n * 2048 + k * 1024); } while (0)
; #define PG8_MMA(ai, bj, At, Bt) do { __builtin_amdgcn_s_setprio(1); _Pragma("unroll") for (int m = 0; m < 4; ++m) _Pragma("unroll") for (int n = 0; n < 2; ++n) _Pragma("unroll") for (int k = 0; k < 2; ++k) \
;         acc[ai][bj][m][n] = __builtin_amdgcn_mfma_f32_16x16x32_bf16(Bt[n][k], At[m][k], acc[ai][bj][m][n], 0, 0, 0); __builtin_amdgcn_s_setprio(0); } while (0)
; #define PG8_WAIT_V(n) asm volatile("s_waitcnt vmcnt(" #n ")" ::: "memory")
; #define PG8_WAIT_L(n) asm volatile("s_waitcnt lgkmcnt(" #n ")" ::: "memory")
; #define PG8_BAR __builtin_amdgcn_s_barrier()
; #define PG8_SCHED __builtin_amdgcn_sched_barrier(0)
; template <class Epi, class Sched, bool ALIGN_EPI = false, bool SP2 = false>
; __device__ __forceinline__ void gemm_phase(PG8_LAS unsigned char* lds, const Gemm g, const Sched& S, const Epi& E) {
;     ...
;             PG8_LDB(B0, 1, 0); PG8_LDB(B1, 1, 1); PG8_SCHED; PG8_LDA(At, 1, 0); PG8_STAGE(PG8_SA(0, 1), a2 + hstep, voffA);
;             PG8_WAIT_V(8); PG8_WAIT_L(0); PG8_BAR; PG8_MMA(0, 0, At, B0); PG8_MMA(0, 1, At, B1); PG8_BAR; PG8_SCHED;
;             PG8_LDA(At, 1, 1); PG8_STAGE(PG8_SB(1, 0), b3, voffB); PG8_STAGE(PG8_SB(1, 1), b3 + hstep, voffB); PG8_STAGE(PG8_SA(1, 0), a3, voffA);
;             PG8_WAIT_V(8); PG8_WAIT_L(0); PG8_BAR; PG8_MMA(1, 0, At, B0); PG8_MMA(1, 1, At, B1); PG8_BAR; PG8_SCHED;
	ds_read_b128 v[130:133], v142
	ds_read_b128 v[156:159], v142 offset:1024
	ds_read_b128 v[168:171], v142 offset:2048
	ds_read_b128 v[172:175], v142 offset:3072
	ds_read_b128 v[180:183], v167
	ds_read_b128 v[184:187], v167 offset:1024
	ds_read_b128 v[188:191], v167 offset:2048
	ds_read_b128 v[198:201], v167 offset:3072
	s_add_u32 s58, s72, 0x4000
	s_addc_u32 s59, s73, 0
	s_mov_b32 m0, s31
	ds_read_b128 v[202:205], v165 offset:32768
	ds_read_b128 v[206:209], v165 offset:33792
	ds_read_b128 v[210:213], v165 offset:34816
	ds_read_b128 v[214:217], v165 offset:35840
	ds_read_b128 v[218:221], v165 offset:36864
	ds_read_b128 v[222:225], v165 offset:37888
	ds_read_b128 v[226:229], v165 offset:38912
	ds_read_b128 v[230:233], v165 offset:39936
	global_load_lds_dwordx4 v134, s[58:59]
	s_mov_b32 m0, s35
	s_nop 0
	global_load_lds_dwordx4 v138, s[58:59]
	s_waitcnt vmcnt(8)
	s_waitcnt lgkmcnt(0)
	s_barrier
	v_mfma_f32_16x16x32_bf16 v[14:17], v[130:133], v[202:205], v[14:17]
	v_mfma_f32_16x16x32_bf16 v[14:17], v[156:159], v[206:209], v[14:17]
	v_mfma_f32_16x16x32_bf16 v[38:41], v[130:133], v[210:213], v[38:41]
	v_mfma_f32_16x16x32_bf16 v[38:41], v[156:159], v[214:217], v[38:41]
	v_mfma_f32_16x16x32_bf16 v[70:73], v[130:133], v[218:221], v[70:73]
	v_mfma_f32_16x16x32_bf16 v[70:73], v[156:159], v[222:225], v[70:73]
	v_mfma_f32_16x16x32_bf16 v[94:97], v[130:133], v[226:229], v[94:97]
	v_mfma_f32_16x16x32_bf16 v[94:97], v[156:159], v[230:233], v[94:97]
	v_mfma_f32_16x16x32_bf16 v[90:93], v[168:171], v[226:229], v[90:93]
	v_mfma_f32_16x16x32_bf16 v[90:93], v[172:175], v[230:233], v[90:93]
	v_mfma_f32_16x16x32_bf16 v[66:69], v[168:171], v[218:221], v[66:69]
	v_mfma_f32_16x16x32_bf16 v[66:69], v[172:175], v[222:225], v[66:69]
	v_mfma_f32_16x16x32_bf16 v[34:37], v[168:171], v[210:213], v[34:37]
	v_mfma_f32_16x16x32_bf16 v[34:37], v[172:175], v[214:217], v[34:37]
	v_mfma_f32_16x16x32_bf16 v[10:13], v[168:171], v[202:205], v[10:13]
	v_mfma_f32_16x16x32_bf16 v[10:13], v[172:175], v[206:209], v[10:13]
	v_mfma_f32_16x16x32_bf16 v[30:33], v[180:183], v[202:205], v[30:33]
	v_mfma_f32_16x16x32_bf16 v[30:33], v[184:187], v[206:209], v[30:33]
	v_mfma_f32_16x16x32_bf16 v[54:57], v[180:183], v[210:213], v[54:57]
	v_mfma_f32_16x16x32_bf16 v[54:57], v[184:187], v[214:217], v[54:57]
	v_mfma_f32_16x16x32_bf16 v[86:89], v[180:183], v[218:221], v[86:89]
	v_mfma_f32_16x16x32_bf16 v[86:89], v[184:187], v[222:225], v[86:89]
	v_mfma_f32_16x16x32_bf16 v[110:113], v[180:183], v[226:229], v[110:113]
	v_mfma_f32_16x16x32_bf16 v[110:113], v[184:187], v[230:233], v[110:113]
	v_mfma_f32_16x16x32_bf16 v[106:109], v[188:191], v[226:229], v[106:109]
	v_mfma_f32_16x16x32_bf16 v[106:109], v[198:201], v[230:233], v[106:109]
	v_mfma_f32_16x16x32_bf16 v[82:85], v[188:191], v[218:221], v[82:85]
	v_mfma_f32_16x16x32_bf16 v[82:85], v[198:201], v[222:225], v[82:85]
	v_mfma_f32_16x16x32_bf16 v[50:53], v[188:191], v[210:213], v[50:53]
	v_mfma_f32_16x16x32_bf16 v[50:53], v[198:201], v[214:217], v[50:53]
	v_mfma_f32_16x16x32_bf16 v[26:29], v[188:191], v[202:205], v[26:29]
	v_mfma_f32_16x16x32_bf16 v[26:29], v[198:201], v[206:209], v[26:29]
	s_barrier
	s_add_u32 s58, s70, 0x8000
	s_addc_u32 s59, s71, 0
	s_mov_b32 m0, s89
	ds_read_b128 v[202:205], v165 offset:49152
	ds_read_b128 v[206:209], v165 offset:50176
	ds_read_b128 v[210:213], v165 offset:51200
	ds_read_b128 v[214:217], v165 offset:52224
	ds_read_b128 v[218:221], v165 offset:53248
	ds_read_b128 v[222:225], v165 offset:54272
	ds_read_b128 v[226:229], v165 offset:55296
	ds_read_b128 v[230:233], v165 offset:56320
	global_load_lds_dwordx4 v136, s[58:59]
	v_lshl_add_u64 v[176:177], s[58:59], 0, v[140:141]
	s_add_u32 s58, s70, 0xc000
	s_mov_b32 m0, s90
	s_addc_u32 s59, s71, 0
	global_load_lds_dwordx4 v[176:177], off
	s_mov_b32 m0, s91
	s_nop 0
	global_load_lds_dwordx4 v136, s[58:59]
	s_mov_b32 m0, s92
	s_nop 0
	global_load_lds_dwordx4 v140, s[58:59]
	s_mov_b32 m0, s75
	s_nop 0
	global_load_lds_dwordx4 v134, s[48:49]
	s_mov_b32 m0, s76
	s_nop 0
	global_load_lds_dwordx4 v138, s[48:49]
	s_waitcnt vmcnt(8)
	s_waitcnt lgkmcnt(0)
	s_barrier
	v_mfma_f32_16x16x32_bf16 v[126:129], v[130:133], v[202:205], v[126:129]
	v_mfma_f32_16x16x32_bf16 v[126:129], v[156:159], v[206:209], v[126:129]
	v_mfma_f32_16x16x32_bf16 v[102:105], v[130:133], v[210:213], v[102:105]
	v_mfma_f32_16x16x32_bf16 v[102:105], v[156:159], v[214:217], v[102:105]
	v_mfma_f32_16x16x32_bf16 v[62:65], v[130:133], v[218:221], v[62:65]
	v_mfma_f32_16x16x32_bf16 v[62:65], v[156:159], v[222:225], v[62:65]
	v_mfma_f32_16x16x32_bf16 v[22:25], v[130:133], v[226:229], v[22:25]
	v_mfma_f32_16x16x32_bf16 v[22:25], v[156:159], v[230:233], v[22:25]
	v_mfma_f32_16x16x32_bf16 v[18:21], v[168:171], v[226:229], v[18:21]
	v_mfma_f32_16x16x32_bf16 v[18:21], v[172:175], v[230:233], v[18:21]
	v_mfma_f32_16x16x32_bf16 v[58:61], v[168:171], v[218:221], v[58:61]
	v_mfma_f32_16x16x32_bf16 v[58:61], v[172:175], v[222:225], v[58:61]
	v_mfma_f32_16x16x32_bf16 v[98:101], v[168:171], v[210:213], v[98:101]
	v_mfma_f32_16x16x32_bf16 v[98:101], v[172:175], v[214:217], v[98:101]
	v_mfma_f32_16x16x32_bf16 v[122:125], v[168:171], v[202:205], v[122:125]
	v_mfma_f32_16x16x32_bf16 v[122:125], v[172:175], v[206:209], v[122:125]
	v_mfma_f32_16x16x32_bf16 v[118:121], v[180:183], v[202:205], v[118:121]
	v_mfma_f32_16x16x32_bf16 v[118:121], v[184:187], v[206:209], v[118:121]
	v_mfma_f32_16x16x32_bf16 v[78:81], v[180:183], v[210:213], v[78:81]
	v_mfma_f32_16x16x32_bf16 v[78:81], v[184:187], v[214:217], v[78:81]
	v_mfma_f32_16x16x32_bf16 v[46:49], v[180:183], v[218:221], v[46:49]
	v_mfma_f32_16x16x32_bf16 v[46:49], v[184:187], v[222:225], v[46:49]
	v_mfma_f32_16x16x32_bf16 v[6:9], v[180:183], v[226:229], v[6:9]
	v_mfma_f32_16x16x32_bf16 v[6:9], v[184:187], v[230:233], v[6:9]
	v_mfma_f32_16x16x32_bf16 v[2:5], v[188:191], v[226:229], v[2:5]
	v_mfma_f32_16x16x32_bf16 v[2:5], v[198:201], v[230:233], v[2:5]
	v_mfma_f32_16x16x32_bf16 v[42:45], v[188:191], v[218:221], v[42:45]
	v_mfma_f32_16x16x32_bf16 v[42:45], v[198:201], v[222:225], v[42:45]
	v_mfma_f32_16x16x32_bf16 v[74:77], v[188:191], v[210:213], v[74:77]
	v_mfma_f32_16x16x32_bf16 v[74:77], v[198:201], v[214:217], v[74:77]
	v_mfma_f32_16x16x32_bf16 v[114:117], v[188:191], v[202:205], v[114:117]
	v_mfma_f32_16x16x32_bf16 v[114:117], v[198:201], v[206:209], v[114:117]
	s_barrier
	s_add_i32 s56, s56, 2
	s_add_u32 s50, s50, 0x10000
	s_addc_u32 s51, s51, 0
	s_add_u32 s26, s26, 0x10000
	s_addc_u32 s33, s33, 0
	s_cmp_lt_u32 s56, 62
	s_cbranch_scc1 .LBB0_684
	s_andn2_b64 vcc, exec, s[12:13]
	s_cbranch_vccnz .LBB0_687
	s_barrier

; #define PG8_STAGE(bufoff, gbase, voff) do { _Pragma("unroll") for (int _i = 0; _i < 2; ++_i) \
;         __builtin_amdgcn_global_load_lds((const unsigned*)((const char*)(gbase) + (voff)[_i]), (PG8_LAS unsigned*)(lds + (bufoff) + ldsw + _i * 8192), 16, 0, 0); } while (0)
; #define PG8_LDA(dst, b, h) do { _Pragma("unroll") for (int m = 0; m < 4; ++m) _Pragma("unroll") for (int k = 0; k < 2; ++k) dst[m][k] = *(const PG8_LAS bf16x8*)(lds + PG8_SA(b, h) + aoff + m * 2048 + k * 1024); } while (0)
; #define PG8_LDB(dst, b, h) do { _Pragma("unroll") for (int n = 0; n < 2; ++n) _Pragma("unroll") for (int k = 0; k < 2; ++k) dst[n][k] = *(const PG8_LAS bf16x8*)(lds + PG8_SB(b, h) + boff + n * 2048 + k * 1024); } while (0)
; #define PG8_MMA(ai, bj, At, Bt) do { __builtin_amdgcn_s_setprio(1); _Pragma("unroll") for (int m = 0; m < 4; ++m) _Pragma("unroll") for (int n = 0; n < 2; ++n) _Pragma("unroll") for (int k = 0; k < 2; ++k) \
;         acc[ai][bj][m][n] = __builtin_amdgcn_mfma_f32_16x16x32_bf16(Bt[n][k], At[m][k], acc[ai][bj][m][n], 0, 0, 0); __builtin_amdgcn_s_setprio(0); } while (0)
; #define PG8_WAIT_V(n) asm volatile("s_waitcnt vmcnt(" #n ")" ::: "memory")
; #define PG8_WAIT_L(n) asm volatile("s_waitcnt lgkmcnt(" #n ")" ::: "memory")
; #define PG8_BAR __builtin_amdgcn_s_barrier()
; #define PG8_SCHED __builtin_amdgcn_sched_barrier(0)
; template <class Epi, class Sched, bool ALIGN_EPI = false, bool SP2 = false>
; __device__ __forceinline__ void gemm_phase(PG8_LAS unsigned char* lds, const Gemm g, const Sched& S, const Epi& E) {
;     ...
;             PG8_LDB(B0, 0, 0); PG8_LDB(B1, 0, 1); PG8_SCHED; PG8_LDA(At, 0, 0); PG8_STAGE(PG8_SA(1, 1), a1 + hstep, voffA);
;             PG8_WAIT_V(8); PG8_WAIT_L(0); PG8_BAR; PG8_MMA(0, 0, At, B0); PG8_MMA(0, 1, At, B1); PG8_BAR; PG8_SCHED;
;             PG8_LDA(At, 0, 1); PG8_STAGE(PG8_SB(0, 0), b2, voffB); PG8_STAGE(PG8_SB(0, 1), b2 + hstep, voffB); PG8_STAGE(PG8_SA(0, 0), a2, voffA);
;             PG8_WAIT_V(8); PG8_WAIT_L(0); PG8_BAR; PG8_MMA(1, 0, At, B0); PG8_MMA(1, 1, At, B1); PG8_BAR; PG8_SCHED;
.LBB0_757:
	ds_read_b128 v[154:157], v149
	ds_read_b128 v[158:161], v149 offset:1024
	ds_read_b128 v[162:165], v149 offset:2048
	ds_read_b128 v[166:169], v149 offset:3072
	ds_read_b128 v[170:173], v150
	ds_read_b128 v[174:177], v150 offset:1024
	ds_read_b128 v[180:183], v150 offset:2048
	ds_read_b128 v[184:187], v150 offset:3072
	s_add_u32 s46, s44, 0x4000
	s_addc_u32 s47, s45, 0
	s_cmp_eq_u32 s70, 60
	s_cselect_b32 s50, s39, s46
	s_cselect_b32 s51, s17, s47
	s_cselect_b32 s48, s41, s68
	s_cselect_b32 s49, s15, s69
	s_add_u32 s46, s50, 0x8000
	s_addc_u32 s47, s51, 0
	s_sub_u32 s46, s44, 0x4000
	s_subb_u32 s47, s45, 0
	s_mov_b32 m0, s57
	s_nop 0
	global_load_lds_dwordx4 v130, s[46:47]
	s_mov_b32 m0, s58
	s_nop 0
	global_load_lds_dwordx4 v134, s[46:47]
	s_add_i32 m0, s26, 0xc000
	ds_read_b128 v[188:191], v151
	ds_read_b128 v[198:201], v151 offset:1024
	ds_read_b128 v[202:205], v151 offset:2048
	ds_read_b128 v[206:209], v151 offset:3072
	ds_read_b128 v[210:213], v151 offset:4096
	ds_read_b128 v[214:217], v151 offset:5120
	ds_read_b128 v[218:221], v151 offset:6144
	ds_read_b128 v[222:225], v151 offset:7168
	global_load_lds_dwordx4 v138, s[44:45]
	s_add_i32 m0, s26, 0xe000
	s_nop 0
	global_load_lds_dwordx4 v140, s[44:45]
	s_waitcnt vmcnt(8)
	s_waitcnt lgkmcnt(0)
	s_barrier
	v_mfma_f32_16x16x32_bf16 v[126:129], v[154:157], v[188:191], v[126:129]
	v_mfma_f32_16x16x32_bf16 v[126:129], v[158:161], v[198:201], v[126:129]
	v_mfma_f32_16x16x32_bf16 v[110:113], v[154:157], v[202:205], v[110:113]
	v_mfma_f32_16x16x32_bf16 v[110:113], v[158:161], v[206:209], v[110:113]
	v_mfma_f32_16x16x32_bf16 v[94:97], v[154:157], v[210:213], v[94:97]
	v_mfma_f32_16x16x32_bf16 v[94:97], v[158:161], v[214:217], v[94:97]
	v_mfma_f32_16x16x32_bf16 v[78:81], v[154:157], v[218:221], v[78:81]
	v_mfma_f32_16x16x32_bf16 v[78:81], v[158:161], v[222:225], v[78:81]
	v_mfma_f32_16x16x32_bf16 v[74:77], v[162:165], v[218:221], v[74:77]
	v_mfma_f32_16x16x32_bf16 v[74:77], v[166:169], v[222:225], v[74:77]
	v_mfma_f32_16x16x32_bf16 v[90:93], v[162:165], v[210:213], v[90:93]
	v_mfma_f32_16x16x32_bf16 v[90:93], v[166:169], v[214:217], v[90:93]
	v_mfma_f32_16x16x32_bf16 v[106:109], v[162:165], v[202:205], v[106:109]
	v_mfma_f32_16x16x32_bf16 v[106:109], v[166:169], v[206:209], v[106:109]
	v_mfma_f32_16x16x32_bf16 v[122:125], v[162:165], v[188:191], v[122:125]
	v_mfma_f32_16x16x32_bf16 v[122:125], v[166:169], v[198:201], v[122:125]
	v_mfma_f32_16x16x32_bf16 v[118:121], v[170:173], v[188:191], v[118:121]
	v_mfma_f32_16x16x32_bf16 v[118:121], v[174:177], v[198:201], v[118:121]
	v_mfma_f32_16x16x32_bf16 v[102:105], v[170:173], v[202:205], v[102:105]
	v_mfma_f32_16x16x32_bf16 v[102:105], v[174:177], v[206:209], v[102:105]
	v_mfma_f32_16x16x32_bf16 v[86:89], v[170:173], v[210:213], v[86:89]
	v_mfma_f32_16x16x32_bf16 v[86:89], v[174:177], v[214:217], v[86:89]
	v_mfma_f32_16x16x32_bf16 v[70:73], v[170:173], v[218:221], v[70:73]
	v_mfma_f32_16x16x32_bf16 v[70:73], v[174:177], v[222:225], v[70:73]
	v_mfma_f32_16x16x32_bf16 v[66:69], v[180:183], v[218:221], v[66:69]
	v_mfma_f32_16x16x32_bf16 v[66:69], v[184:187], v[222:225], v[66:69]
	v_mfma_f32_16x16x32_bf16 v[82:85], v[180:183], v[210:213], v[82:85]
	v_mfma_f32_16x16x32_bf16 v[82:85], v[184:187], v[214:217], v[82:85]
	v_mfma_f32_16x16x32_bf16 v[98:101], v[180:183], v[202:205], v[98:101]
	v_mfma_f32_16x16x32_bf16 v[98:101], v[184:187], v[206:209], v[98:101]
	v_mfma_f32_16x16x32_bf16 v[114:117], v[180:183], v[188:191], v[114:117]
	v_mfma_f32_16x16x32_bf16 v[114:117], v[184:187], v[198:201], v[114:117]
	s_barrier
	s_add_i32 s71, s59, s3
	s_mov_b32 m0, s71
	ds_read_b128 v[188:191], v151 offset:16384
	ds_read_b128 v[198:201], v151 offset:17408
	ds_read_b128 v[202:205], v151 offset:18432
	ds_read_b128 v[206:209], v151 offset:19456
	ds_read_b128 v[210:213], v151 offset:20480
	ds_read_b128 v[214:217], v151 offset:21504
	ds_read_b128 v[218:221], v151 offset:22528
	ds_read_b128 v[222:225], v151 offset:23552
	global_load_lds_dwordx4 v132, s[48:49]
	s_add_i32 m0, s71, 0x2000
	s_add_u32 s72, s48, 0x4000
	s_addc_u32 s73, s49, 0
	s_add_i32 s71, s61, s3
	global_load_lds_dwordx4 v136, s[48:49]
	s_mov_b32 m0, s71
	s_nop 0
	global_load_lds_dwordx4 v132, s[72:73]
	s_add_i32 m0, s71, 0x2000
	s_nop 0
	global_load_lds_dwordx4 v136, s[72:73]
	s_waitcnt vmcnt(6)
	s_waitcnt lgkmcnt(0)
	s_barrier
	v_mfma_f32_16x16x32_bf16 v[62:65], v[154:157], v[188:191], v[62:65]
	v_mfma_f32_16x16x32_bf16 v[62:65], v[158:161], v[198:201], v[62:65]
	v_mfma_f32_16x16x32_bf16 v[46:49], v[154:157], v[202:205], v[46:49]
	v_mfma_f32_16x16x32_bf16 v[46:49], v[158:161], v[206:209], v[46:49]
	v_mfma_f32_16x16x32_bf16 v[30:33], v[154:157], v[210:213], v[30:33]
	v_mfma_f32_16x16x32_bf16 v[30:33], v[158:161], v[214:217], v[30:33]
	v_mfma_f32_16x16x32_bf16 v[14:17], v[154:157], v[218:221], v[14:17]
	v_mfma_f32_16x16x32_bf16 v[14:17], v[158:161], v[222:225], v[14:17]
	v_mfma_f32_16x16x32_bf16 v[10:13], v[162:165], v[218:221], v[10:13]
	v_mfma_f32_16x16x32_bf16 v[10:13], v[166:169], v[222:225], v[10:13]
	v_mfma_f32_16x16x32_bf16 v[26:29], v[162:165], v[210:213], v[26:29]
	v_mfma_f32_16x16x32_bf16 v[26:29], v[166:169], v[214:217], v[26:29]
	v_mfma_f32_16x16x32_bf16 v[42:45], v[162:165], v[202:205], v[42:45]
	v_mfma_f32_16x16x32_bf16 v[42:45], v[166:169], v[206:209], v[42:45]
	v_mfma_f32_16x16x32_bf16 v[58:61], v[162:165], v[188:191], v[58:61]
	v_mfma_f32_16x16x32_bf16 v[58:61], v[166:169], v[198:201], v[58:61]
	v_mfma_f32_16x16x32_bf16 v[54:57], v[170:173], v[188:191], v[54:57]
	v_mfma_f32_16x16x32_bf16 v[54:57], v[174:177], v[198:201], v[54:57]
	v_mfma_f32_16x16x32_bf16 v[38:41], v[170:173], v[202:205], v[38:41]
	v_mfma_f32_16x16x32_bf16 v[38:41], v[174:177], v[206:209], v[38:41]
	v_mfma_f32_16x16x32_bf16 v[22:25], v[170:173], v[210:213], v[22:25]
	v_mfma_f32_16x16x32_bf16 v[22:25], v[174:177], v[214:217], v[22:25]
	v_mfma_f32_16x16x32_bf16 v[6:9], v[170:173], v[218:221], v[6:9]
	v_mfma_f32_16x16x32_bf16 v[6:9], v[174:177], v[222:225], v[6:9]
	v_mfma_f32_16x16x32_bf16 v[2:5], v[180:183], v[218:221], v[2:5]
	v_mfma_f32_16x16x32_bf16 v[2:5], v[184:187], v[222:225], v[2:5]
	v_mfma_f32_16x16x32_bf16 v[18:21], v[180:183], v[210:213], v[18:21]
	v_mfma_f32_16x16x32_bf16 v[18:21], v[184:187], v[214:217], v[18:21]
	v_mfma_f32_16x16x32_bf16 v[34:37], v[180:183], v[202:205], v[34:37]
	v_mfma_f32_16x16x32_bf16 v[34:37], v[184:187], v[206:209], v[34:37]
	v_mfma_f32_16x16x32_bf16 v[50:53], v[180:183], v[188:191], v[50:53]
	v_mfma_f32_16x16x32_bf16 v[50:53], v[184:187], v[198:201], v[50:53]
	s_barrier
; #define PG8_STAGE(bufoff, gbase, voff) do { _Pragma("unroll") for (int _i = 0; _i < 2; ++_i) \
;         __builtin_amdgcn_global_load_lds((const unsigned*)((const char*)(gbase) + (voff)[_i]), (PG8_LAS unsigned*)(lds + (bufoff) + ldsw + _i * 8192), 16, 0, 0); } while (0)
; #define PG8_LDA(dst, b, h) do { _Pragma("unroll") for (int m = 0; m < 4; ++m) _Pragma("unroll") for (int k = 0; k < 2; ++k) dst[m][k] = *(const PG8_LAS bf16x8*)(lds + PG8_SA(b, h) + aoff + m * 2048 + k * 1024); } while (0)
; #define PG8_LDB(dst, b, h) do { _Pragma("unroll") for (int n = 0; n < 2; ++n) _Pragma("unroll") for (int k = 0; k < 2; ++k) dst[n][k] = *(const PG8_LAS bf16x8*)(lds + PG8_SB(b, h) + boff + n * 2048 + k * 1024); } while (0)
; #define PG8_MMA(ai, bj, At, Bt) do { __builtin_amdgcn_s_setprio(1); _Pragma("unroll") for (int m = 0; m < 4; ++m) _Pragma("unroll") for (int n = 0; n < 2; ++n) _Pragma("unroll") for (int k = 0; k < 2; ++k) \
;         acc[ai][bj][m][n] = __builtin_amdgcn_mfma_f32_16x16x32_bf16(Bt[n][k], At[m][k], acc[ai][bj][m][n], 0, 0, 0); __builtin_amdgcn_s_setprio(0); } while (0)
; #define PG8_WAIT_V(n) asm volatile("s_waitcnt vmcnt(" #n ")" ::: "memory")
; #define PG8_WAIT_L(n) asm volatile("s_waitcnt lgkmcnt(" #n ")" ::: "memory")
; #define PG8_BAR __builtin_amdgcn_s_barrier()
; #define PG8_SCHED __builtin_amdgcn_sched_barrier(0)
; template <class Epi, class Sched, bool ALIGN_EPI = false, bool SP2 = false>
; __device__ __forceinline__ void gemm_phase(PG8_LAS unsigned char* lds, const Gemm g, const Sched& S, const Epi& E) {
;     ...
;             PG8_LDB(B0, 1, 0); PG8_LDB(B1, 1, 1); PG8_SCHED; PG8_LDA(At, 1, 0); PG8_STAGE(PG8_SA(0, 1), a2 + hstep, voffA);
;             PG8_WAIT_V(8); PG8_WAIT_L(0); PG8_BAR; PG8_MMA(0, 0, At, B0); PG8_MMA(0, 1, At, B1); PG8_BAR; PG8_SCHED;
;             PG8_LDA(At, 1, 1); PG8_STAGE(PG8_SB(1, 0), b3, voffB); PG8_STAGE(PG8_SB(1, 1), b3 + hstep, voffB); PG8_STAGE(PG8_SA(1, 0), a3, voffA);
;             PG8_WAIT_V(8); PG8_WAIT_L(0); PG8_BAR; PG8_MMA(1, 0, At, B0); PG8_MMA(1, 1, At, B1); PG8_BAR; PG8_SCHED;
	s_add_i32 s71, 0, 0x18000
	v_add_u32_e32 v146, s71, v1
	s_add_i32 s72, 0, 0x1c000
	ds_read_b128 v[154:157], v146
	ds_read_b128 v[158:161], v146 offset:1024
	ds_read_b128 v[162:165], v146 offset:2048
	ds_read_b128 v[166:169], v146 offset:3072
	v_add_u32_e32 v146, s72, v1
	ds_read_b128 v[170:173], v146
	ds_read_b128 v[174:177], v146 offset:1024
	ds_read_b128 v[180:183], v146 offset:2048
	ds_read_b128 v[184:187], v146 offset:3072
	s_mov_b32 m0, s26
	s_nop 0
	global_load_lds_dwordx4 v130, s[50:51]
	s_mov_b32 m0, s27
	s_nop 0
	global_load_lds_dwordx4 v134, s[50:51]
	s_add_u32 s50, s50, 0x4000
	s_addc_u32 s51, s51, 0
	s_mov_b32 m0, s28
	ds_read_b128 v[188:191], v151 offset:32768
	ds_read_b128 v[198:201], v151 offset:33792
	ds_read_b128 v[202:205], v151 offset:34816
	ds_read_b128 v[206:209], v151 offset:35840
	ds_read_b128 v[210:213], v151 offset:36864
	ds_read_b128 v[214:217], v151 offset:37888
	ds_read_b128 v[218:221], v151 offset:38912
	ds_read_b128 v[222:225], v151 offset:39936
	global_load_lds_dwordx4 v130, s[50:51]
	s_mov_b32 m0, s29
	s_nop 0
	global_load_lds_dwordx4 v134, s[50:51]
	s_waitcnt vmcnt(8)
	s_waitcnt lgkmcnt(0)
	s_barrier
	v_mfma_f32_16x16x32_bf16 v[126:129], v[154:157], v[188:191], v[126:129]
	v_mfma_f32_16x16x32_bf16 v[126:129], v[158:161], v[198:201], v[126:129]
	v_mfma_f32_16x16x32_bf16 v[110:113], v[154:157], v[202:205], v[110:113]
	v_mfma_f32_16x16x32_bf16 v[110:113], v[158:161], v[206:209], v[110:113]
	v_mfma_f32_16x16x32_bf16 v[94:97], v[154:157], v[210:213], v[94:97]
	v_mfma_f32_16x16x32_bf16 v[94:97], v[158:161], v[214:217], v[94:97]
	v_mfma_f32_16x16x32_bf16 v[78:81], v[154:157], v[218:221], v[78:81]
	v_mfma_f32_16x16x32_bf16 v[78:81], v[158:161], v[222:225], v[78:81]
	v_mfma_f32_16x16x32_bf16 v[74:77], v[162:165], v[218:221], v[74:77]
	v_mfma_f32_16x16x32_bf16 v[74:77], v[166:169], v[222:225], v[74:77]
	v_mfma_f32_16x16x32_bf16 v[90:93], v[162:165], v[210:213], v[90:93]
	v_mfma_f32_16x16x32_bf16 v[90:93], v[166:169], v[214:217], v[90:93]
	v_mfma_f32_16x16x32_bf16 v[106:109], v[162:165], v[202:205], v[106:109]
	v_mfma_f32_16x16x32_bf16 v[106:109], v[166:169], v[206:209], v[106:109]
	v_mfma_f32_16x16x32_bf16 v[122:125], v[162:165], v[188:191], v[122:125]
	v_mfma_f32_16x16x32_bf16 v[122:125], v[166:169], v[198:201], v[122:125]
	v_mfma_f32_16x16x32_bf16 v[118:121], v[170:173], v[188:191], v[118:121]
	v_mfma_f32_16x16x32_bf16 v[118:121], v[174:177], v[198:201], v[118:121]
	v_mfma_f32_16x16x32_bf16 v[102:105], v[170:173], v[202:205], v[102:105]
	v_mfma_f32_16x16x32_bf16 v[102:105], v[174:177], v[206:209], v[102:105]
	v_mfma_f32_16x16x32_bf16 v[86:89], v[170:173], v[210:213], v[86:89]
	v_mfma_f32_16x16x32_bf16 v[86:89], v[174:177], v[214:217], v[86:89]
	v_mfma_f32_16x16x32_bf16 v[70:73], v[170:173], v[218:221], v[70:73]
	v_mfma_f32_16x16x32_bf16 v[70:73], v[174:177], v[222:225], v[70:73]
	v_mfma_f32_16x16x32_bf16 v[66:69], v[180:183], v[218:221], v[66:69]
	v_mfma_f32_16x16x32_bf16 v[66:69], v[184:187], v[222:225], v[66:69]
	v_mfma_f32_16x16x32_bf16 v[82:85], v[180:183], v[210:213], v[82:85]
	v_mfma_f32_16x16x32_bf16 v[82:85], v[184:187], v[214:217], v[82:85]
	v_mfma_f32_16x16x32_bf16 v[98:101], v[180:183], v[202:205], v[98:101]
	v_mfma_f32_16x16x32_bf16 v[98:101], v[184:187], v[206:209], v[98:101]
	v_mfma_f32_16x16x32_bf16 v[114:117], v[180:183], v[188:191], v[114:117]
	v_mfma_f32_16x16x32_bf16 v[114:117], v[184:187], v[198:201], v[114:117]
	s_barrier
	s_add_u32 s50, s48, 0x8000
	s_addc_u32 s51, s49, 0
	s_add_i32 s71, s71, s3
	s_mov_b32 m0, s71
	ds_read_b128 v[188:191], v151 offset:49152
	ds_read_b128 v[198:201], v151 offset:50176
	ds_read_b128 v[202:205], v151 offset:51200
	ds_read_b128 v[206:209], v151 offset:52224
	ds_read_b128 v[210:213], v151 offset:53248
	ds_read_b128 v[214:217], v151 offset:54272
	ds_read_b128 v[218:221], v151 offset:55296
	ds_read_b128 v[222:225], v151 offset:56320
	global_load_lds_dwordx4 v132, s[50:51]
	s_add_i32 m0, s71, 0x2000
	s_add_u32 s48, s48, 0xc000
	v_lshl_add_u64 v[146:147], s[50:51], 0, v[136:137]
	s_addc_u32 s49, s49, 0
	s_add_i32 s50, s72, s3
	global_load_lds_dwordx4 v[146:147], off
	s_mov_b32 m0, s50
	s_nop 0
	global_load_lds_dwordx4 v132, s[48:49]
	s_add_i32 m0, s50, 0x2000
	s_nop 0
	global_load_lds_dwordx4 v136, s[48:49]
	s_waitcnt vmcnt(6)
	s_waitcnt lgkmcnt(0)
	s_barrier
	v_mfma_f32_16x16x32_bf16 v[62:65], v[154:157], v[188:191], v[62:65]
	v_mfma_f32_16x16x32_bf16 v[62:65], v[158:161], v[198:201], v[62:65]
	v_mfma_f32_16x16x32_bf16 v[46:49], v[154:157], v[202:205], v[46:49]
	v_mfma_f32_16x16x32_bf16 v[46:49], v[158:161], v[206:209], v[46:49]
	v_mfma_f32_16x16x32_bf16 v[30:33], v[154:157], v[210:213], v[30:33]
	v_mfma_f32_16x16x32_bf16 v[30:33], v[158:161], v[214:217], v[30:33]
	v_mfma_f32_16x16x32_bf16 v[14:17], v[154:157], v[218:221], v[14:17]
	v_mfma_f32_16x16x32_bf16 v[14:17], v[158:161], v[222:225], v[14:17]
	v_mfma_f32_16x16x32_bf16 v[10:13], v[162:165], v[218:221], v[10:13]
	v_mfma_f32_16x16x32_bf16 v[10:13], v[166:169], v[222:225], v[10:13]
	v_mfma_f32_16x16x32_bf16 v[26:29], v[162:165], v[210:213], v[26:29]
	v_mfma_f32_16x16x32_bf16 v[26:29], v[166:169], v[214:217], v[26:29]
	v_mfma_f32_16x16x32_bf16 v[42:45], v[162:165], v[202:205], v[42:45]
	v_mfma_f32_16x16x32_bf16 v[42:45], v[166:169], v[206:209], v[42:45]
	v_mfma_f32_16x16x32_bf16 v[58:61], v[162:165], v[188:191], v[58:61]
	v_mfma_f32_16x16x32_bf16 v[58:61], v[166:169], v[198:201], v[58:61]
	v_mfma_f32_16x16x32_bf16 v[54:57], v[170:173], v[188:191], v[54:57]
	v_mfma_f32_16x16x32_bf16 v[54:57], v[174:177], v[198:201], v[54:57]
	v_mfma_f32_16x16x32_bf16 v[38:41], v[170:173], v[202:205], v[38:41]
	v_mfma_f32_16x16x32_bf16 v[38:41], v[174:177], v[206:209], v[38:41]
	v_mfma_f32_16x16x32_bf16 v[22:25], v[170:173], v[210:213], v[22:25]
	v_mfma_f32_16x16x32_bf16 v[22:25], v[174:177], v[214:217], v[22:25]
	v_mfma_f32_16x16x32_bf16 v[6:9], v[170:173], v[218:221], v[6:9]
	v_mfma_f32_16x16x32_bf16 v[6:9], v[174:177], v[222:225], v[6:9]
	v_mfma_f32_16x16x32_bf16 v[2:5], v[180:183], v[218:221], v[2:5]
	v_mfma_f32_16x16x32_bf16 v[2:5], v[184:187], v[222:225], v[2:5]
	v_mfma_f32_16x16x32_bf16 v[18:21], v[180:183], v[210:213], v[18:21]
	v_mfma_f32_16x16x32_bf16 v[18:21], v[184:187], v[214:217], v[18:21]
	v_mfma_f32_16x16x32_bf16 v[34:37], v[180:183], v[202:205], v[34:37]
	v_mfma_f32_16x16x32_bf16 v[34:37], v[184:187], v[206:209], v[34:37]
	v_mfma_f32_16x16x32_bf16 v[50:53], v[180:183], v[188:191], v[50:53]
	v_mfma_f32_16x16x32_bf16 v[50:53], v[184:187], v[198:201], v[50:53]
	s_barrier
	s_add_i32 s70, s70, 2
	s_add_u32 s44, s44, 0x10000
	s_addc_u32 s45, s45, 0
	s_add_u32 s68, s68, 0x10000
	s_addc_u32 s69, s69, 0
	s_cmp_gt_u32 s70, 61
	s_cbranch_scc0 .LBB0_757
	s_and_b64 vcc, exec, s[12:13]
	s_cbranch_vccz .LBB0_760
	s_barrier

; #define PG8_STAGE(bufoff, gbase, voff) do { _Pragma("unroll") for (int _i = 0; _i < 2; ++_i) \
;         __builtin_amdgcn_global_load_lds((const unsigned*)((const char*)(gbase) + (voff)[_i]), (PG8_LAS unsigned*)(lds + (bufoff) + ldsw + _i * 8192), 16, 0, 0); } while (0)
; #define PG8_LDA(dst, b, h) do { _Pragma("unroll") for (int m = 0; m < 4; ++m) _Pragma("unroll") for (int k = 0; k < 2; ++k) dst[m][k] = *(const PG8_LAS bf16x8*)(lds + PG8_SA(b, h) + aoff + m * 2048 + k * 1024); } while (0)
; #define PG8_LDB(dst, b, h) do { _Pragma("unroll") for (int n = 0; n < 2; ++n) _Pragma("unroll") for (int k = 0; k < 2; ++k) dst[n][k] = *(const PG8_LAS bf16x8*)(lds + PG8_SB(b, h) + boff + n * 2048 + k * 1024); } while (0)
; #define PG8_MMA(ai, bj, At, Bt) do { __builtin_amdgcn_s_setprio(1); _Pragma("unroll") for (int m = 0; m < 4; ++m) _Pragma("unroll") for (int n = 0; n < 2; ++n) _Pragma("unroll") for (int k = 0; k < 2; ++k) \
;         acc[ai][bj][m][n] = __builtin_amdgcn_mfma_f32_16x16x32_bf16(Bt[n][k], At[m][k], acc[ai][bj][m][n], 0, 0, 0); __builtin_amdgcn_s_setprio(0); } while (0)
; #define PG8_WAIT_V(n) asm volatile("s_waitcnt vmcnt(" #n ")" ::: "memory")
; #define PG8_WAIT_L(n) asm volatile("s_waitcnt lgkmcnt(" #n ")" ::: "memory")
; #define PG8_BAR __builtin_amdgcn_s_barrier()
; template <class Epi, class Sched, bool ALIGN_EPI = false, bool SP2 = false>
; __device__ __forceinline__ void gemm_phase(PG8_LAS unsigned char* lds, const Gemm g, const Sched& S, const Epi& E) {
;     ...
;             const char* a1 = cA + (size_t)(t + 1) * kstep;
;             const char* a2 = last ? nA : cA + (size_t)(t + 2) * kstep; const char* b2 = last ? nB : cB + (size_t)(t + 2) * kstep;
;             const char* a3 = a2 + kstep; const char* b3 = b2 + kstep;
;             if (last && has_next) S.a_ready(nxt);
;             if constexpr (SP2) {
;             PG8_LDB(B0, 0, 0); PG8_LDB(B1, 0, 1); PG8_SCHED; PG8_LDA(At, 0, 0); PG8_STAGE(PG8_SA(1, 1), a1 + hstep, voffA);
;             PG8_WAIT_V(8); PG8_WAIT_L(0); PG8_BAR; PG8_MMA(0, 0, At, B0); PG8_MMA(0, 1, At, B1); PG8_BAR; PG8_SCHED;
;             PG8_LDA(At, 0, 1); PG8_STAGE(PG8_SB(0, 0), b2, voffB); PG8_STAGE(PG8_SB(0, 1), b2 + hstep, voffB); PG8_STAGE(PG8_SA(0, 0), a2, voffA);
;             PG8_WAIT_V(8); PG8_WAIT_L(0); PG8_BAR; PG8_MMA(1, 0, At, B0); PG8_MMA(1, 1, At, B1); PG8_BAR; PG8_SCHED;
.LBB0_840:
	ds_read_b128 v[148:151], v153
	ds_read_b128 v[158:161], v153 offset:1024
	ds_read_b128 v[162:165], v153 offset:2048
	ds_read_b128 v[166:169], v153 offset:3072
	ds_read_b128 v[170:173], v154
	ds_read_b128 v[174:177], v154 offset:1024
	ds_read_b128 v[180:183], v154 offset:2048
	ds_read_b128 v[184:187], v154 offset:3072
	s_add_u32 s42, s40, 0x4000
	s_addc_u32 s43, s41, 0
	s_cmp_eq_u32 s69, 60
	s_cselect_b32 s46, s65, s42
	s_cselect_b32 s47, s23, s43
	s_cselect_b32 s44, s66, s67
	s_cselect_b32 s45, s17, s68
	s_add_u32 s42, s46, 0x8000
	s_addc_u32 s43, s47, 0
	s_sub_u32 s42, s40, 0x4000
	s_subb_u32 s43, s41, 0
	s_mov_b32 m0, s50
	s_nop 0
	global_load_lds_dwordx4 v130, s[42:43]
	s_mov_b32 m0, s51
	s_nop 0
	global_load_lds_dwordx4 v134, s[42:43]
	s_add_i32 m0, s28, 0xc000
	ds_read_b128 v[188:191], v155
	ds_read_b128 v[198:201], v155 offset:1024
	ds_read_b128 v[202:205], v155 offset:2048
	ds_read_b128 v[206:209], v155 offset:3072
	ds_read_b128 v[210:213], v155 offset:4096
	ds_read_b128 v[214:217], v155 offset:5120
	ds_read_b128 v[218:221], v155 offset:6144
	ds_read_b128 v[222:225], v155 offset:7168
	global_load_lds_dwordx4 v140, s[40:41]
	s_add_i32 m0, s28, 0xe000
	s_nop 0
	global_load_lds_dwordx4 v142, s[40:41]
	s_waitcnt vmcnt(8)
	s_waitcnt lgkmcnt(0)
	s_barrier
	v_mfma_f32_16x16x32_bf16 v[126:129], v[148:151], v[188:191], v[126:129]
	v_mfma_f32_16x16x32_bf16 v[126:129], v[158:161], v[198:201], v[126:129]
	v_mfma_f32_16x16x32_bf16 v[110:113], v[148:151], v[202:205], v[110:113]
	v_mfma_f32_16x16x32_bf16 v[110:113], v[158:161], v[206:209], v[110:113]
	v_mfma_f32_16x16x32_bf16 v[94:97], v[148:151], v[210:213], v[94:97]
	v_mfma_f32_16x16x32_bf16 v[94:97], v[158:161], v[214:217], v[94:97]
	v_mfma_f32_16x16x32_bf16 v[78:81], v[148:151], v[218:221], v[78:81]
	v_mfma_f32_16x16x32_bf16 v[78:81], v[158:161], v[222:225], v[78:81]
	v_mfma_f32_16x16x32_bf16 v[74:77], v[162:165], v[218:221], v[74:77]
	v_mfma_f32_16x16x32_bf16 v[74:77], v[166:169], v[222:225], v[74:77]
	v_mfma_f32_16x16x32_bf16 v[90:93], v[162:165], v[210:213], v[90:93]
	v_mfma_f32_16x16x32_bf16 v[90:93], v[166:169], v[214:217], v[90:93]
	v_mfma_f32_16x16x32_bf16 v[106:109], v[162:165], v[202:205], v[106:109]
	v_mfma_f32_16x16x32_bf16 v[106:109], v[166:169], v[206:209], v[106:109]
	v_mfma_f32_16x16x32_bf16 v[122:125], v[162:165], v[188:191], v[122:125]
	v_mfma_f32_16x16x32_bf16 v[122:125], v[166:169], v[198:201], v[122:125]
	v_mfma_f32_16x16x32_bf16 v[118:121], v[170:173], v[188:191], v[118:121]
	v_mfma_f32_16x16x32_bf16 v[118:121], v[174:177], v[198:201], v[118:121]
	v_mfma_f32_16x16x32_bf16 v[102:105], v[170:173], v[202:205], v[102:105]
	v_mfma_f32_16x16x32_bf16 v[102:105], v[174:177], v[206:209], v[102:105]
	v_mfma_f32_16x16x32_bf16 v[86:89], v[170:173], v[210:213], v[86:89]
	v_mfma_f32_16x16x32_bf16 v[86:89], v[174:177], v[214:217], v[86:89]
	v_mfma_f32_16x16x32_bf16 v[70:73], v[170:173], v[218:221], v[70:73]
	v_mfma_f32_16x16x32_bf16 v[70:73], v[174:177], v[222:225], v[70:73]
	v_mfma_f32_16x16x32_bf16 v[66:69], v[180:183], v[218:221], v[66:69]
	v_mfma_f32_16x16x32_bf16 v[66:69], v[184:187], v[222:225], v[66:69]
	v_mfma_f32_16x16x32_bf16 v[82:85], v[180:183], v[210:213], v[82:85]
	v_mfma_f32_16x16x32_bf16 v[82:85], v[184:187], v[214:217], v[82:85]
	v_mfma_f32_16x16x32_bf16 v[98:101], v[180:183], v[202:205], v[98:101]
	v_mfma_f32_16x16x32_bf16 v[98:101], v[184:187], v[206:209], v[98:101]
	v_mfma_f32_16x16x32_bf16 v[114:117], v[180:183], v[188:191], v[114:117]
	v_mfma_f32_16x16x32_bf16 v[114:117], v[184:187], v[198:201], v[114:117]
	s_barrier
	s_add_i32 s70, s56, s3
	s_mov_b32 m0, s70
	ds_read_b128 v[188:191], v155 offset:16384
	ds_read_b128 v[198:201], v155 offset:17408
	ds_read_b128 v[202:205], v155 offset:18432
	ds_read_b128 v[206:209], v155 offset:19456
	ds_read_b128 v[210:213], v155 offset:20480
	ds_read_b128 v[214:217], v155 offset:21504
	ds_read_b128 v[218:221], v155 offset:22528
	ds_read_b128 v[222:225], v155 offset:23552
	global_load_lds_dwordx4 v132, s[44:45]
	s_add_i32 m0, s70, 0x2000
	s_add_u32 s70, s44, 0x4000
	s_addc_u32 s71, s45, 0
	s_add_i32 s72, s57, s3
	global_load_lds_dwordx4 v136, s[44:45]
	s_mov_b32 m0, s72
	s_nop 0
	global_load_lds_dwordx4 v132, s[70:71]
	s_add_i32 m0, s72, 0x2000
	s_nop 0
	global_load_lds_dwordx4 v136, s[70:71]
	s_waitcnt vmcnt(6)
	s_waitcnt lgkmcnt(0)
	s_barrier
	v_mfma_f32_16x16x32_bf16 v[62:65], v[148:151], v[188:191], v[62:65]
	v_mfma_f32_16x16x32_bf16 v[62:65], v[158:161], v[198:201], v[62:65]
	v_mfma_f32_16x16x32_bf16 v[46:49], v[148:151], v[202:205], v[46:49]
	v_mfma_f32_16x16x32_bf16 v[46:49], v[158:161], v[206:209], v[46:49]
	v_mfma_f32_16x16x32_bf16 v[30:33], v[148:151], v[210:213], v[30:33]
	v_mfma_f32_16x16x32_bf16 v[30:33], v[158:161], v[214:217], v[30:33]
	v_mfma_f32_16x16x32_bf16 v[14:17], v[148:151], v[218:221], v[14:17]
	v_mfma_f32_16x16x32_bf16 v[14:17], v[158:161], v[222:225], v[14:17]
	v_mfma_f32_16x16x32_bf16 v[10:13], v[162:165], v[218:221], v[10:13]
	v_mfma_f32_16x16x32_bf16 v[10:13], v[166:169], v[222:225], v[10:13]
	v_mfma_f32_16x16x32_bf16 v[26:29], v[162:165], v[210:213], v[26:29]
	v_mfma_f32_16x16x32_bf16 v[26:29], v[166:169], v[214:217], v[26:29]
	v_mfma_f32_16x16x32_bf16 v[42:45], v[162:165], v[202:205], v[42:45]
	v_mfma_f32_16x16x32_bf16 v[42:45], v[166:169], v[206:209], v[42:45]
	v_mfma_f32_16x16x32_bf16 v[58:61], v[162:165], v[188:191], v[58:61]
	v_mfma_f32_16x16x32_bf16 v[58:61], v[166:169], v[198:201], v[58:61]
	v_mfma_f32_16x16x32_bf16 v[54:57], v[170:173], v[188:191], v[54:57]
	v_mfma_f32_16x16x32_bf16 v[54:57], v[174:177], v[198:201], v[54:57]
	v_mfma_f32_16x16x32_bf16 v[38:41], v[170:173], v[202:205], v[38:41]
	v_mfma_f32_16x16x32_bf16 v[38:41], v[174:177], v[206:209], v[38:41]
	v_mfma_f32_16x16x32_bf16 v[22:25], v[170:173], v[210:213], v[22:25]
	v_mfma_f32_16x16x32_bf16 v[22:25], v[174:177], v[214:217], v[22:25]
	v_mfma_f32_16x16x32_bf16 v[6:9], v[170:173], v[218:221], v[6:9]
	v_mfma_f32_16x16x32_bf16 v[6:9], v[174:177], v[222:225], v[6:9]
	v_mfma_f32_16x16x32_bf16 v[2:5], v[180:183], v[218:221], v[2:5]
	v_mfma_f32_16x16x32_bf16 v[2:5], v[184:187], v[222:225], v[2:5]
	v_mfma_f32_16x16x32_bf16 v[18:21], v[180:183], v[210:213], v[18:21]
	v_mfma_f32_16x16x32_bf16 v[18:21], v[184:187], v[214:217], v[18:21]
	v_mfma_f32_16x16x32_bf16 v[34:37], v[180:183], v[202:205], v[34:37]
	v_mfma_f32_16x16x32_bf16 v[34:37], v[184:187], v[206:209], v[34:37]
	v_mfma_f32_16x16x32_bf16 v[50:53], v[180:183], v[188:191], v[50:53]
	v_mfma_f32_16x16x32_bf16 v[50:53], v[184:187], v[198:201], v[50:53]
	s_barrier
; #define PG8_STAGE(bufoff, gbase, voff) do { _Pragma("unroll") for (int _i = 0; _i < 2; ++_i) \
;         __builtin_amdgcn_global_load_lds((const unsigned*)((const char*)(gbase) + (voff)[_i]), (PG8_LAS unsigned*)(lds + (bufoff) + ldsw + _i * 8192), 16, 0, 0); } while (0)
; #define PG8_LDA(dst, b, h) do { _Pragma("unroll") for (int m = 0; m < 4; ++m) _Pragma("unroll") for (int k = 0; k < 2; ++k) dst[m][k] = *(const PG8_LAS bf16x8*)(lds + PG8_SA(b, h) + aoff + m * 2048 + k * 1024); } while (0)
; #define PG8_LDB(dst, b, h) do { _Pragma("unroll") for (int n = 0; n < 2; ++n) _Pragma("unroll") for (int k = 0; k < 2; ++k) dst[n][k] = *(const PG8_LAS bf16x8*)(lds + PG8_SB(b, h) + boff + n * 2048 + k * 1024); } while (0)
; #define PG8_MMA(ai, bj, At, Bt) do { __builtin_amdgcn_s_setprio(1); _Pragma("unroll") for (int m = 0; m < 4; ++m) _Pragma("unroll") for (int n = 0; n < 2; ++n) _Pragma("unroll") for (int k = 0; k < 2; ++k) \
;         acc[ai][bj][m][n] = __builtin_amdgcn_mfma_f32_16x16x32_bf16(Bt[n][k], At[m][k], acc[ai][bj][m][n], 0, 0, 0); __builtin_amdgcn_s_setprio(0); } while (0)
; #define PG8_WAIT_V(n) asm volatile("s_waitcnt vmcnt(" #n ")" ::: "memory")
; #define PG8_WAIT_L(n) asm volatile("s_waitcnt lgkmcnt(" #n ")" ::: "memory")
; #define PG8_BAR __builtin_amdgcn_s_barrier()
; #define PG8_SCHED __builtin_amdgcn_sched_barrier(0)
; template <class Epi, class Sched, bool ALIGN_EPI = false, bool SP2 = false>
; __device__ __forceinline__ void gemm_phase(PG8_LAS unsigned char* lds, const Gemm g, const Sched& S, const Epi& E) {
;     ...
;             PG8_LDB(B0, 1, 0); PG8_LDB(B1, 1, 1); PG8_SCHED; PG8_LDA(At, 1, 0); PG8_STAGE(PG8_SA(0, 1), a2 + hstep, voffA);
;             PG8_WAIT_V(8); PG8_WAIT_L(0); PG8_BAR; PG8_MMA(0, 0, At, B0); PG8_MMA(0, 1, At, B1); PG8_BAR; PG8_SCHED;
;             PG8_LDA(At, 1, 1); PG8_STAGE(PG8_SB(1, 0), b3, voffB); PG8_STAGE(PG8_SB(1, 1), b3 + hstep, voffB); PG8_STAGE(PG8_SA(1, 0), a3, voffA);
;             PG8_WAIT_V(8); PG8_WAIT_L(0); PG8_BAR; PG8_MMA(1, 0, At, B0); PG8_MMA(1, 1, At, B1); PG8_BAR; PG8_SCHED;
	s_add_i32 s70, 0, 0x18000
	v_add_u32_e32 v138, s70, v1
	s_add_i32 s71, 0, 0x1c000
	ds_read_b128 v[148:151], v138
	ds_read_b128 v[158:161], v138 offset:1024
	ds_read_b128 v[162:165], v138 offset:2048
	ds_read_b128 v[166:169], v138 offset:3072
	v_add_u32_e32 v138, s71, v1
	ds_read_b128 v[170:173], v138
	ds_read_b128 v[174:177], v138 offset:1024
	ds_read_b128 v[180:183], v138 offset:2048
	ds_read_b128 v[184:187], v138 offset:3072
	s_mov_b32 m0, s28
	s_nop 0
	global_load_lds_dwordx4 v130, s[46:47]
	s_mov_b32 m0, s29
	s_nop 0
	global_load_lds_dwordx4 v134, s[46:47]
	s_add_u32 s46, s46, 0x4000
	s_addc_u32 s47, s47, 0
	s_mov_b32 m0, s30
	ds_read_b128 v[188:191], v155 offset:32768
	ds_read_b128 v[198:201], v155 offset:33792
	ds_read_b128 v[202:205], v155 offset:34816
	ds_read_b128 v[206:209], v155 offset:35840
	ds_read_b128 v[210:213], v155 offset:36864
	ds_read_b128 v[214:217], v155 offset:37888
	ds_read_b128 v[218:221], v155 offset:38912
	ds_read_b128 v[222:225], v155 offset:39936
	global_load_lds_dwordx4 v130, s[46:47]
	s_mov_b32 m0, s31
	s_nop 0
	global_load_lds_dwordx4 v134, s[46:47]
	s_waitcnt vmcnt(8)
	s_waitcnt lgkmcnt(0)
	s_barrier
	v_mfma_f32_16x16x32_bf16 v[126:129], v[148:151], v[188:191], v[126:129]
	v_mfma_f32_16x16x32_bf16 v[126:129], v[158:161], v[198:201], v[126:129]
	v_mfma_f32_16x16x32_bf16 v[110:113], v[148:151], v[202:205], v[110:113]
	v_mfma_f32_16x16x32_bf16 v[110:113], v[158:161], v[206:209], v[110:113]
	v_mfma_f32_16x16x32_bf16 v[94:97], v[148:151], v[210:213], v[94:97]
	v_mfma_f32_16x16x32_bf16 v[94:97], v[158:161], v[214:217], v[94:97]
	v_mfma_f32_16x16x32_bf16 v[78:81], v[148:151], v[218:221], v[78:81]
	v_mfma_f32_16x16x32_bf16 v[78:81], v[158:161], v[222:225], v[78:81]
	v_mfma_f32_16x16x32_bf16 v[74:77], v[162:165], v[218:221], v[74:77]
	v_mfma_f32_16x16x32_bf16 v[74:77], v[166:169], v[222:225], v[74:77]
	v_mfma_f32_16x16x32_bf16 v[90:93], v[162:165], v[210:213], v[90:93]
	v_mfma_f32_16x16x32_bf16 v[90:93], v[166:169], v[214:217], v[90:93]
	v_mfma_f32_16x16x32_bf16 v[106:109], v[162:165], v[202:205], v[106:109]
	v_mfma_f32_16x16x32_bf16 v[106:109], v[166:169], v[206:209], v[106:109]
	v_mfma_f32_16x16x32_bf16 v[122:125], v[162:165], v[188:191], v[122:125]
	v_mfma_f32_16x16x32_bf16 v[122:125], v[166:169], v[198:201], v[122:125]
	v_mfma_f32_16x16x32_bf16 v[118:121], v[170:173], v[188:191], v[118:121]
	v_mfma_f32_16x16x32_bf16 v[118:121], v[174:177], v[198:201], v[118:121]
	v_mfma_f32_16x16x32_bf16 v[102:105], v[170:173], v[202:205], v[102:105]
	v_mfma_f32_16x16x32_bf16 v[102:105], v[174:177], v[206:209], v[102:105]
	v_mfma_f32_16x16x32_bf16 v[86:89], v[170:173], v[210:213], v[86:89]
	v_mfma_f32_16x16x32_bf16 v[86:89], v[174:177], v[214:217], v[86:89]
	v_mfma_f32_16x16x32_bf16 v[70:73], v[170:173], v[218:221], v[70:73]
	v_mfma_f32_16x16x32_bf16 v[70:73], v[174:177], v[222:225], v[70:73]
	v_mfma_f32_16x16x32_bf16 v[66:69], v[180:183], v[218:221], v[66:69]
	v_mfma_f32_16x16x32_bf16 v[66:69], v[184:187], v[222:225], v[66:69]
	v_mfma_f32_16x16x32_bf16 v[82:85], v[180:183], v[210:213], v[82:85]
	v_mfma_f32_16x16x32_bf16 v[82:85], v[184:187], v[214:217], v[82:85]
	v_mfma_f32_16x16x32_bf16 v[98:101], v[180:183], v[202:205], v[98:101]
	v_mfma_f32_16x16x32_bf16 v[98:101], v[184:187], v[206:209], v[98:101]
	v_mfma_f32_16x16x32_bf16 v[114:117], v[180:183], v[188:191], v[114:117]
	v_mfma_f32_16x16x32_bf16 v[114:117], v[184:187], v[198:201], v[114:117]
	s_barrier
	s_add_u32 s46, s44, 0x8000
	s_addc_u32 s47, s45, 0
	s_add_i32 s70, s70, s3
	s_mov_b32 m0, s70
	ds_read_b128 v[188:191], v155 offset:49152
	ds_read_b128 v[198:201], v155 offset:50176
	ds_read_b128 v[202:205], v155 offset:51200
	ds_read_b128 v[206:209], v155 offset:52224
	ds_read_b128 v[210:213], v155 offset:53248
	ds_read_b128 v[214:217], v155 offset:54272
	ds_read_b128 v[218:221], v155 offset:55296
	ds_read_b128 v[222:225], v155 offset:56320
	global_load_lds_dwordx4 v132, s[46:47]
	s_add_i32 m0, s70, 0x2000
	s_add_u32 s44, s44, 0xc000
	v_lshl_add_u64 v[226:227], s[46:47], 0, v[136:137]
	s_addc_u32 s45, s45, 0
	s_add_i32 s46, s71, s3
	global_load_lds_dwordx4 v[226:227], off
	s_mov_b32 m0, s46
	s_nop 0
	global_load_lds_dwordx4 v132, s[44:45]
	s_add_i32 m0, s46, 0x2000
	s_nop 0
	global_load_lds_dwordx4 v136, s[44:45]
	s_waitcnt vmcnt(6)
	s_waitcnt lgkmcnt(0)
	s_barrier
	v_mfma_f32_16x16x32_bf16 v[62:65], v[148:151], v[188:191], v[62:65]
	v_mfma_f32_16x16x32_bf16 v[62:65], v[158:161], v[198:201], v[62:65]
	v_mfma_f32_16x16x32_bf16 v[46:49], v[148:151], v[202:205], v[46:49]
	v_mfma_f32_16x16x32_bf16 v[46:49], v[158:161], v[206:209], v[46:49]
	v_mfma_f32_16x16x32_bf16 v[30:33], v[148:151], v[210:213], v[30:33]
	v_mfma_f32_16x16x32_bf16 v[30:33], v[158:161], v[214:217], v[30:33]
	v_mfma_f32_16x16x32_bf16 v[14:17], v[148:151], v[218:221], v[14:17]
	v_mfma_f32_16x16x32_bf16 v[14:17], v[158:161], v[222:225], v[14:17]
	v_mfma_f32_16x16x32_bf16 v[10:13], v[162:165], v[218:221], v[10:13]
	v_mfma_f32_16x16x32_bf16 v[10:13], v[166:169], v[222:225], v[10:13]
	v_mfma_f32_16x16x32_bf16 v[26:29], v[162:165], v[210:213], v[26:29]
	v_mfma_f32_16x16x32_bf16 v[26:29], v[166:169], v[214:217], v[26:29]
	v_mfma_f32_16x16x32_bf16 v[42:45], v[162:165], v[202:205], v[42:45]
	v_mfma_f32_16x16x32_bf16 v[42:45], v[166:169], v[206:209], v[42:45]
	v_mfma_f32_16x16x32_bf16 v[58:61], v[162:165], v[188:191], v[58:61]
	v_mfma_f32_16x16x32_bf16 v[58:61], v[166:169], v[198:201], v[58:61]
	v_mfma_f32_16x16x32_bf16 v[54:57], v[170:173], v[188:191], v[54:57]
	v_mfma_f32_16x16x32_bf16 v[54:57], v[174:177], v[198:201], v[54:57]
	v_mfma_f32_16x16x32_bf16 v[38:41], v[170:173], v[202:205], v[38:41]
	v_mfma_f32_16x16x32_bf16 v[38:41], v[174:177], v[206:209], v[38:41]
	v_mfma_f32_16x16x32_bf16 v[22:25], v[170:173], v[210:213], v[22:25]
	v_mfma_f32_16x16x32_bf16 v[22:25], v[174:177], v[214:217], v[22:25]
	v_mfma_f32_16x16x32_bf16 v[6:9], v[170:173], v[218:221], v[6:9]
	v_mfma_f32_16x16x32_bf16 v[6:9], v[174:177], v[222:225], v[6:9]
	v_mfma_f32_16x16x32_bf16 v[2:5], v[180:183], v[218:221], v[2:5]
	v_mfma_f32_16x16x32_bf16 v[2:5], v[184:187], v[222:225], v[2:5]
	v_mfma_f32_16x16x32_bf16 v[18:21], v[180:183], v[210:213], v[18:21]
	v_mfma_f32_16x16x32_bf16 v[18:21], v[184:187], v[214:217], v[18:21]
	v_mfma_f32_16x16x32_bf16 v[34:37], v[180:183], v[202:205], v[34:37]
	v_mfma_f32_16x16x32_bf16 v[34:37], v[184:187], v[206:209], v[34:37]
	v_mfma_f32_16x16x32_bf16 v[50:53], v[180:183], v[188:191], v[50:53]
	v_mfma_f32_16x16x32_bf16 v[50:53], v[184:187], v[198:201], v[50:53]
	s_barrier
	s_add_i32 s69, s69, 2
	s_add_u32 s40, s40, 0x10000
	s_addc_u32 s41, s41, 0
	s_add_u32 s67, s67, 0x10000
	s_addc_u32 s68, s68, 0
	s_cmp_gt_u32 s69, 61
	s_cbranch_scc0 .LBB0_840
	s_and_b64 vcc, exec, s[14:15]
	s_cbranch_vccz .LBB0_843
	s_barrier

; #define PG8_STAGE(bufoff, gbase, voff) do { _Pragma("unroll") for (int _i = 0; _i < 2; ++_i) \
;         __builtin_amdgcn_global_load_lds((const unsigned*)((const char*)(gbase) + (voff)[_i]), (PG8_LAS unsigned*)(lds + (bufoff) + ldsw + _i * 8192), 16, 0, 0); } while (0)
; #define PG8_LDA(dst, b, h) do { _Pragma("unroll") for (int m = 0; m < 4; ++m) _Pragma("unroll") for (int k = 0; k < 2; ++k) dst[m][k] = *(const PG8_LAS bf16x8*)(lds + PG8_SA(b, h) + aoff + m * 2048 + k * 1024); } while (0)
; #define PG8_LDB(dst, b, h) do { _Pragma("unroll") for (int n = 0; n < 2; ++n) _Pragma("unroll") for (int k = 0; k < 2; ++k) dst[n][k] = *(const PG8_LAS bf16x8*)(lds + PG8_SB(b, h) + boff + n * 2048 + k * 1024); } while (0)
; #define PG8_MMA(ai, bj, At, Bt) do { __builtin_amdgcn_s_setprio(1); _Pragma("unroll") for (int m = 0; m < 4; ++m) _Pragma("unroll") for (int n = 0; n < 2; ++n) _Pragma("unroll") for (int k = 0; k < 2; ++k) \
;         acc[ai][bj][m][n] = __builtin_amdgcn_mfma_f32_16x16x32_bf16(Bt[n][k], At[m][k], acc[ai][bj][m][n], 0, 0, 0); __builtin_amdgcn_s_setprio(0); } while (0)
; #define PG8_WAIT_V(n) asm volatile("s_waitcnt vmcnt(" #n ")" ::: "memory")
; #define PG8_WAIT_L(n) asm volatile("s_waitcnt lgkmcnt(" #n ")" ::: "memory")
; #define PG8_BAR __builtin_amdgcn_s_barrier()
; #define PG8_SCHED __builtin_amdgcn_sched_barrier(0)
; template <class Epi, class Sched, bool ALIGN_EPI = false, bool SP2 = false>
; __device__ __forceinline__ void gemm_phase(PG8_LAS unsigned char* lds, const Gemm g, const Sched& S, const Epi& E) {
;     ...
;             const char* a1 = cA + (size_t)(t + 1) * kstep;
;             const char* a2 = last ? nA : cA + (size_t)(t + 2) * kstep; const char* b2 = last ? nB : cB + (size_t)(t + 2) * kstep;
;             const char* a3 = a2 + kstep; const char* b3 = b2 + kstep;
;             if (last && has_next) S.a_ready(nxt);
;             if constexpr (SP2) {
;             PG8_LDB(B0, 0, 0); PG8_LDB(B1, 0, 1); PG8_SCHED; PG8_LDA(At, 0, 0); PG8_STAGE(PG8_SA(1, 1), a1 + hstep, voffA);
;             PG8_WAIT_V(8); PG8_WAIT_L(0); PG8_BAR; PG8_MMA(0, 0, At, B0); PG8_MMA(0, 1, At, B1); PG8_BAR; PG8_SCHED;
;             PG8_LDA(At, 0, 1); PG8_STAGE(PG8_SB(0, 0), b2, voffB); PG8_STAGE(PG8_SB(0, 1), b2 + hstep, voffB); PG8_STAGE(PG8_SA(0, 0), a2, voffA);
.LBB0_939:
	s_or_b32 s24, s59, 1
	s_lshl_b64 s[62:63], s[24:25], 15
	s_add_i32 s24, s59, 2
	ds_read_b128 v[156:159], v193
	ds_read_b128 v[160:163], v193 offset:1024
	ds_read_b128 v[196:199], v193 offset:2048
	ds_read_b128 v[200:203], v193 offset:3072
	ds_read_b128 v[204:207], v194
	ds_read_b128 v[208:211], v194 offset:1024
	ds_read_b128 v[212:215], v194 offset:2048
	ds_read_b128 v[216:219], v194 offset:3072
	s_lshl_b64 s[8:9], s[24:25], 15
	s_add_u32 s44, s6, s8
	s_addc_u32 s45, s7, s9
	s_cmpk_eq_i32 s59, 0xaa
	s_cselect_b32 s46, s58, s44
	s_cselect_b32 s47, s56, s45
	s_cselect_b32 s44, 0, s8
	s_cselect_b32 s45, 0, s9
	s_add_u32 s8, s46, 0x8000
	s_addc_u32 s9, s47, 0
	s_add_u32 s44, s14, s44
	s_addc_u32 s45, s15, s45
	s_add_u32 s62, s6, s62
	s_addc_u32 s63, s7, s63
	s_add_u32 s62, s62, 0x4000
	s_addc_u32 s63, s63, 0
	s_sub_u32 s8, s62, 0x4000
	s_subb_u32 s9, s63, 0
	s_mov_b32 m0, s51
	s_nop 0
	global_load_lds_dwordx4 v130, s[8:9]
	s_mov_b32 m0, s57
	s_nop 0
	global_load_lds_dwordx4 v134, s[8:9]
	s_add_i32 m0, s30, 0xc000
	ds_read_b128 v[220:223], v186
	ds_read_b128 v[224:227], v186 offset:1024
	ds_read_b128 v[228:231], v186 offset:2048
	ds_read_b128 v[232:235], v186 offset:3072
	ds_read_b128 v[236:239], v186 offset:4096
	ds_read_b128 v[240:243], v186 offset:5120
	ds_read_b128 v[244:247], v186 offset:6144
	ds_read_b128 v[248:251], v186 offset:7168
	global_load_lds_dwordx4 v130, s[62:63]
	s_add_i32 m0, s30, 0xe000
	s_nop 0
	global_load_lds_dwordx4 v134, s[62:63]
	s_waitcnt vmcnt(8)
	s_waitcnt lgkmcnt(0)
	s_barrier
	v_mfma_f32_16x16x32_bf16 v[126:129], v[156:159], v[220:223], v[126:129]
	v_mfma_f32_16x16x32_bf16 v[126:129], v[160:163], v[224:227], v[126:129]
	v_mfma_f32_16x16x32_bf16 v[110:113], v[156:159], v[228:231], v[110:113]
	v_mfma_f32_16x16x32_bf16 v[110:113], v[160:163], v[232:235], v[110:113]
	v_mfma_f32_16x16x32_bf16 v[94:97], v[156:159], v[236:239], v[94:97]
	v_mfma_f32_16x16x32_bf16 v[94:97], v[160:163], v[240:243], v[94:97]
	v_mfma_f32_16x16x32_bf16 v[78:81], v[156:159], v[244:247], v[78:81]
	v_mfma_f32_16x16x32_bf16 v[78:81], v[160:163], v[248:251], v[78:81]
	v_mfma_f32_16x16x32_bf16 v[74:77], v[196:199], v[244:247], v[74:77]
	v_mfma_f32_16x16x32_bf16 v[74:77], v[200:203], v[248:251], v[74:77]
	v_mfma_f32_16x16x32_bf16 v[90:93], v[196:199], v[236:239], v[90:93]
	v_mfma_f32_16x16x32_bf16 v[90:93], v[200:203], v[240:243], v[90:93]
	v_mfma_f32_16x16x32_bf16 v[106:109], v[196:199], v[228:231], v[106:109]
	v_mfma_f32_16x16x32_bf16 v[106:109], v[200:203], v[232:235], v[106:109]
	v_mfma_f32_16x16x32_bf16 v[122:125], v[196:199], v[220:223], v[122:125]
	v_mfma_f32_16x16x32_bf16 v[122:125], v[200:203], v[224:227], v[122:125]
	v_mfma_f32_16x16x32_bf16 v[118:121], v[204:207], v[220:223], v[118:121]
	v_mfma_f32_16x16x32_bf16 v[118:121], v[208:211], v[224:227], v[118:121]
	v_mfma_f32_16x16x32_bf16 v[102:105], v[204:207], v[228:231], v[102:105]
	v_mfma_f32_16x16x32_bf16 v[102:105], v[208:211], v[232:235], v[102:105]
	v_mfma_f32_16x16x32_bf16 v[86:89], v[204:207], v[236:239], v[86:89]
	v_mfma_f32_16x16x32_bf16 v[86:89], v[208:211], v[240:243], v[86:89]
	v_mfma_f32_16x16x32_bf16 v[70:73], v[204:207], v[244:247], v[70:73]
	v_mfma_f32_16x16x32_bf16 v[70:73], v[208:211], v[248:251], v[70:73]
	v_mfma_f32_16x16x32_bf16 v[66:69], v[212:215], v[244:247], v[66:69]
	v_mfma_f32_16x16x32_bf16 v[66:69], v[216:219], v[248:251], v[66:69]
	v_mfma_f32_16x16x32_bf16 v[82:85], v[212:215], v[236:239], v[82:85]
	v_mfma_f32_16x16x32_bf16 v[82:85], v[216:219], v[240:243], v[82:85]
	v_mfma_f32_16x16x32_bf16 v[98:101], v[212:215], v[228:231], v[98:101]
	v_mfma_f32_16x16x32_bf16 v[98:101], v[216:219], v[232:235], v[98:101]
	v_mfma_f32_16x16x32_bf16 v[114:117], v[212:215], v[220:223], v[114:117]
	v_mfma_f32_16x16x32_bf16 v[114:117], v[216:219], v[224:227], v[114:117]
	s_barrier
	s_add_i32 s62, s67, s29
	s_mov_b32 m0, s62
	ds_read_b128 v[220:223], v186 offset:16384
	ds_read_b128 v[224:227], v186 offset:17408
	ds_read_b128 v[228:231], v186 offset:18432
	ds_read_b128 v[232:235], v186 offset:19456
	ds_read_b128 v[236:239], v186 offset:20480
	ds_read_b128 v[240:243], v186 offset:21504
	ds_read_b128 v[244:247], v186 offset:22528
	ds_read_b128 v[248:251], v186 offset:23552
	global_load_lds_dwordx4 v132, s[44:45]
	s_add_i32 m0, s62, 0x2000
	s_add_u32 s62, s44, 0x4000
	s_addc_u32 s63, s45, 0
	s_add_i32 s72, s68, s29
	global_load_lds_dwordx4 v136, s[44:45]
	s_mov_b32 m0, s72
	s_nop 0
	global_load_lds_dwordx4 v132, s[62:63]
	s_add_i32 m0, s72, 0x2000
	s_nop 0
	global_load_lds_dwordx4 v136, s[62:63]
	s_waitcnt vmcnt(6)
	s_waitcnt lgkmcnt(0)
	s_barrier
; #define PG8_STAGE(bufoff, gbase, voff) do { _Pragma("unroll") for (int _i = 0; _i < 2; ++_i) \
;         __builtin_amdgcn_global_load_lds((const unsigned*)((const char*)(gbase) + (voff)[_i]), (PG8_LAS unsigned*)(lds + (bufoff) + ldsw + _i * 8192), 16, 0, 0); } while (0)
; #define PG8_LDA(dst, b, h) do { _Pragma("unroll") for (int m = 0; m < 4; ++m) _Pragma("unroll") for (int k = 0; k < 2; ++k) dst[m][k] = *(const PG8_LAS bf16x8*)(lds + PG8_SA(b, h) + aoff + m * 2048 + k * 1024); } while (0)
; #define PG8_LDB(dst, b, h) do { _Pragma("unroll") for (int n = 0; n < 2; ++n) _Pragma("unroll") for (int k = 0; k < 2; ++k) dst[n][k] = *(const PG8_LAS bf16x8*)(lds + PG8_SB(b, h) + boff + n * 2048 + k * 1024); } while (0)
; #define PG8_MMA(ai, bj, At, Bt) do { __builtin_amdgcn_s_setprio(1); _Pragma("unroll") for (int m = 0; m < 4; ++m) _Pragma("unroll") for (int n = 0; n < 2; ++n) _Pragma("unroll") for (int k = 0; k < 2; ++k) \
;         acc[ai][bj][m][n] = __builtin_amdgcn_mfma_f32_16x16x32_bf16(Bt[n][k], At[m][k], acc[ai][bj][m][n], 0, 0, 0); __builtin_amdgcn_s_setprio(0); } while (0)
; #define PG8_WAIT_V(n) asm volatile("s_waitcnt vmcnt(" #n ")" ::: "memory")
; #define PG8_WAIT_L(n) asm volatile("s_waitcnt lgkmcnt(" #n ")" ::: "memory")
; #define PG8_BAR __builtin_amdgcn_s_barrier()
; #define PG8_SCHED __builtin_amdgcn_sched_barrier(0)
; template <class Epi, class Sched, bool ALIGN_EPI = false, bool SP2 = false>
; __device__ __forceinline__ void gemm_phase(PG8_LAS unsigned char* lds, const Gemm g, const Sched& S, const Epi& E) {
;     ...
;             PG8_WAIT_V(8); PG8_WAIT_L(0); PG8_BAR; PG8_MMA(1, 0, At, B0); PG8_MMA(1, 1, At, B1); PG8_BAR; PG8_SCHED;
;             PG8_LDB(B0, 1, 0); PG8_LDB(B1, 1, 1); PG8_SCHED; PG8_LDA(At, 1, 0); PG8_STAGE(PG8_SA(0, 1), a2 + hstep, voffA);
;             PG8_WAIT_V(8); PG8_WAIT_L(0); PG8_BAR; PG8_MMA(0, 0, At, B0); PG8_MMA(0, 1, At, B1); PG8_BAR; PG8_SCHED;
;             PG8_LDA(At, 1, 1); PG8_STAGE(PG8_SB(1, 0), b3, voffB); PG8_STAGE(PG8_SB(1, 1), b3 + hstep, voffB); PG8_STAGE(PG8_SA(1, 0), a3, voffA);
	v_mfma_f32_16x16x32_bf16 v[62:65], v[156:159], v[220:223], v[62:65]
	v_mfma_f32_16x16x32_bf16 v[62:65], v[160:163], v[224:227], v[62:65]
	v_mfma_f32_16x16x32_bf16 v[46:49], v[156:159], v[228:231], v[46:49]
	v_mfma_f32_16x16x32_bf16 v[46:49], v[160:163], v[232:235], v[46:49]
	v_mfma_f32_16x16x32_bf16 v[30:33], v[156:159], v[236:239], v[30:33]
	v_mfma_f32_16x16x32_bf16 v[30:33], v[160:163], v[240:243], v[30:33]
	v_mfma_f32_16x16x32_bf16 v[14:17], v[156:159], v[244:247], v[14:17]
	v_mfma_f32_16x16x32_bf16 v[14:17], v[160:163], v[248:251], v[14:17]
	v_mfma_f32_16x16x32_bf16 v[10:13], v[196:199], v[244:247], v[10:13]
	v_mfma_f32_16x16x32_bf16 v[10:13], v[200:203], v[248:251], v[10:13]
	v_mfma_f32_16x16x32_bf16 v[26:29], v[196:199], v[236:239], v[26:29]
	v_mfma_f32_16x16x32_bf16 v[26:29], v[200:203], v[240:243], v[26:29]
	v_mfma_f32_16x16x32_bf16 v[42:45], v[196:199], v[228:231], v[42:45]
	v_mfma_f32_16x16x32_bf16 v[42:45], v[200:203], v[232:235], v[42:45]
	v_mfma_f32_16x16x32_bf16 v[58:61], v[196:199], v[220:223], v[58:61]
	v_mfma_f32_16x16x32_bf16 v[58:61], v[200:203], v[224:227], v[58:61]
	v_mfma_f32_16x16x32_bf16 v[54:57], v[204:207], v[220:223], v[54:57]
	v_mfma_f32_16x16x32_bf16 v[54:57], v[208:211], v[224:227], v[54:57]
	v_mfma_f32_16x16x32_bf16 v[38:41], v[204:207], v[228:231], v[38:41]
	v_mfma_f32_16x16x32_bf16 v[38:41], v[208:211], v[232:235], v[38:41]
	v_mfma_f32_16x16x32_bf16 v[22:25], v[204:207], v[236:239], v[22:25]
	v_mfma_f32_16x16x32_bf16 v[22:25], v[208:211], v[240:243], v[22:25]
	v_mfma_f32_16x16x32_bf16 v[6:9], v[204:207], v[244:247], v[6:9]
	v_mfma_f32_16x16x32_bf16 v[6:9], v[208:211], v[248:251], v[6:9]
	v_mfma_f32_16x16x32_bf16 v[2:5], v[212:215], v[244:247], v[2:5]
	v_mfma_f32_16x16x32_bf16 v[2:5], v[216:219], v[248:251], v[2:5]
	v_mfma_f32_16x16x32_bf16 v[18:21], v[212:215], v[236:239], v[18:21]
	v_mfma_f32_16x16x32_bf16 v[18:21], v[216:219], v[240:243], v[18:21]
	v_mfma_f32_16x16x32_bf16 v[34:37], v[212:215], v[228:231], v[34:37]
	v_mfma_f32_16x16x32_bf16 v[34:37], v[216:219], v[232:235], v[34:37]
	v_mfma_f32_16x16x32_bf16 v[50:53], v[212:215], v[220:223], v[50:53]
	v_mfma_f32_16x16x32_bf16 v[50:53], v[216:219], v[224:227], v[50:53]
	s_barrier
	s_add_i32 s62, 0, 0x18000
	v_add_u32_e32 v145, s62, v166
	s_add_i32 s63, 0, 0x1c000
	ds_read_b128 v[156:159], v145
	ds_read_b128 v[160:163], v145 offset:1024
	ds_read_b128 v[196:199], v145 offset:2048
	ds_read_b128 v[200:203], v145 offset:3072
	v_add_u32_e32 v145, s63, v166
	ds_read_b128 v[204:207], v145
	ds_read_b128 v[208:211], v145 offset:1024
	ds_read_b128 v[212:215], v145 offset:2048
	ds_read_b128 v[216:219], v145 offset:3072
	s_mov_b32 m0, s30
	s_nop 0
	global_load_lds_dwordx4 v130, s[46:47]
	s_mov_b32 m0, s31
	s_nop 0
	global_load_lds_dwordx4 v134, s[46:47]
	s_add_u32 s46, s46, 0x4000
	s_addc_u32 s47, s47, 0
	s_mov_b32 m0, s35
	ds_read_b128 v[220:223], v186 offset:32768
	ds_read_b128 v[224:227], v186 offset:33792
	ds_read_b128 v[228:231], v186 offset:34816
	ds_read_b128 v[232:235], v186 offset:35840
	ds_read_b128 v[236:239], v186 offset:36864
	ds_read_b128 v[240:243], v186 offset:37888
	ds_read_b128 v[244:247], v186 offset:38912
	ds_read_b128 v[248:251], v186 offset:39936
	global_load_lds_dwordx4 v130, s[46:47]
	s_mov_b32 m0, s48
	s_nop 0
	global_load_lds_dwordx4 v134, s[46:47]
	s_waitcnt vmcnt(8)
	s_waitcnt lgkmcnt(0)
	s_barrier
; #define PG8_STAGE(bufoff, gbase, voff) do { _Pragma("unroll") for (int _i = 0; _i < 2; ++_i) \
;         __builtin_amdgcn_global_load_lds((const unsigned*)((const char*)(gbase) + (voff)[_i]), (PG8_LAS unsigned*)(lds + (bufoff) + ldsw + _i * 8192), 16, 0, 0); } while (0)
; #define PG8_LDA(dst, b, h) do { _Pragma("unroll") for (int m = 0; m < 4; ++m) _Pragma("unroll") for (int k = 0; k < 2; ++k) dst[m][k] = *(const PG8_LAS bf16x8*)(lds + PG8_SA(b, h) + aoff + m * 2048 + k * 1024); } while (0)
; #define PG8_MMA(ai, bj, At, Bt) do { __builtin_amdgcn_s_setprio(1); _Pragma("unroll") for (int m = 0; m < 4; ++m) _Pragma("unroll") for (int n = 0; n < 2; ++n) _Pragma("unroll") for (int k = 0; k < 2; ++k) \
;         acc[ai][bj][m][n] = __builtin_amdgcn_mfma_f32_16x16x32_bf16(Bt[n][k], At[m][k], acc[ai][bj][m][n], 0, 0, 0); __builtin_amdgcn_s_setprio(0); } while (0)
; #define PG8_WAIT_V(n) asm volatile("s_waitcnt vmcnt(" #n ")" ::: "memory")
; #define PG8_WAIT_L(n) asm volatile("s_waitcnt lgkmcnt(" #n ")" ::: "memory")
; #define PG8_BAR __builtin_amdgcn_s_barrier()
; #define PG8_SCHED __builtin_amdgcn_sched_barrier(0)
; template <class Epi, class Sched, bool ALIGN_EPI = false, bool SP2 = false>
; __device__ __forceinline__ void gemm_phase(PG8_LAS unsigned char* lds, const Gemm g, const Sched& S, const Epi& E) {
;     ...
;             PG8_LDA(At, 1, 1); PG8_STAGE(PG8_SB(1, 0), b3, voffB); PG8_STAGE(PG8_SB(1, 1), b3 + hstep, voffB); PG8_STAGE(PG8_SA(1, 0), a3, voffA);
;             PG8_WAIT_V(8); PG8_WAIT_L(0); PG8_BAR; PG8_MMA(1, 0, At, B0); PG8_MMA(1, 1, At, B1); PG8_BAR; PG8_SCHED;
	v_mfma_f32_16x16x32_bf16 v[126:129], v[156:159], v[220:223], v[126:129]
	v_mfma_f32_16x16x32_bf16 v[126:129], v[160:163], v[224:227], v[126:129]
	v_mfma_f32_16x16x32_bf16 v[110:113], v[156:159], v[228:231], v[110:113]
	v_mfma_f32_16x16x32_bf16 v[110:113], v[160:163], v[232:235], v[110:113]
	v_mfma_f32_16x16x32_bf16 v[94:97], v[156:159], v[236:239], v[94:97]
	v_mfma_f32_16x16x32_bf16 v[94:97], v[160:163], v[240:243], v[94:97]
	v_mfma_f32_16x16x32_bf16 v[78:81], v[156:159], v[244:247], v[78:81]
	v_mfma_f32_16x16x32_bf16 v[78:81], v[160:163], v[248:251], v[78:81]
	v_mfma_f32_16x16x32_bf16 v[74:77], v[196:199], v[244:247], v[74:77]
	v_mfma_f32_16x16x32_bf16 v[74:77], v[200:203], v[248:251], v[74:77]
	v_mfma_f32_16x16x32_bf16 v[90:93], v[196:199], v[236:239], v[90:93]
	v_mfma_f32_16x16x32_bf16 v[90:93], v[200:203], v[240:243], v[90:93]
	v_mfma_f32_16x16x32_bf16 v[106:109], v[196:199], v[228:231], v[106:109]
	v_mfma_f32_16x16x32_bf16 v[106:109], v[200:203], v[232:235], v[106:109]
	v_mfma_f32_16x16x32_bf16 v[122:125], v[196:199], v[220:223], v[122:125]
	v_mfma_f32_16x16x32_bf16 v[122:125], v[200:203], v[224:227], v[122:125]
	v_mfma_f32_16x16x32_bf16 v[118:121], v[204:207], v[220:223], v[118:121]
	v_mfma_f32_16x16x32_bf16 v[118:121], v[208:211], v[224:227], v[118:121]
	v_mfma_f32_16x16x32_bf16 v[102:105], v[204:207], v[228:231], v[102:105]
	v_mfma_f32_16x16x32_bf16 v[102:105], v[208:211], v[232:235], v[102:105]
	v_mfma_f32_16x16x32_bf16 v[86:89], v[204:207], v[236:239], v[86:89]
	v_mfma_f32_16x16x32_bf16 v[86:89], v[208:211], v[240:243], v[86:89]
	v_mfma_f32_16x16x32_bf16 v[70:73], v[204:207], v[244:247], v[70:73]
	v_mfma_f32_16x16x32_bf16 v[70:73], v[208:211], v[248:251], v[70:73]
	v_mfma_f32_16x16x32_bf16 v[66:69], v[212:215], v[244:247], v[66:69]
	v_mfma_f32_16x16x32_bf16 v[66:69], v[216:219], v[248:251], v[66:69]
	v_mfma_f32_16x16x32_bf16 v[82:85], v[212:215], v[236:239], v[82:85]
	v_mfma_f32_16x16x32_bf16 v[82:85], v[216:219], v[240:243], v[82:85]
	v_mfma_f32_16x16x32_bf16 v[98:101], v[212:215], v[228:231], v[98:101]
	v_mfma_f32_16x16x32_bf16 v[98:101], v[216:219], v[232:235], v[98:101]
	v_mfma_f32_16x16x32_bf16 v[114:117], v[212:215], v[220:223], v[114:117]
	v_mfma_f32_16x16x32_bf16 v[114:117], v[216:219], v[224:227], v[114:117]
	s_barrier
	s_add_u32 s46, s44, 0x8000
	s_addc_u32 s47, s45, 0
	s_add_i32 s62, s62, s29
	s_mov_b32 m0, s62
	ds_read_b128 v[220:223], v186 offset:49152
	ds_read_b128 v[224:227], v186 offset:50176
	ds_read_b128 v[228:231], v186 offset:51200
	ds_read_b128 v[232:235], v186 offset:52224
	ds_read_b128 v[236:239], v186 offset:53248
	ds_read_b128 v[240:243], v186 offset:54272
	ds_read_b128 v[244:247], v186 offset:55296
	ds_read_b128 v[248:251], v186 offset:56320
	global_load_lds_dwordx4 v132, s[46:47]
	s_add_i32 m0, s62, 0x2000
	s_add_u32 s44, s44, 0xc000
	v_lshl_add_u64 v[164:165], s[46:47], 0, v[136:137]
	s_addc_u32 s45, s45, 0
	s_add_i32 s46, s63, s29
	global_load_lds_dwordx4 v[164:165], off
	s_mov_b32 m0, s46
	s_nop 0
	global_load_lds_dwordx4 v132, s[44:45]
	s_add_i32 m0, s46, 0x2000
	s_nop 0
	global_load_lds_dwordx4 v136, s[44:45]
	s_waitcnt vmcnt(6)
	s_waitcnt lgkmcnt(0)
	s_barrier
	v_mfma_f32_16x16x32_bf16 v[62:65], v[156:159], v[220:223], v[62:65]
	v_mfma_f32_16x16x32_bf16 v[62:65], v[160:163], v[224:227], v[62:65]
	v_mfma_f32_16x16x32_bf16 v[46:49], v[156:159], v[228:231], v[46:49]
	v_mfma_f32_16x16x32_bf16 v[46:49], v[160:163], v[232:235], v[46:49]
	v_mfma_f32_16x16x32_bf16 v[30:33], v[156:159], v[236:239], v[30:33]
	v_mfma_f32_16x16x32_bf16 v[30:33], v[160:163], v[240:243], v[30:33]
	v_mfma_f32_16x16x32_bf16 v[14:17], v[156:159], v[244:247], v[14:17]
	v_mfma_f32_16x16x32_bf16 v[14:17], v[160:163], v[248:251], v[14:17]
	v_mfma_f32_16x16x32_bf16 v[10:13], v[196:199], v[244:247], v[10:13]
	v_mfma_f32_16x16x32_bf16 v[10:13], v[200:203], v[248:251], v[10:13]
	v_mfma_f32_16x16x32_bf16 v[26:29], v[196:199], v[236:239], v[26:29]
	v_mfma_f32_16x16x32_bf16 v[26:29], v[200:203], v[240:243], v[26:29]
	v_mfma_f32_16x16x32_bf16 v[42:45], v[196:199], v[228:231], v[42:45]
	v_mfma_f32_16x16x32_bf16 v[42:45], v[200:203], v[232:235], v[42:45]
	v_mfma_f32_16x16x32_bf16 v[58:61], v[196:199], v[220:223], v[58:61]
	v_mfma_f32_16x16x32_bf16 v[58:61], v[200:203], v[224:227], v[58:61]
	v_mfma_f32_16x16x32_bf16 v[54:57], v[204:207], v[220:223], v[54:57]
	v_mfma_f32_16x16x32_bf16 v[54:57], v[208:211], v[224:227], v[54:57]
	v_mfma_f32_16x16x32_bf16 v[38:41], v[204:207], v[228:231], v[38:41]
	v_mfma_f32_16x16x32_bf16 v[38:41], v[208:211], v[232:235], v[38:41]
	v_mfma_f32_16x16x32_bf16 v[22:25], v[204:207], v[236:239], v[22:25]
	v_mfma_f32_16x16x32_bf16 v[22:25], v[208:211], v[240:243], v[22:25]
	v_mfma_f32_16x16x32_bf16 v[6:9], v[204:207], v[244:247], v[6:9]
	v_mfma_f32_16x16x32_bf16 v[6:9], v[208:211], v[248:251], v[6:9]
	v_mfma_f32_16x16x32_bf16 v[2:5], v[212:215], v[244:247], v[2:5]
	v_mfma_f32_16x16x32_bf16 v[2:5], v[216:219], v[248:251], v[2:5]
	v_mfma_f32_16x16x32_bf16 v[18:21], v[212:215], v[236:239], v[18:21]
	v_mfma_f32_16x16x32_bf16 v[18:21], v[216:219], v[240:243], v[18:21]
	v_mfma_f32_16x16x32_bf16 v[34:37], v[212:215], v[228:231], v[34:37]
	v_mfma_f32_16x16x32_bf16 v[34:37], v[216:219], v[232:235], v[34:37]
	v_mfma_f32_16x16x32_bf16 v[50:53], v[212:215], v[220:223], v[50:53]
	v_mfma_f32_16x16x32_bf16 v[50:53], v[216:219], v[224:227], v[50:53]
	s_barrier
	s_cmpk_gt_u32 s59, 0xa9
	s_mov_b32 s59, s24
	s_cbranch_scc0 .LBB0_939
	s_and_b64 vcc, exec, s[38:39]
	s_cbranch_vccz .LBB0_942
	s_barrier
